# v48 + lgkmcnt(0) moved before the MMA-opening barrier also in phases 3/7 (next to the existing vmcnt(10))
# baseline (speedup 1.0000x reference)
.LBB0_127:
	s_add_u32 s22, s20, 0xfff80080
	s_addc_u32 s23, s21, -1
	s_add_i32 s50, 0, 0x10000
	s_cmp_eq_u32 s49, 4
	s_cselect_b32 s23, s81, s23
	s_cselect_b32 s22, s80, s22
	s_cselect_b32 s39, s19, s48
	s_cselect_b32 s38, s31, s47
	v_lshl_add_u64 v[178:179], s[20:21], 0, v[138:139]
	s_add_i32 m0, s27, 0xc000
	ds_read_b128 v[162:165], v144
	ds_read_b128 v[166:169], v144 offset:1024
	ds_read_b128 v[170:173], v144 offset:2048
	ds_read_b128 v[174:177], v144 offset:3072
	ds_read_b128 v[192:195], v144 offset:4096
	ds_read_b128 v[196:199], v144 offset:5120
	ds_read_b128 v[200:203], v144 offset:6144
	ds_read_b128 v[204:207], v144 offset:7168
	global_load_lds_dwordx4 v[178:179], off
	s_add_i32 m0, s27, 0xe000
	v_lshl_add_u64 v[178:179], s[20:21], 0, v[140:141]
	global_load_lds_dwordx4 v[178:179], off
	s_barrier
	s_waitcnt lgkmcnt(0)
	v_mfma_f32_16x16x32_bf16 v[126:129], v[146:149], v[162:165], v[126:129]
	v_mfma_f32_16x16x32_bf16 v[122:125], v[154:157], v[162:165], v[122:125]
	v_mfma_f32_16x16x32_bf16 v[118:121], v[146:149], v[170:173], v[118:121]
	v_mfma_f32_16x16x32_bf16 v[114:117], v[154:157], v[170:173], v[114:117]
	v_mfma_f32_16x16x32_bf16 v[102:105], v[146:149], v[192:195], v[102:105]
	v_mfma_f32_16x16x32_bf16 v[98:101], v[154:157], v[192:195], v[98:101]
	v_mfma_f32_16x16x32_bf16 v[86:89], v[146:149], v[200:203], v[86:89]
	v_mfma_f32_16x16x32_bf16 v[82:85], v[154:157], v[200:203], v[82:85]
	v_mfma_f32_16x16x32_bf16 v[126:129], v[150:153], v[166:169], v[126:129]
	v_mfma_f32_16x16x32_bf16 v[122:125], v[158:161], v[166:169], v[122:125]
	v_mfma_f32_16x16x32_bf16 v[118:121], v[150:153], v[174:177], v[118:121]
	v_mfma_f32_16x16x32_bf16 v[114:117], v[158:161], v[174:177], v[114:117]
	v_mfma_f32_16x16x32_bf16 v[102:105], v[150:153], v[196:199], v[102:105]
	v_mfma_f32_16x16x32_bf16 v[98:101], v[158:161], v[196:199], v[98:101]
	v_mfma_f32_16x16x32_bf16 v[86:89], v[150:153], v[204:207], v[86:89]
	v_mfma_f32_16x16x32_bf16 v[82:85], v[158:161], v[204:207], v[82:85]
	s_barrier
	s_add_i32 s52, 0, 0x14000
	s_add_i32 s50, s50, s26
	v_add_u32_e32 v145, s52, v142
	v_lshl_add_u64 v[178:179], s[38:39], 0, v[134:135]
	s_mov_b32 m0, s50
	ds_read_b128 v[208:211], v145
	ds_read_b128 v[224:227], v145 offset:1024
	ds_read_b128 v[228:231], v145 offset:2048
	ds_read_b128 v[232:235], v145 offset:3072
	global_load_lds_dwordx4 v[178:179], off
	s_add_i32 m0, s50, 0x2000
	v_lshl_add_u64 v[212:213], s[38:39], 0, v[130:131]
	global_load_lds_dwordx4 v[212:213], off
	s_mov_b32 m0, s27
	v_lshl_add_u64 v[236:237], s[22:23], 0, v[136:137]
	s_waitcnt lgkmcnt(0)
	s_barrier
	v_mfma_f32_16x16x32_bf16 v[110:113], v[208:211], v[162:165], v[110:113]
	v_mfma_f32_16x16x32_bf16 v[106:109], v[228:231], v[162:165], v[106:109]
	v_mfma_f32_16x16x32_bf16 v[94:97], v[208:211], v[170:173], v[94:97]
	v_mfma_f32_16x16x32_bf16 v[90:93], v[228:231], v[170:173], v[90:93]
	v_mfma_f32_16x16x32_bf16 v[78:81], v[208:211], v[192:195], v[78:81]
	v_mfma_f32_16x16x32_bf16 v[74:77], v[228:231], v[192:195], v[74:77]
	v_mfma_f32_16x16x32_bf16 v[70:73], v[208:211], v[200:203], v[70:73]
	v_mfma_f32_16x16x32_bf16 v[66:69], v[228:231], v[200:203], v[66:69]
	v_mfma_f32_16x16x32_bf16 v[110:113], v[224:227], v[166:169], v[110:113]
	v_mfma_f32_16x16x32_bf16 v[106:109], v[232:235], v[166:169], v[106:109]
	v_mfma_f32_16x16x32_bf16 v[94:97], v[224:227], v[174:177], v[94:97]
	v_mfma_f32_16x16x32_bf16 v[90:93], v[232:235], v[174:177], v[90:93]
	v_mfma_f32_16x16x32_bf16 v[78:81], v[224:227], v[196:199], v[78:81]
	v_mfma_f32_16x16x32_bf16 v[74:77], v[232:235], v[196:199], v[74:77]
	v_mfma_f32_16x16x32_bf16 v[70:73], v[224:227], v[204:207], v[70:73]
	v_mfma_f32_16x16x32_bf16 v[66:69], v[232:235], v[204:207], v[66:69]
	s_barrier
	ds_read_b128 v[162:165], v144 offset:16384
	ds_read_b128 v[166:169], v144 offset:17408
	ds_read_b128 v[170:173], v144 offset:18432
	ds_read_b128 v[174:177], v144 offset:19456
	ds_read_b128 v[192:195], v144 offset:20480
	ds_read_b128 v[196:199], v144 offset:21504
	ds_read_b128 v[200:203], v144 offset:22528
	ds_read_b128 v[204:207], v144 offset:23552
	global_load_lds_dwordx4 v[236:237], off
	s_mov_b32 m0, s28
	v_lshl_add_u64 v[238:239], s[22:23], 0, v[132:133]
	global_load_lds_dwordx4 v[238:239], off
	s_waitcnt vmcnt(10)
	s_waitcnt lgkmcnt(0)
	s_barrier
	v_mfma_f32_16x16x32_bf16 v[62:65], v[146:149], v[162:165], v[62:65]
	v_mfma_f32_16x16x32_bf16 v[58:61], v[154:157], v[162:165], v[58:61]
	v_mfma_f32_16x16x32_bf16 v[54:57], v[146:149], v[170:173], v[54:57]
	v_mfma_f32_16x16x32_bf16 v[50:53], v[154:157], v[170:173], v[50:53]
	v_mfma_f32_16x16x32_bf16 v[38:41], v[146:149], v[192:195], v[38:41]
	v_mfma_f32_16x16x32_bf16 v[34:37], v[154:157], v[192:195], v[34:37]
	v_mfma_f32_16x16x32_bf16 v[22:25], v[146:149], v[200:203], v[22:25]
	v_mfma_f32_16x16x32_bf16 v[18:21], v[154:157], v[200:203], v[18:21]
	v_mfma_f32_16x16x32_bf16 v[62:65], v[150:153], v[166:169], v[62:65]
	v_mfma_f32_16x16x32_bf16 v[58:61], v[158:161], v[166:169], v[58:61]
	v_mfma_f32_16x16x32_bf16 v[54:57], v[150:153], v[174:177], v[54:57]
	v_mfma_f32_16x16x32_bf16 v[50:53], v[158:161], v[174:177], v[50:53]
	v_mfma_f32_16x16x32_bf16 v[38:41], v[150:153], v[196:199], v[38:41]
	v_mfma_f32_16x16x32_bf16 v[34:37], v[158:161], v[196:199], v[34:37]
	v_mfma_f32_16x16x32_bf16 v[22:25], v[150:153], v[204:207], v[22:25]
	v_mfma_f32_16x16x32_bf16 v[18:21], v[158:161], v[204:207], v[18:21]
	s_barrier
	s_add_u32 s50, s38, 0x20000
	s_addc_u32 s51, s39, 0
	s_add_i32 s52, s52, s26
	s_mov_b32 m0, s52
	v_lshl_add_u64 v[146:147], s[50:51], 0, v[134:135]
	global_load_lds_dwordx4 v[146:147], off
	s_add_i32 m0, s52, 0x2000
	v_lshl_add_u64 v[146:147], s[50:51], 0, v[130:131]
	global_load_lds_dwordx4 v[146:147], off
	v_add_u32_e32 v145, 0x18000, v142
	ds_read_b128 v[146:149], v145
	ds_read_b128 v[150:153], v145 offset:1024
	ds_read_b128 v[154:157], v145 offset:2048
	ds_read_b128 v[158:161], v145 offset:3072
	s_add_i32 s50, 0, 0x18000
	s_waitcnt vmcnt(6)
	s_barrier
	v_mfma_f32_16x16x32_bf16 v[46:49], v[208:211], v[162:165], v[46:49]
	v_mfma_f32_16x16x32_bf16 v[42:45], v[228:231], v[162:165], v[42:45]
	v_mfma_f32_16x16x32_bf16 v[30:33], v[208:211], v[170:173], v[30:33]
	v_mfma_f32_16x16x32_bf16 v[26:29], v[228:231], v[170:173], v[26:29]
	v_mfma_f32_16x16x32_bf16 v[14:17], v[208:211], v[192:195], v[14:17]
	v_mfma_f32_16x16x32_bf16 v[10:13], v[228:231], v[192:195], v[10:13]
	v_mfma_f32_16x16x32_bf16 v[6:9], v[208:211], v[200:203], v[6:9]
	v_mfma_f32_16x16x32_bf16 v[2:5], v[228:231], v[200:203], v[2:5]
	v_mfma_f32_16x16x32_bf16 v[46:49], v[224:227], v[166:169], v[46:49]
	v_mfma_f32_16x16x32_bf16 v[42:45], v[232:235], v[166:169], v[42:45]
	v_mfma_f32_16x16x32_bf16 v[30:33], v[224:227], v[174:177], v[30:33]
	v_mfma_f32_16x16x32_bf16 v[26:29], v[232:235], v[174:177], v[26:29]
	v_mfma_f32_16x16x32_bf16 v[14:17], v[224:227], v[196:199], v[14:17]
	v_mfma_f32_16x16x32_bf16 v[10:13], v[232:235], v[196:199], v[10:13]
	v_mfma_f32_16x16x32_bf16 v[6:9], v[224:227], v[204:207], v[6:9]
	v_mfma_f32_16x16x32_bf16 v[2:5], v[232:235], v[204:207], v[2:5]
	s_barrier
	s_add_u32 s22, s22, 0x80000
	s_addc_u32 s23, s23, 0
	s_mov_b32 m0, s29
	v_lshl_add_u64 v[208:209], s[22:23], 0, v[136:137]
	ds_read_b128 v[162:165], v144 offset:32768
	ds_read_b128 v[166:169], v144 offset:33792
	ds_read_b128 v[170:173], v144 offset:34816
	ds_read_b128 v[174:177], v144 offset:35840
	ds_read_b128 v[192:195], v144 offset:36864
	ds_read_b128 v[196:199], v144 offset:37888
	ds_read_b128 v[200:203], v144 offset:38912
	ds_read_b128 v[204:207], v144 offset:39936
	global_load_lds_dwordx4 v[208:209], off
	s_mov_b32 m0, s36
	v_lshl_add_u64 v[208:209], s[22:23], 0, v[132:133]
	global_load_lds_dwordx4 v[208:209], off
	s_barrier
	s_waitcnt lgkmcnt(0)
	v_mfma_f32_16x16x32_bf16 v[126:129], v[146:149], v[162:165], v[126:129]
	v_mfma_f32_16x16x32_bf16 v[122:125], v[154:157], v[162:165], v[122:125]
	v_mfma_f32_16x16x32_bf16 v[118:121], v[146:149], v[170:173], v[118:121]
	v_mfma_f32_16x16x32_bf16 v[114:117], v[154:157], v[170:173], v[114:117]
	v_mfma_f32_16x16x32_bf16 v[102:105], v[146:149], v[192:195], v[102:105]
	v_mfma_f32_16x16x32_bf16 v[98:101], v[154:157], v[192:195], v[98:101]
	v_mfma_f32_16x16x32_bf16 v[86:89], v[146:149], v[200:203], v[86:89]
	v_mfma_f32_16x16x32_bf16 v[82:85], v[154:157], v[200:203], v[82:85]
	v_mfma_f32_16x16x32_bf16 v[126:129], v[150:153], v[166:169], v[126:129]
	v_mfma_f32_16x16x32_bf16 v[122:125], v[158:161], v[166:169], v[122:125]
	v_mfma_f32_16x16x32_bf16 v[118:121], v[150:153], v[174:177], v[118:121]
	v_mfma_f32_16x16x32_bf16 v[114:117], v[158:161], v[174:177], v[114:117]
	v_mfma_f32_16x16x32_bf16 v[102:105], v[150:153], v[196:199], v[102:105]
	v_mfma_f32_16x16x32_bf16 v[98:101], v[158:161], v[196:199], v[98:101]
	v_mfma_f32_16x16x32_bf16 v[86:89], v[150:153], v[204:207], v[86:89]
	v_mfma_f32_16x16x32_bf16 v[82:85], v[158:161], v[204:207], v[82:85]
	s_barrier
	s_add_i32 s51, 0, 0x1c000
	s_add_i32 s22, s50, s26
	v_add_u32_e32 v145, s51, v142
	v_lshl_add_u64 v[178:179], v[178:179], 0, s[78:79]
	s_mov_b32 m0, s22
	ds_read_b128 v[208:211], v145
	ds_read_b128 v[224:227], v145 offset:1024
	ds_read_b128 v[228:231], v145 offset:2048
	ds_read_b128 v[232:235], v145 offset:3072
	global_load_lds_dwordx4 v[178:179], off
	s_add_i32 m0, s22, 0x2000
	v_lshl_add_u64 v[178:179], v[212:213], 0, s[78:79]
	global_load_lds_dwordx4 v[178:179], off
	s_mov_b32 m0, s42
	v_lshl_add_u64 v[178:179], v[236:237], 0, s[78:79]
	s_waitcnt lgkmcnt(0)
	s_barrier
	v_mfma_f32_16x16x32_bf16 v[110:113], v[208:211], v[162:165], v[110:113]
	v_mfma_f32_16x16x32_bf16 v[106:109], v[228:231], v[162:165], v[106:109]
	v_mfma_f32_16x16x32_bf16 v[94:97], v[208:211], v[170:173], v[94:97]
	v_mfma_f32_16x16x32_bf16 v[90:93], v[228:231], v[170:173], v[90:93]
	v_mfma_f32_16x16x32_bf16 v[78:81], v[208:211], v[192:195], v[78:81]
	v_mfma_f32_16x16x32_bf16 v[74:77], v[228:231], v[192:195], v[74:77]
	v_mfma_f32_16x16x32_bf16 v[70:73], v[208:211], v[200:203], v[70:73]
	v_mfma_f32_16x16x32_bf16 v[66:69], v[228:231], v[200:203], v[66:69]
	v_mfma_f32_16x16x32_bf16 v[110:113], v[224:227], v[166:169], v[110:113]
	v_mfma_f32_16x16x32_bf16 v[106:109], v[232:235], v[166:169], v[106:109]
	v_mfma_f32_16x16x32_bf16 v[94:97], v[224:227], v[174:177], v[94:97]
	v_mfma_f32_16x16x32_bf16 v[90:93], v[232:235], v[174:177], v[90:93]
	v_mfma_f32_16x16x32_bf16 v[78:81], v[224:227], v[196:199], v[78:81]
	v_mfma_f32_16x16x32_bf16 v[74:77], v[232:235], v[196:199], v[74:77]
	v_mfma_f32_16x16x32_bf16 v[70:73], v[224:227], v[204:207], v[70:73]
	v_mfma_f32_16x16x32_bf16 v[66:69], v[232:235], v[204:207], v[66:69]
	s_barrier
	ds_read_b128 v[162:165], v144 offset:49152
	ds_read_b128 v[166:169], v144 offset:50176
	ds_read_b128 v[170:173], v144 offset:51200
	ds_read_b128 v[174:177], v144 offset:52224
	ds_read_b128 v[192:195], v144 offset:53248
	ds_read_b128 v[196:199], v144 offset:54272
	ds_read_b128 v[200:203], v144 offset:55296
	ds_read_b128 v[204:207], v144 offset:56320
	global_load_lds_dwordx4 v[178:179], off
	s_mov_b32 m0, s43
	v_lshl_add_u64 v[178:179], v[238:239], 0, s[78:79]
	global_load_lds_dwordx4 v[178:179], off
	s_waitcnt vmcnt(10)
	s_waitcnt lgkmcnt(0)
	s_barrier
	v_mfma_f32_16x16x32_bf16 v[62:65], v[146:149], v[162:165], v[62:65]
	v_mfma_f32_16x16x32_bf16 v[58:61], v[154:157], v[162:165], v[58:61]
	v_mfma_f32_16x16x32_bf16 v[54:57], v[146:149], v[170:173], v[54:57]
	v_mfma_f32_16x16x32_bf16 v[50:53], v[154:157], v[170:173], v[50:53]
	v_mfma_f32_16x16x32_bf16 v[38:41], v[146:149], v[192:195], v[38:41]
	v_mfma_f32_16x16x32_bf16 v[34:37], v[154:157], v[192:195], v[34:37]
	v_mfma_f32_16x16x32_bf16 v[22:25], v[146:149], v[200:203], v[22:25]
	v_mfma_f32_16x16x32_bf16 v[18:21], v[154:157], v[200:203], v[18:21]
	v_mfma_f32_16x16x32_bf16 v[62:65], v[150:153], v[166:169], v[62:65]
	v_mfma_f32_16x16x32_bf16 v[58:61], v[158:161], v[166:169], v[58:61]
	v_mfma_f32_16x16x32_bf16 v[54:57], v[150:153], v[174:177], v[54:57]
	v_mfma_f32_16x16x32_bf16 v[50:53], v[158:161], v[174:177], v[50:53]
	v_mfma_f32_16x16x32_bf16 v[38:41], v[150:153], v[196:199], v[38:41]
	v_mfma_f32_16x16x32_bf16 v[34:37], v[158:161], v[196:199], v[34:37]
	v_mfma_f32_16x16x32_bf16 v[22:25], v[150:153], v[204:207], v[22:25]
	v_mfma_f32_16x16x32_bf16 v[18:21], v[158:161], v[204:207], v[18:21]
	s_barrier
	s_add_u32 s22, s38, 0x20080
	s_addc_u32 s23, s39, 0
	s_add_i32 s38, s51, s26
	s_mov_b32 m0, s38
	v_lshl_add_u64 v[146:147], s[22:23], 0, v[134:135]
	global_load_lds_dwordx4 v[146:147], off
	s_add_i32 m0, s38, 0x2000
	v_lshl_add_u64 v[146:147], s[22:23], 0, v[130:131]
	global_load_lds_dwordx4 v[146:147], off
	v_add_u32_e32 v145, 0x10000, v142
	ds_read_b128 v[146:149], v145
	ds_read_b128 v[150:153], v145 offset:1024
	ds_read_b128 v[154:157], v145 offset:2048
	ds_read_b128 v[158:161], v145 offset:3072
	s_add_i32 s49, s49, 2
	s_add_u32 s20, s20, 0x100
	s_addc_u32 s21, s21, 0
	s_add_u32 s47, s47, 0x100
	s_addc_u32 s48, s48, 0
	s_cmp_gt_u32 s49, 5
	s_waitcnt vmcnt(6)
	s_barrier
	v_mfma_f32_16x16x32_bf16 v[46:49], v[208:211], v[162:165], v[46:49]
	v_mfma_f32_16x16x32_bf16 v[42:45], v[228:231], v[162:165], v[42:45]
	v_mfma_f32_16x16x32_bf16 v[30:33], v[208:211], v[170:173], v[30:33]
	v_mfma_f32_16x16x32_bf16 v[26:29], v[228:231], v[170:173], v[26:29]
	v_mfma_f32_16x16x32_bf16 v[14:17], v[208:211], v[192:195], v[14:17]
	v_mfma_f32_16x16x32_bf16 v[10:13], v[228:231], v[192:195], v[10:13]
	v_mfma_f32_16x16x32_bf16 v[6:9], v[208:211], v[200:203], v[6:9]
	v_mfma_f32_16x16x32_bf16 v[2:5], v[228:231], v[200:203], v[2:5]
	v_mfma_f32_16x16x32_bf16 v[46:49], v[224:227], v[166:169], v[46:49]
	v_mfma_f32_16x16x32_bf16 v[42:45], v[232:235], v[166:169], v[42:45]
	v_mfma_f32_16x16x32_bf16 v[30:33], v[224:227], v[174:177], v[30:33]
	v_mfma_f32_16x16x32_bf16 v[26:29], v[232:235], v[174:177], v[26:29]
	v_mfma_f32_16x16x32_bf16 v[14:17], v[224:227], v[196:199], v[14:17]
	v_mfma_f32_16x16x32_bf16 v[10:13], v[232:235], v[196:199], v[10:13]
	v_mfma_f32_16x16x32_bf16 v[6:9], v[224:227], v[204:207], v[6:9]
	v_mfma_f32_16x16x32_bf16 v[2:5], v[232:235], v[204:207], v[2:5]
	s_barrier
	s_cbranch_scc0 .LBB0_127
	s_waitcnt lgkmcnt(0)
	v_lshl_add_u32 v146, s46, 8, v1
	v_lshl_or_b32 v148, s45, 8, v143
	v_ashrrev_i32_e32 v147, 31, v146
	v_readlane_b32 s48, v254, 40
	v_ashrrev_i32_e32 v149, 31, v148
	v_lshlrev_b64 v[150:151], 12, v[146:147]
	v_readlane_b32 s52, v254, 44
	v_readlane_b32 s53, v254, 45
	v_lshlrev_b64 v[148:149], 1, v[148:149]
	s_mov_b32 s19, 0x80000
	v_lshl_add_u64 v[150:151], s[52:53], 0, v[150:151]
	v_lshl_add_u64 v[150:151], v[150:151], 0, v[148:149]
	s_mov_b64 s[20:21], 0x80000
	v_cvt_pk_bf16_f32 v62, v62, v63
	v_cvt_pk_bf16_f32 v63, v64, v65
	v_cvt_pk_bf16_f32 v64, v58, v59
	v_add_co_u32_e32 v58, vcc, s19, v150
	v_cvt_pk_bf16_f32 v70, v70, v71
	v_cvt_pk_bf16_f32 v71, v72, v73
	v_cvt_pk_bf16_f32 v72, v66, v67
	v_lshl_add_u64 v[66:67], v[150:151], 0, s[20:21]
	v_addc_co_u32_e32 v59, vcc, 0, v151, vcc
	v_cvt_pk_bf16_f32 v46, v46, v47
	v_cvt_pk_bf16_f32 v47, v48, v49
	v_cvt_pk_bf16_f32 v48, v42, v43
	v_cvt_pk_bf16_f32 v49, v44, v45
	s_mov_b32 s19, 0x90000
	v_cvt_pk_bf16_f32 v110, v110, v111
	v_cvt_pk_bf16_f32 v111, v112, v113
	v_cvt_pk_bf16_f32 v112, v106, v107
	v_or_b32_e32 v106, 16, v146
	global_store_dwordx4 v[66:67], v[46:49], off offset:256
	s_mov_b64 s[20:21], 0x90000
	v_ashrrev_i32_e32 v107, 31, v106
	v_add_co_u32_e32 v48, vcc, s19, v150
	v_cvt_pk_bf16_f32 v94, v94, v95
	v_cvt_pk_bf16_f32 v95, v96, v97
	v_cvt_pk_bf16_f32 v96, v90, v91
	v_or_b32_e32 v90, 32, v146
	v_lshl_add_u64 v[46:47], v[150:151], 0, s[20:21]
	v_addc_co_u32_e32 v49, vcc, 0, v151, vcc
	v_cvt_pk_bf16_f32 v30, v30, v31
	v_cvt_pk_bf16_f32 v31, v32, v33
	v_cvt_pk_bf16_f32 v32, v26, v27
	v_cvt_pk_bf16_f32 v33, v28, v29
	s_mov_b32 s19, 0xa0000
	v_lshlrev_b64 v[106:107], 12, v[106:107]
	v_ashrrev_i32_e32 v91, 31, v90
	v_cvt_pk_bf16_f32 v78, v78, v79
	v_cvt_pk_bf16_f32 v79, v80, v81
	v_cvt_pk_bf16_f32 v80, v74, v75
	v_or_b32_e32 v74, 48, v146
	global_store_dwordx4 v[46:47], v[30:33], off offset:256
	s_mov_b64 s[20:21], 0xa0000
	v_cvt_pk_bf16_f32 v113, v108, v109
	v_add_co_u32_e32 v32, vcc, s19, v150
	v_lshl_add_u64 v[106:107], s[52:53], 0, v[106:107]
	v_lshlrev_b64 v[90:91], 12, v[90:91]
	v_ashrrev_i32_e32 v75, 31, v74
	v_lshl_add_u64 v[30:31], v[150:151], 0, s[20:21]
	v_addc_co_u32_e32 v33, vcc, 0, v151, vcc
	v_cvt_pk_bf16_f32 v14, v14, v15
	v_cvt_pk_bf16_f32 v15, v16, v17
	v_cvt_pk_bf16_f32 v16, v10, v11
	v_cvt_pk_bf16_f32 v17, v12, v13
	s_mov_b32 s19, 0xb0000
	global_store_dwordx4 v[150:151], v[110:113], off offset:256
	v_cvt_pk_bf16_f32 v97, v92, v93
	v_lshl_add_u64 v[90:91], s[52:53], 0, v[90:91]
	v_lshl_add_u64 v[110:111], v[106:107], 0, v[148:149]
	v_lshlrev_b64 v[74:75], 12, v[74:75]
	global_store_dwordx4 v[30:31], v[14:17], off offset:256
	global_store_dwordx4 v[110:111], v[94:97], off offset:256
	v_cvt_pk_bf16_f32 v81, v76, v77
	v_add_co_u32_e32 v16, vcc, s19, v150
	v_lshl_add_u64 v[94:95], v[90:91], 0, v[148:149]
	v_lshl_add_u64 v[74:75], s[52:53], 0, v[74:75]
	s_mov_b64 s[20:21], 0xb0000
	v_addc_co_u32_e32 v17, vcc, 0, v151, vcc
	v_cvt_pk_bf16_f32 v126, v126, v127
	v_cvt_pk_bf16_f32 v127, v128, v129
	v_cvt_pk_bf16_f32 v128, v122, v123
	v_cvt_pk_bf16_f32 v129, v124, v125
	v_cvt_pk_bf16_f32 v106, v118, v119
	v_cvt_pk_bf16_f32 v107, v120, v121
	v_cvt_pk_bf16_f32 v108, v114, v115
	v_cvt_pk_bf16_f32 v109, v116, v117
	v_cvt_pk_bf16_f32 v90, v102, v103
	v_cvt_pk_bf16_f32 v91, v104, v105
	v_cvt_pk_bf16_f32 v92, v98, v99
	v_cvt_pk_bf16_f32 v93, v100, v101
	global_store_dwordx4 v[94:95], v[78:81], off offset:256
	v_cvt_pk_bf16_f32 v76, v82, v83
	v_cvt_pk_bf16_f32 v77, v84, v85
	v_lshl_add_u64 v[78:79], v[74:75], 0, v[148:149]
	v_cvt_pk_bf16_f32 v74, v86, v87
	v_cvt_pk_bf16_f32 v75, v88, v89
	v_cvt_pk_bf16_f32 v73, v68, v69
	v_cvt_pk_bf16_f32 v65, v60, v61
	v_cvt_pk_bf16_f32 v42, v54, v55
	v_cvt_pk_bf16_f32 v43, v56, v57
	v_cvt_pk_bf16_f32 v44, v50, v51
	v_cvt_pk_bf16_f32 v45, v52, v53
	v_cvt_pk_bf16_f32 v26, v38, v39
	v_cvt_pk_bf16_f32 v27, v40, v41
	v_cvt_pk_bf16_f32 v28, v34, v35
	v_cvt_pk_bf16_f32 v29, v36, v37
	v_lshl_add_u64 v[14:15], v[150:151], 0, s[20:21]
	v_cvt_pk_bf16_f32 v10, v22, v23
	v_cvt_pk_bf16_f32 v11, v24, v25
	v_cvt_pk_bf16_f32 v12, v18, v19
	v_cvt_pk_bf16_f32 v13, v20, v21
	v_cvt_pk_bf16_f32 v6, v6, v7
	v_cvt_pk_bf16_f32 v7, v8, v9
	v_cvt_pk_bf16_f32 v8, v2, v3
	v_cvt_pk_bf16_f32 v9, v4, v5
	s_and_b64 vcc, exec, s[0:1]
	s_mov_b32 s45, s18
	s_mov_b32 s46, s30
	s_mov_b64 s[22:23], s[82:83]
	s_mov_b64 s[20:21], s[80:81]
	s_mov_b32 s64, 0x800000
	s_movk_i32 s65, 0x1fff
	v_readlane_b32 s49, v254, 41
	v_readlane_b32 s50, v254, 42
	v_readlane_b32 s51, v254, 43
	v_readlane_b32 s54, v254, 46
	v_readlane_b32 s55, v254, 47
	v_readlane_b32 s56, v254, 48
	v_readlane_b32 s57, v254, 49
	v_readlane_b32 s58, v254, 50
	v_readlane_b32 s59, v254, 51
	v_readlane_b32 s60, v254, 52
	v_readlane_b32 s61, v254, 53
	v_readlane_b32 s62, v254, 54
	v_readlane_b32 s63, v254, 55
	global_store_dwordx4 v[150:151], v[126:129], off
	global_store_dwordx4 v[110:111], v[106:109], off
	global_store_dwordx4 v[94:95], v[90:93], off
	global_store_dwordx4 v[78:79], v[74:77], off
	global_store_dwordx4 v[78:79], v[70:73], off offset:256
	global_store_dwordx4 v[58:59], v[62:65], off
	global_store_dwordx4 v[48:49], v[42:45], off
	global_store_dwordx4 v[32:33], v[26:29], off
	global_store_dwordx4 v[16:17], v[10:13], off
	global_store_dwordx4 v[14:15], v[6:9], off offset:256
	s_cbranch_vccz .LBB0_118
	s_waitcnt vmcnt(0)
	v_readlane_b32 s44, v255, 30
	s_mov_b32 s66, s90
	s_cmpk_gt_u32 s25, 0xff
	v_readlane_b32 s45, v255, 31
	v_readlane_b32 s42, v255, 32
	s_cbranch_scc1 .LBB0_131
	s_barrier

.LBB0_240:
	s_add_u32 s22, s80, 0xfff80080
	s_addc_u32 s23, s81, -1
	s_add_i32 s52, 0, 0x10000
	s_cmp_eq_u32 s51, 28
	s_cselect_b32 s23, s21, s23
	s_cselect_b32 s22, s47, s22
	s_cselect_b32 s83, s19, s50
	s_cselect_b32 s82, s48, s49
	v_lshl_add_u64 v[178:179], s[80:81], 0, v[134:135]
	s_add_i32 m0, s27, 0xc000
	ds_read_b128 v[158:161], v140
	ds_read_b128 v[162:165], v140 offset:1024
	ds_read_b128 v[166:169], v140 offset:2048
	ds_read_b128 v[170:173], v140 offset:3072
	ds_read_b128 v[174:177], v140 offset:4096
	ds_read_b128 v[192:195], v140 offset:5120
	ds_read_b128 v[196:199], v140 offset:6144
	ds_read_b128 v[200:203], v140 offset:7168
	global_load_lds_dwordx4 v[178:179], off
	s_add_i32 m0, s27, 0xe000
	v_lshl_add_u64 v[178:179], s[80:81], 0, v[136:137]
	global_load_lds_dwordx4 v[178:179], off
	s_barrier
	s_waitcnt lgkmcnt(0)
	v_mfma_f32_16x16x32_bf16 v[126:129], v[142:145], v[158:161], v[126:129]
	v_mfma_f32_16x16x32_bf16 v[122:125], v[150:153], v[158:161], v[122:125]
	v_mfma_f32_16x16x32_bf16 v[118:121], v[142:145], v[166:169], v[118:121]
	v_mfma_f32_16x16x32_bf16 v[114:117], v[150:153], v[166:169], v[114:117]
	v_mfma_f32_16x16x32_bf16 v[110:113], v[142:145], v[174:177], v[110:113]
	v_mfma_f32_16x16x32_bf16 v[102:105], v[150:153], v[174:177], v[102:105]
	v_mfma_f32_16x16x32_bf16 v[94:97], v[142:145], v[196:199], v[94:97]
	v_mfma_f32_16x16x32_bf16 v[86:89], v[150:153], v[196:199], v[86:89]
	v_mfma_f32_16x16x32_bf16 v[126:129], v[146:149], v[162:165], v[126:129]
	v_mfma_f32_16x16x32_bf16 v[122:125], v[154:157], v[162:165], v[122:125]
	v_mfma_f32_16x16x32_bf16 v[118:121], v[146:149], v[170:173], v[118:121]
	v_mfma_f32_16x16x32_bf16 v[114:117], v[154:157], v[170:173], v[114:117]
	v_mfma_f32_16x16x32_bf16 v[110:113], v[146:149], v[192:195], v[110:113]
	v_mfma_f32_16x16x32_bf16 v[102:105], v[154:157], v[192:195], v[102:105]
	v_mfma_f32_16x16x32_bf16 v[94:97], v[146:149], v[200:203], v[94:97]
	v_mfma_f32_16x16x32_bf16 v[86:89], v[154:157], v[200:203], v[86:89]
	s_barrier
	s_add_i32 s54, 0, 0x14000
	s_add_i32 s52, s52, s26
	v_add_u32_e32 v141, s54, v138
	v_lshl_add_u64 v[178:179], s[82:83], 0, v[132:133]
	s_mov_b32 m0, s52
	ds_read_b128 v[204:207], v141
	ds_read_b128 v[208:211], v141 offset:1024
	ds_read_b128 v[224:227], v141 offset:2048
	ds_read_b128 v[228:231], v141 offset:3072
	global_load_lds_dwordx4 v[178:179], off
	s_add_i32 m0, s52, 0x2000
	v_lshl_add_u64 v[212:213], s[82:83], 0, v[130:131]
	global_load_lds_dwordx4 v[212:213], off
	s_mov_b32 m0, s27
	v_lshl_add_u64 v[232:233], s[22:23], 0, v[132:133]
	s_waitcnt lgkmcnt(0)
	s_barrier
	v_mfma_f32_16x16x32_bf16 v[106:109], v[204:207], v[158:161], v[106:109]
	v_mfma_f32_16x16x32_bf16 v[98:101], v[224:227], v[158:161], v[98:101]
	v_mfma_f32_16x16x32_bf16 v[90:93], v[204:207], v[166:169], v[90:93]
	v_mfma_f32_16x16x32_bf16 v[82:85], v[224:227], v[166:169], v[82:85]
	v_mfma_f32_16x16x32_bf16 v[78:81], v[204:207], v[174:177], v[78:81]
	v_mfma_f32_16x16x32_bf16 v[74:77], v[224:227], v[174:177], v[74:77]
	v_mfma_f32_16x16x32_bf16 v[70:73], v[204:207], v[196:199], v[70:73]
	v_mfma_f32_16x16x32_bf16 v[66:69], v[224:227], v[196:199], v[66:69]
	v_mfma_f32_16x16x32_bf16 v[106:109], v[208:211], v[162:165], v[106:109]
	v_mfma_f32_16x16x32_bf16 v[98:101], v[228:231], v[162:165], v[98:101]
	v_mfma_f32_16x16x32_bf16 v[90:93], v[208:211], v[170:173], v[90:93]
	v_mfma_f32_16x16x32_bf16 v[82:85], v[228:231], v[170:173], v[82:85]
	v_mfma_f32_16x16x32_bf16 v[78:81], v[208:211], v[192:195], v[78:81]
	v_mfma_f32_16x16x32_bf16 v[74:77], v[228:231], v[192:195], v[74:77]
	v_mfma_f32_16x16x32_bf16 v[70:73], v[208:211], v[200:203], v[70:73]
	v_mfma_f32_16x16x32_bf16 v[66:69], v[228:231], v[200:203], v[66:69]
	s_barrier
	ds_read_b128 v[158:161], v140 offset:16384
	ds_read_b128 v[162:165], v140 offset:17408
	ds_read_b128 v[166:169], v140 offset:18432
	ds_read_b128 v[170:173], v140 offset:19456
	ds_read_b128 v[174:177], v140 offset:20480
	ds_read_b128 v[192:195], v140 offset:21504
	ds_read_b128 v[196:199], v140 offset:22528
	ds_read_b128 v[200:203], v140 offset:23552
	global_load_lds_dwordx4 v[232:233], off
	s_mov_b32 m0, s28
	v_lshl_add_u64 v[234:235], s[22:23], 0, v[130:131]
	global_load_lds_dwordx4 v[234:235], off
	s_waitcnt vmcnt(10)
	s_waitcnt lgkmcnt(0)
	s_barrier
	v_mfma_f32_16x16x32_bf16 v[62:65], v[142:145], v[158:161], v[62:65]
	v_mfma_f32_16x16x32_bf16 v[58:61], v[150:153], v[158:161], v[58:61]
	v_mfma_f32_16x16x32_bf16 v[54:57], v[142:145], v[166:169], v[54:57]
	v_mfma_f32_16x16x32_bf16 v[50:53], v[150:153], v[166:169], v[50:53]
	v_mfma_f32_16x16x32_bf16 v[46:49], v[142:145], v[174:177], v[46:49]
	v_mfma_f32_16x16x32_bf16 v[38:41], v[150:153], v[174:177], v[38:41]
	v_mfma_f32_16x16x32_bf16 v[30:33], v[142:145], v[196:199], v[30:33]
	v_mfma_f32_16x16x32_bf16 v[22:25], v[150:153], v[196:199], v[22:25]
	v_mfma_f32_16x16x32_bf16 v[62:65], v[146:149], v[162:165], v[62:65]
	v_mfma_f32_16x16x32_bf16 v[58:61], v[154:157], v[162:165], v[58:61]
	v_mfma_f32_16x16x32_bf16 v[54:57], v[146:149], v[170:173], v[54:57]
	v_mfma_f32_16x16x32_bf16 v[50:53], v[154:157], v[170:173], v[50:53]
	v_mfma_f32_16x16x32_bf16 v[46:49], v[146:149], v[192:195], v[46:49]
	v_mfma_f32_16x16x32_bf16 v[38:41], v[154:157], v[192:195], v[38:41]
	v_mfma_f32_16x16x32_bf16 v[30:33], v[146:149], v[200:203], v[30:33]
	v_mfma_f32_16x16x32_bf16 v[22:25], v[154:157], v[200:203], v[22:25]
	s_barrier
	s_add_u32 s52, s82, 0x80000
	s_addc_u32 s53, s83, 0
	s_add_i32 s54, s54, s26
	s_mov_b32 m0, s54
	v_lshl_add_u64 v[142:143], s[52:53], 0, v[132:133]
	global_load_lds_dwordx4 v[142:143], off
	s_add_i32 m0, s54, 0x2000
	v_lshl_add_u64 v[142:143], s[52:53], 0, v[130:131]
	global_load_lds_dwordx4 v[142:143], off
	v_add_u32_e32 v141, 0x18000, v138
	ds_read_b128 v[142:145], v141
	ds_read_b128 v[146:149], v141 offset:1024
	ds_read_b128 v[150:153], v141 offset:2048
	ds_read_b128 v[154:157], v141 offset:3072
	s_add_i32 s52, 0, 0x18000
	s_waitcnt vmcnt(6)
	s_barrier
	v_mfma_f32_16x16x32_bf16 v[42:45], v[204:207], v[158:161], v[42:45]
	v_mfma_f32_16x16x32_bf16 v[34:37], v[224:227], v[158:161], v[34:37]
	v_mfma_f32_16x16x32_bf16 v[26:29], v[204:207], v[166:169], v[26:29]
	v_mfma_f32_16x16x32_bf16 v[18:21], v[224:227], v[166:169], v[18:21]
	v_mfma_f32_16x16x32_bf16 v[14:17], v[204:207], v[174:177], v[14:17]
	v_mfma_f32_16x16x32_bf16 v[10:13], v[224:227], v[174:177], v[10:13]
	v_mfma_f32_16x16x32_bf16 v[6:9], v[204:207], v[196:199], v[6:9]
	v_mfma_f32_16x16x32_bf16 v[2:5], v[224:227], v[196:199], v[2:5]
	v_mfma_f32_16x16x32_bf16 v[42:45], v[208:211], v[162:165], v[42:45]
	v_mfma_f32_16x16x32_bf16 v[34:37], v[228:231], v[162:165], v[34:37]
	v_mfma_f32_16x16x32_bf16 v[26:29], v[208:211], v[170:173], v[26:29]
	v_mfma_f32_16x16x32_bf16 v[18:21], v[228:231], v[170:173], v[18:21]
	v_mfma_f32_16x16x32_bf16 v[14:17], v[208:211], v[192:195], v[14:17]
	v_mfma_f32_16x16x32_bf16 v[10:13], v[228:231], v[192:195], v[10:13]
	v_mfma_f32_16x16x32_bf16 v[6:9], v[208:211], v[200:203], v[6:9]
	v_mfma_f32_16x16x32_bf16 v[2:5], v[228:231], v[200:203], v[2:5]
	s_barrier
	s_add_u32 s22, s22, 0x80000
	s_addc_u32 s23, s23, 0
	s_mov_b32 m0, s29
	v_lshl_add_u64 v[204:205], s[22:23], 0, v[132:133]
	ds_read_b128 v[158:161], v140 offset:32768
	ds_read_b128 v[162:165], v140 offset:33792
	ds_read_b128 v[166:169], v140 offset:34816
	ds_read_b128 v[170:173], v140 offset:35840
	ds_read_b128 v[174:177], v140 offset:36864
	ds_read_b128 v[192:195], v140 offset:37888
	ds_read_b128 v[196:199], v140 offset:38912
	ds_read_b128 v[200:203], v140 offset:39936
	global_load_lds_dwordx4 v[204:205], off
	s_mov_b32 m0, s36
	v_lshl_add_u64 v[204:205], s[22:23], 0, v[130:131]
	global_load_lds_dwordx4 v[204:205], off
	s_barrier
	s_waitcnt lgkmcnt(0)
	v_mfma_f32_16x16x32_bf16 v[126:129], v[142:145], v[158:161], v[126:129]
	v_mfma_f32_16x16x32_bf16 v[122:125], v[150:153], v[158:161], v[122:125]
	v_mfma_f32_16x16x32_bf16 v[118:121], v[142:145], v[166:169], v[118:121]
	v_mfma_f32_16x16x32_bf16 v[114:117], v[150:153], v[166:169], v[114:117]
	v_mfma_f32_16x16x32_bf16 v[110:113], v[142:145], v[174:177], v[110:113]
	v_mfma_f32_16x16x32_bf16 v[102:105], v[150:153], v[174:177], v[102:105]
	v_mfma_f32_16x16x32_bf16 v[94:97], v[142:145], v[196:199], v[94:97]
	v_mfma_f32_16x16x32_bf16 v[86:89], v[150:153], v[196:199], v[86:89]
	v_mfma_f32_16x16x32_bf16 v[126:129], v[146:149], v[162:165], v[126:129]
	v_mfma_f32_16x16x32_bf16 v[122:125], v[154:157], v[162:165], v[122:125]
	v_mfma_f32_16x16x32_bf16 v[118:121], v[146:149], v[170:173], v[118:121]
	v_mfma_f32_16x16x32_bf16 v[114:117], v[154:157], v[170:173], v[114:117]
	v_mfma_f32_16x16x32_bf16 v[110:113], v[146:149], v[192:195], v[110:113]
	v_mfma_f32_16x16x32_bf16 v[102:105], v[154:157], v[192:195], v[102:105]
	v_mfma_f32_16x16x32_bf16 v[94:97], v[146:149], v[200:203], v[94:97]
	v_mfma_f32_16x16x32_bf16 v[86:89], v[154:157], v[200:203], v[86:89]
	s_barrier
	s_add_i32 s53, 0, 0x1c000
	s_add_i32 s22, s52, s26
	v_add_u32_e32 v141, s53, v138
	v_lshl_add_u64 v[178:179], v[178:179], 0, s[78:79]
	s_mov_b32 m0, s22
	ds_read_b128 v[204:207], v141
	ds_read_b128 v[208:211], v141 offset:1024
	ds_read_b128 v[224:227], v141 offset:2048
	ds_read_b128 v[228:231], v141 offset:3072
	global_load_lds_dwordx4 v[178:179], off
	s_add_i32 m0, s22, 0x2000
	v_lshl_add_u64 v[178:179], v[212:213], 0, s[78:79]
	global_load_lds_dwordx4 v[178:179], off
	s_mov_b32 m0, s42
	v_lshl_add_u64 v[178:179], v[232:233], 0, s[78:79]
	s_waitcnt lgkmcnt(0)
	s_barrier
	v_mfma_f32_16x16x32_bf16 v[106:109], v[204:207], v[158:161], v[106:109]
	v_mfma_f32_16x16x32_bf16 v[98:101], v[224:227], v[158:161], v[98:101]
	v_mfma_f32_16x16x32_bf16 v[90:93], v[204:207], v[166:169], v[90:93]
	v_mfma_f32_16x16x32_bf16 v[82:85], v[224:227], v[166:169], v[82:85]
	v_mfma_f32_16x16x32_bf16 v[78:81], v[204:207], v[174:177], v[78:81]
	v_mfma_f32_16x16x32_bf16 v[74:77], v[224:227], v[174:177], v[74:77]
	v_mfma_f32_16x16x32_bf16 v[70:73], v[204:207], v[196:199], v[70:73]
	v_mfma_f32_16x16x32_bf16 v[66:69], v[224:227], v[196:199], v[66:69]
	v_mfma_f32_16x16x32_bf16 v[106:109], v[208:211], v[162:165], v[106:109]
	v_mfma_f32_16x16x32_bf16 v[98:101], v[228:231], v[162:165], v[98:101]
	v_mfma_f32_16x16x32_bf16 v[90:93], v[208:211], v[170:173], v[90:93]
	v_mfma_f32_16x16x32_bf16 v[82:85], v[228:231], v[170:173], v[82:85]
	v_mfma_f32_16x16x32_bf16 v[78:81], v[208:211], v[192:195], v[78:81]
	v_mfma_f32_16x16x32_bf16 v[74:77], v[228:231], v[192:195], v[74:77]
	v_mfma_f32_16x16x32_bf16 v[70:73], v[208:211], v[200:203], v[70:73]
	v_mfma_f32_16x16x32_bf16 v[66:69], v[228:231], v[200:203], v[66:69]
	s_barrier
	ds_read_b128 v[158:161], v140 offset:49152
	ds_read_b128 v[162:165], v140 offset:50176
	ds_read_b128 v[166:169], v140 offset:51200
	ds_read_b128 v[170:173], v140 offset:52224
	ds_read_b128 v[174:177], v140 offset:53248
	ds_read_b128 v[192:195], v140 offset:54272
	ds_read_b128 v[196:199], v140 offset:55296
	ds_read_b128 v[200:203], v140 offset:56320
	global_load_lds_dwordx4 v[178:179], off
	s_mov_b32 m0, s43
	v_lshl_add_u64 v[178:179], v[234:235], 0, s[78:79]
	global_load_lds_dwordx4 v[178:179], off
	s_waitcnt vmcnt(10)
	s_waitcnt lgkmcnt(0)
	s_barrier
	v_mfma_f32_16x16x32_bf16 v[62:65], v[142:145], v[158:161], v[62:65]
	v_mfma_f32_16x16x32_bf16 v[58:61], v[150:153], v[158:161], v[58:61]
	v_mfma_f32_16x16x32_bf16 v[54:57], v[142:145], v[166:169], v[54:57]
	v_mfma_f32_16x16x32_bf16 v[50:53], v[150:153], v[166:169], v[50:53]
	v_mfma_f32_16x16x32_bf16 v[46:49], v[142:145], v[174:177], v[46:49]
	v_mfma_f32_16x16x32_bf16 v[38:41], v[150:153], v[174:177], v[38:41]
	v_mfma_f32_16x16x32_bf16 v[30:33], v[142:145], v[196:199], v[30:33]
	v_mfma_f32_16x16x32_bf16 v[22:25], v[150:153], v[196:199], v[22:25]
	v_mfma_f32_16x16x32_bf16 v[62:65], v[146:149], v[162:165], v[62:65]
	v_mfma_f32_16x16x32_bf16 v[58:61], v[154:157], v[162:165], v[58:61]
	v_mfma_f32_16x16x32_bf16 v[54:57], v[146:149], v[170:173], v[54:57]
	v_mfma_f32_16x16x32_bf16 v[50:53], v[154:157], v[170:173], v[50:53]
	v_mfma_f32_16x16x32_bf16 v[46:49], v[146:149], v[192:195], v[46:49]
	v_mfma_f32_16x16x32_bf16 v[38:41], v[154:157], v[192:195], v[38:41]
	v_mfma_f32_16x16x32_bf16 v[30:33], v[146:149], v[200:203], v[30:33]
	v_mfma_f32_16x16x32_bf16 v[22:25], v[154:157], v[200:203], v[22:25]
	s_barrier
	s_add_u32 s22, s82, 0x80080
	s_addc_u32 s23, s83, 0
	s_add_i32 s52, s53, s26
	s_mov_b32 m0, s52
	v_lshl_add_u64 v[142:143], s[22:23], 0, v[132:133]
	global_load_lds_dwordx4 v[142:143], off
	s_add_i32 m0, s52, 0x2000
	v_lshl_add_u64 v[142:143], s[22:23], 0, v[130:131]
	global_load_lds_dwordx4 v[142:143], off
	v_add_u32_e32 v141, 0x10000, v138
	ds_read_b128 v[142:145], v141
	ds_read_b128 v[146:149], v141 offset:1024
	ds_read_b128 v[150:153], v141 offset:2048
	ds_read_b128 v[154:157], v141 offset:3072
	s_add_i32 s51, s51, 2
	s_add_u32 s80, s80, 0x100
	s_addc_u32 s81, s81, 0
	s_add_u32 s49, s49, 0x100
	s_addc_u32 s50, s50, 0
	s_cmp_gt_u32 s51, 29
	s_waitcnt vmcnt(6)
	s_barrier
	v_mfma_f32_16x16x32_bf16 v[42:45], v[204:207], v[158:161], v[42:45]
	v_mfma_f32_16x16x32_bf16 v[34:37], v[224:227], v[158:161], v[34:37]
	v_mfma_f32_16x16x32_bf16 v[26:29], v[204:207], v[166:169], v[26:29]
	v_mfma_f32_16x16x32_bf16 v[18:21], v[224:227], v[166:169], v[18:21]
	v_mfma_f32_16x16x32_bf16 v[14:17], v[204:207], v[174:177], v[14:17]
	v_mfma_f32_16x16x32_bf16 v[10:13], v[224:227], v[174:177], v[10:13]
	v_mfma_f32_16x16x32_bf16 v[6:9], v[204:207], v[196:199], v[6:9]
	v_mfma_f32_16x16x32_bf16 v[2:5], v[224:227], v[196:199], v[2:5]
	v_mfma_f32_16x16x32_bf16 v[42:45], v[208:211], v[162:165], v[42:45]
	v_mfma_f32_16x16x32_bf16 v[34:37], v[228:231], v[162:165], v[34:37]
	v_mfma_f32_16x16x32_bf16 v[26:29], v[208:211], v[170:173], v[26:29]
	v_mfma_f32_16x16x32_bf16 v[18:21], v[228:231], v[170:173], v[18:21]
	v_mfma_f32_16x16x32_bf16 v[14:17], v[208:211], v[192:195], v[14:17]
	v_mfma_f32_16x16x32_bf16 v[10:13], v[228:231], v[192:195], v[10:13]
	v_mfma_f32_16x16x32_bf16 v[6:9], v[208:211], v[200:203], v[6:9]
	v_mfma_f32_16x16x32_bf16 v[2:5], v[228:231], v[200:203], v[2:5]
	s_barrier
	s_cbranch_scc0 .LBB0_240
	s_waitcnt lgkmcnt(0)
	v_readlane_b32 s48, v254, 40
	v_lshl_or_b32 v142, s45, 8, v139
	v_readlane_b32 s52, v254, 44
	v_readlane_b32 s53, v254, 45
	v_lshl_add_u32 v141, s46, 8, v1
	v_ashrrev_i32_e32 v143, 31, v142
	v_mov_b64_e32 v[144:145], s[52:53]
	s_movk_i32 s19, 0x1400
	v_mad_i64_i32 v[146:147], s[22:23], v141, s19, v[144:145]
	v_lshlrev_b64 v[142:143], 2, v[142:143]
	v_lshl_add_u64 v[146:147], v[146:147], 0, v[142:143]
	global_store_dwordx4 v[146:147], v[126:129], off
	global_store_dwordx4 v[146:147], v[122:125], off offset:64
	global_store_dwordx4 v[146:147], v[106:109], off offset:512
	global_store_dwordx4 v[146:147], v[98:101], off offset:576
	s_movk_i32 s94, 0x1400
	s_and_b64 vcc, exec, s[0:1]
	v_or_b32_e32 v98, 16, v141
	v_mad_i64_i32 v[98:99], s[22:23], v98, s19, v[144:145]
	v_lshl_add_u64 v[98:99], v[98:99], 0, v[142:143]
	global_store_dwordx4 v[98:99], v[118:121], off
	global_store_dwordx4 v[98:99], v[114:117], off offset:64
	global_store_dwordx4 v[98:99], v[90:93], off offset:512
	global_store_dwordx4 v[98:99], v[82:85], off offset:576
	s_mov_b32 s45, s18
	s_mov_b32 s46, s20
	v_or_b32_e32 v82, 32, v141
	v_mad_i64_i32 v[82:83], s[22:23], v82, s19, v[144:145]
	v_lshl_add_u64 v[82:83], v[82:83], 0, v[142:143]
	global_store_dwordx4 v[82:83], v[110:113], off
	global_store_dwordx4 v[82:83], v[102:105], off offset:64
	global_store_dwordx4 v[82:83], v[78:81], off offset:512
	global_store_dwordx4 v[82:83], v[74:77], off offset:576
	s_mov_b64 s[80:81], s[30:31]
	v_readlane_b32 s49, v254, 41
	v_or_b32_e32 v74, 48, v141
	v_mad_i64_i32 v[74:75], s[22:23], v74, s19, v[144:145]
	v_lshl_add_u64 v[74:75], v[74:75], 0, v[142:143]
	global_store_dwordx4 v[74:75], v[94:97], off
	global_store_dwordx4 v[74:75], v[86:89], off offset:64
	global_store_dwordx4 v[74:75], v[70:73], off offset:512
	global_store_dwordx4 v[74:75], v[66:69], off offset:576
	v_readlane_b32 s50, v254, 42
	v_readlane_b32 s51, v254, 43
	v_add_u32_e32 v66, 0x80, v141
	v_mad_i64_i32 v[66:67], s[22:23], v66, s19, v[144:145]
	v_lshl_add_u64 v[66:67], v[66:67], 0, v[142:143]
	global_store_dwordx4 v[66:67], v[62:65], off
	global_store_dwordx4 v[66:67], v[58:61], off offset:64
	global_store_dwordx4 v[66:67], v[42:45], off offset:512
	global_store_dwordx4 v[66:67], v[34:37], off offset:576
	v_readlane_b32 s54, v254, 46
	v_readlane_b32 s55, v254, 47
	v_add_u32_e32 v34, 0x90, v141
	v_mad_i64_i32 v[34:35], s[22:23], v34, s19, v[144:145]
	v_lshl_add_u64 v[34:35], v[34:35], 0, v[142:143]
	global_store_dwordx4 v[34:35], v[54:57], off
	global_store_dwordx4 v[34:35], v[50:53], off offset:64
	global_store_dwordx4 v[34:35], v[26:29], off offset:512
	global_store_dwordx4 v[34:35], v[18:21], off offset:576
	v_readlane_b32 s56, v254, 48
	v_readlane_b32 s57, v254, 49
	v_add_u32_e32 v18, 0xa0, v141
	v_mad_i64_i32 v[18:19], s[22:23], v18, s19, v[144:145]
	v_lshl_add_u64 v[18:19], v[18:19], 0, v[142:143]
	global_store_dwordx4 v[18:19], v[46:49], off
	global_store_dwordx4 v[18:19], v[38:41], off offset:64
	global_store_dwordx4 v[18:19], v[14:17], off offset:512
	global_store_dwordx4 v[18:19], v[10:13], off offset:576
	v_readlane_b32 s58, v254, 50
	v_readlane_b32 s59, v254, 51
	v_add_u32_e32 v10, 0xb0, v141
	v_mad_i64_i32 v[10:11], s[22:23], v10, s19, v[144:145]
	v_lshl_add_u64 v[10:11], v[10:11], 0, v[142:143]
	s_mov_b64 s[22:23], s[38:39]
	v_readlane_b32 s60, v254, 52
	v_readlane_b32 s61, v254, 53
	v_readlane_b32 s62, v254, 54
	v_readlane_b32 s63, v254, 55
	global_store_dwordx4 v[10:11], v[30:33], off
	global_store_dwordx4 v[10:11], v[22:25], off offset:64
	global_store_dwordx4 v[10:11], v[6:9], off offset:512
	global_store_dwordx4 v[10:11], v[2:5], off offset:576
	s_cbranch_vccz .LBB0_237
	s_waitcnt vmcnt(0)
	v_readlane_b32 s44, v255, 30
	s_cmpk_gt_u32 s25, 0xff
	v_readlane_b32 s45, v255, 31
	v_readlane_b32 s42, v255, 32
	s_cbranch_scc1 .LBB0_244
	s_barrier

.LBB0_357:
	s_add_u32 s22, s20, 0xfffe0080
	s_addc_u32 s23, s21, -1
	s_add_i32 s52, 0, 0x10000
	s_cmp_eq_u32 s51, 4
	s_cselect_b32 s23, s31, s23
	s_cselect_b32 s22, s47, s22
	s_cselect_b32 s85, s19, s50
	s_cselect_b32 s84, s48, s49
	v_lshl_add_u64 v[178:179], s[20:21], 0, v[138:139]
	s_add_i32 m0, s27, 0xc000
	ds_read_b128 v[162:165], v144
	ds_read_b128 v[166:169], v144 offset:1024
	ds_read_b128 v[170:173], v144 offset:2048
	ds_read_b128 v[174:177], v144 offset:3072
	ds_read_b128 v[192:195], v144 offset:4096
	ds_read_b128 v[196:199], v144 offset:5120
	ds_read_b128 v[200:203], v144 offset:6144
	ds_read_b128 v[204:207], v144 offset:7168
	global_load_lds_dwordx4 v[178:179], off
	s_add_i32 m0, s27, 0xe000
	v_lshl_add_u64 v[178:179], s[20:21], 0, v[140:141]
	global_load_lds_dwordx4 v[178:179], off
	s_barrier
	s_waitcnt lgkmcnt(0)
	v_mfma_f32_16x16x32_bf16 v[126:129], v[146:149], v[162:165], v[126:129]
	v_mfma_f32_16x16x32_bf16 v[122:125], v[154:157], v[162:165], v[122:125]
	v_mfma_f32_16x16x32_bf16 v[118:121], v[146:149], v[170:173], v[118:121]
	v_mfma_f32_16x16x32_bf16 v[114:117], v[154:157], v[170:173], v[114:117]
	v_mfma_f32_16x16x32_bf16 v[102:105], v[146:149], v[192:195], v[102:105]
	v_mfma_f32_16x16x32_bf16 v[98:101], v[154:157], v[192:195], v[98:101]
	v_mfma_f32_16x16x32_bf16 v[86:89], v[146:149], v[200:203], v[86:89]
	v_mfma_f32_16x16x32_bf16 v[82:85], v[154:157], v[200:203], v[82:85]
	v_mfma_f32_16x16x32_bf16 v[126:129], v[150:153], v[166:169], v[126:129]
	v_mfma_f32_16x16x32_bf16 v[122:125], v[158:161], v[166:169], v[122:125]
	v_mfma_f32_16x16x32_bf16 v[118:121], v[150:153], v[174:177], v[118:121]
	v_mfma_f32_16x16x32_bf16 v[114:117], v[158:161], v[174:177], v[114:117]
	v_mfma_f32_16x16x32_bf16 v[102:105], v[150:153], v[196:199], v[102:105]
	v_mfma_f32_16x16x32_bf16 v[98:101], v[158:161], v[196:199], v[98:101]
	v_mfma_f32_16x16x32_bf16 v[86:89], v[150:153], v[204:207], v[86:89]
	v_mfma_f32_16x16x32_bf16 v[82:85], v[158:161], v[204:207], v[82:85]
	s_barrier
	s_add_i32 s54, 0, 0x14000
	s_add_i32 s52, s52, s26
	v_add_u32_e32 v145, s54, v142
	v_lshl_add_u64 v[178:179], s[84:85], 0, v[134:135]
	s_mov_b32 m0, s52
	ds_read_b128 v[208:211], v145
	ds_read_b128 v[224:227], v145 offset:1024
	ds_read_b128 v[228:231], v145 offset:2048
	ds_read_b128 v[232:235], v145 offset:3072
	global_load_lds_dwordx4 v[178:179], off
	s_add_i32 m0, s52, 0x2000
	v_lshl_add_u64 v[212:213], s[84:85], 0, v[130:131]
	global_load_lds_dwordx4 v[212:213], off
	s_mov_b32 m0, s27
	v_lshl_add_u64 v[236:237], s[22:23], 0, v[136:137]
	s_waitcnt lgkmcnt(0)
	s_barrier
	v_mfma_f32_16x16x32_bf16 v[110:113], v[208:211], v[162:165], v[110:113]
	v_mfma_f32_16x16x32_bf16 v[106:109], v[228:231], v[162:165], v[106:109]
	v_mfma_f32_16x16x32_bf16 v[94:97], v[208:211], v[170:173], v[94:97]
	v_mfma_f32_16x16x32_bf16 v[90:93], v[228:231], v[170:173], v[90:93]
	v_mfma_f32_16x16x32_bf16 v[78:81], v[208:211], v[192:195], v[78:81]
	v_mfma_f32_16x16x32_bf16 v[74:77], v[228:231], v[192:195], v[74:77]
	v_mfma_f32_16x16x32_bf16 v[70:73], v[208:211], v[200:203], v[70:73]
	v_mfma_f32_16x16x32_bf16 v[66:69], v[228:231], v[200:203], v[66:69]
	v_mfma_f32_16x16x32_bf16 v[110:113], v[224:227], v[166:169], v[110:113]
	v_mfma_f32_16x16x32_bf16 v[106:109], v[232:235], v[166:169], v[106:109]
	v_mfma_f32_16x16x32_bf16 v[94:97], v[224:227], v[174:177], v[94:97]
	v_mfma_f32_16x16x32_bf16 v[90:93], v[232:235], v[174:177], v[90:93]
	v_mfma_f32_16x16x32_bf16 v[78:81], v[224:227], v[196:199], v[78:81]
	v_mfma_f32_16x16x32_bf16 v[74:77], v[232:235], v[196:199], v[74:77]
	v_mfma_f32_16x16x32_bf16 v[70:73], v[224:227], v[204:207], v[70:73]
	v_mfma_f32_16x16x32_bf16 v[66:69], v[232:235], v[204:207], v[66:69]
	s_barrier
	ds_read_b128 v[162:165], v144 offset:16384
	ds_read_b128 v[166:169], v144 offset:17408
	ds_read_b128 v[170:173], v144 offset:18432
	ds_read_b128 v[174:177], v144 offset:19456
	ds_read_b128 v[192:195], v144 offset:20480
	ds_read_b128 v[196:199], v144 offset:21504
	ds_read_b128 v[200:203], v144 offset:22528
	ds_read_b128 v[204:207], v144 offset:23552
	global_load_lds_dwordx4 v[236:237], off
	s_mov_b32 m0, s28
	v_lshl_add_u64 v[238:239], s[22:23], 0, v[132:133]
	global_load_lds_dwordx4 v[238:239], off
	s_waitcnt vmcnt(10)
	s_waitcnt lgkmcnt(0)
	s_barrier
	v_mfma_f32_16x16x32_bf16 v[62:65], v[146:149], v[162:165], v[62:65]
	v_mfma_f32_16x16x32_bf16 v[58:61], v[154:157], v[162:165], v[58:61]
	v_mfma_f32_16x16x32_bf16 v[54:57], v[146:149], v[170:173], v[54:57]
	v_mfma_f32_16x16x32_bf16 v[50:53], v[154:157], v[170:173], v[50:53]
	v_mfma_f32_16x16x32_bf16 v[38:41], v[146:149], v[192:195], v[38:41]
	v_mfma_f32_16x16x32_bf16 v[34:37], v[154:157], v[192:195], v[34:37]
	v_mfma_f32_16x16x32_bf16 v[22:25], v[146:149], v[200:203], v[22:25]
	v_mfma_f32_16x16x32_bf16 v[18:21], v[154:157], v[200:203], v[18:21]
	v_mfma_f32_16x16x32_bf16 v[62:65], v[150:153], v[166:169], v[62:65]
	v_mfma_f32_16x16x32_bf16 v[58:61], v[158:161], v[166:169], v[58:61]
	v_mfma_f32_16x16x32_bf16 v[54:57], v[150:153], v[174:177], v[54:57]
	v_mfma_f32_16x16x32_bf16 v[50:53], v[158:161], v[174:177], v[50:53]
	v_mfma_f32_16x16x32_bf16 v[38:41], v[150:153], v[196:199], v[38:41]
	v_mfma_f32_16x16x32_bf16 v[34:37], v[158:161], v[196:199], v[34:37]
	v_mfma_f32_16x16x32_bf16 v[22:25], v[150:153], v[204:207], v[22:25]
	v_mfma_f32_16x16x32_bf16 v[18:21], v[158:161], v[204:207], v[18:21]
	s_barrier
	s_add_u32 s52, s84, 0x20000
	s_addc_u32 s53, s85, 0
	s_add_i32 s54, s54, s26
	s_mov_b32 m0, s54
	v_lshl_add_u64 v[146:147], s[52:53], 0, v[134:135]
	global_load_lds_dwordx4 v[146:147], off
	s_add_i32 m0, s54, 0x2000
	v_lshl_add_u64 v[146:147], s[52:53], 0, v[130:131]
	global_load_lds_dwordx4 v[146:147], off
	v_add_u32_e32 v145, 0x18000, v142
	ds_read_b128 v[146:149], v145
	ds_read_b128 v[150:153], v145 offset:1024
	ds_read_b128 v[154:157], v145 offset:2048
	ds_read_b128 v[158:161], v145 offset:3072
	s_add_i32 s52, 0, 0x18000
	s_waitcnt vmcnt(6)
	s_barrier
	v_mfma_f32_16x16x32_bf16 v[46:49], v[208:211], v[162:165], v[46:49]
	v_mfma_f32_16x16x32_bf16 v[42:45], v[228:231], v[162:165], v[42:45]
	v_mfma_f32_16x16x32_bf16 v[30:33], v[208:211], v[170:173], v[30:33]
	v_mfma_f32_16x16x32_bf16 v[26:29], v[228:231], v[170:173], v[26:29]
	v_mfma_f32_16x16x32_bf16 v[14:17], v[208:211], v[192:195], v[14:17]
	v_mfma_f32_16x16x32_bf16 v[10:13], v[228:231], v[192:195], v[10:13]
	v_mfma_f32_16x16x32_bf16 v[6:9], v[208:211], v[200:203], v[6:9]
	v_mfma_f32_16x16x32_bf16 v[2:5], v[228:231], v[200:203], v[2:5]
	v_mfma_f32_16x16x32_bf16 v[46:49], v[224:227], v[166:169], v[46:49]
	v_mfma_f32_16x16x32_bf16 v[42:45], v[232:235], v[166:169], v[42:45]
	v_mfma_f32_16x16x32_bf16 v[30:33], v[224:227], v[174:177], v[30:33]
	v_mfma_f32_16x16x32_bf16 v[26:29], v[232:235], v[174:177], v[26:29]
	v_mfma_f32_16x16x32_bf16 v[14:17], v[224:227], v[196:199], v[14:17]
	v_mfma_f32_16x16x32_bf16 v[10:13], v[232:235], v[196:199], v[10:13]
	v_mfma_f32_16x16x32_bf16 v[6:9], v[224:227], v[204:207], v[6:9]
	v_mfma_f32_16x16x32_bf16 v[2:5], v[232:235], v[204:207], v[2:5]
	s_barrier
	s_add_u32 s22, s22, 0x20000
	s_addc_u32 s23, s23, 0
	s_mov_b32 m0, s29
	v_lshl_add_u64 v[208:209], s[22:23], 0, v[136:137]
	ds_read_b128 v[162:165], v144 offset:32768
	ds_read_b128 v[166:169], v144 offset:33792
	ds_read_b128 v[170:173], v144 offset:34816
	ds_read_b128 v[174:177], v144 offset:35840
	ds_read_b128 v[192:195], v144 offset:36864
	ds_read_b128 v[196:199], v144 offset:37888
	ds_read_b128 v[200:203], v144 offset:38912
	ds_read_b128 v[204:207], v144 offset:39936
	global_load_lds_dwordx4 v[208:209], off
	s_mov_b32 m0, s36
	v_lshl_add_u64 v[208:209], s[22:23], 0, v[132:133]
	global_load_lds_dwordx4 v[208:209], off
	s_barrier
	s_waitcnt lgkmcnt(0)
	v_mfma_f32_16x16x32_bf16 v[126:129], v[146:149], v[162:165], v[126:129]
	v_mfma_f32_16x16x32_bf16 v[122:125], v[154:157], v[162:165], v[122:125]
	v_mfma_f32_16x16x32_bf16 v[118:121], v[146:149], v[170:173], v[118:121]
	v_mfma_f32_16x16x32_bf16 v[114:117], v[154:157], v[170:173], v[114:117]
	v_mfma_f32_16x16x32_bf16 v[102:105], v[146:149], v[192:195], v[102:105]
	v_mfma_f32_16x16x32_bf16 v[98:101], v[154:157], v[192:195], v[98:101]
	v_mfma_f32_16x16x32_bf16 v[86:89], v[146:149], v[200:203], v[86:89]
	v_mfma_f32_16x16x32_bf16 v[82:85], v[154:157], v[200:203], v[82:85]
	v_mfma_f32_16x16x32_bf16 v[126:129], v[150:153], v[166:169], v[126:129]
	v_mfma_f32_16x16x32_bf16 v[122:125], v[158:161], v[166:169], v[122:125]
	v_mfma_f32_16x16x32_bf16 v[118:121], v[150:153], v[174:177], v[118:121]
	v_mfma_f32_16x16x32_bf16 v[114:117], v[158:161], v[174:177], v[114:117]
	v_mfma_f32_16x16x32_bf16 v[102:105], v[150:153], v[196:199], v[102:105]
	v_mfma_f32_16x16x32_bf16 v[98:101], v[158:161], v[196:199], v[98:101]
	v_mfma_f32_16x16x32_bf16 v[86:89], v[150:153], v[204:207], v[86:89]
	v_mfma_f32_16x16x32_bf16 v[82:85], v[158:161], v[204:207], v[82:85]
	s_barrier
	s_add_i32 s53, 0, 0x1c000
	s_add_i32 s22, s52, s26
	v_add_u32_e32 v145, s53, v142
	v_lshl_add_u64 v[178:179], v[178:179], 0, s[78:79]
	s_mov_b32 m0, s22
	ds_read_b128 v[208:211], v145
	ds_read_b128 v[224:227], v145 offset:1024
	ds_read_b128 v[228:231], v145 offset:2048
	ds_read_b128 v[232:235], v145 offset:3072
	global_load_lds_dwordx4 v[178:179], off
	s_add_i32 m0, s22, 0x2000
	v_lshl_add_u64 v[178:179], v[212:213], 0, s[78:79]
	global_load_lds_dwordx4 v[178:179], off
	s_mov_b32 m0, s42
	v_lshl_add_u64 v[178:179], v[236:237], 0, s[78:79]
	s_waitcnt lgkmcnt(0)
	s_barrier
	v_mfma_f32_16x16x32_bf16 v[110:113], v[208:211], v[162:165], v[110:113]
	v_mfma_f32_16x16x32_bf16 v[106:109], v[228:231], v[162:165], v[106:109]
	v_mfma_f32_16x16x32_bf16 v[94:97], v[208:211], v[170:173], v[94:97]
	v_mfma_f32_16x16x32_bf16 v[90:93], v[228:231], v[170:173], v[90:93]
	v_mfma_f32_16x16x32_bf16 v[78:81], v[208:211], v[192:195], v[78:81]
	v_mfma_f32_16x16x32_bf16 v[74:77], v[228:231], v[192:195], v[74:77]
	v_mfma_f32_16x16x32_bf16 v[70:73], v[208:211], v[200:203], v[70:73]
	v_mfma_f32_16x16x32_bf16 v[66:69], v[228:231], v[200:203], v[66:69]
	v_mfma_f32_16x16x32_bf16 v[110:113], v[224:227], v[166:169], v[110:113]
	v_mfma_f32_16x16x32_bf16 v[106:109], v[232:235], v[166:169], v[106:109]
	v_mfma_f32_16x16x32_bf16 v[94:97], v[224:227], v[174:177], v[94:97]
	v_mfma_f32_16x16x32_bf16 v[90:93], v[232:235], v[174:177], v[90:93]
	v_mfma_f32_16x16x32_bf16 v[78:81], v[224:227], v[196:199], v[78:81]
	v_mfma_f32_16x16x32_bf16 v[74:77], v[232:235], v[196:199], v[74:77]
	v_mfma_f32_16x16x32_bf16 v[70:73], v[224:227], v[204:207], v[70:73]
	v_mfma_f32_16x16x32_bf16 v[66:69], v[232:235], v[204:207], v[66:69]
	s_barrier
	ds_read_b128 v[162:165], v144 offset:49152
	ds_read_b128 v[166:169], v144 offset:50176
	ds_read_b128 v[170:173], v144 offset:51200
	ds_read_b128 v[174:177], v144 offset:52224
	ds_read_b128 v[192:195], v144 offset:53248
	ds_read_b128 v[196:199], v144 offset:54272
	ds_read_b128 v[200:203], v144 offset:55296
	ds_read_b128 v[204:207], v144 offset:56320
	global_load_lds_dwordx4 v[178:179], off
	s_mov_b32 m0, s43
	v_lshl_add_u64 v[178:179], v[238:239], 0, s[78:79]
	global_load_lds_dwordx4 v[178:179], off
	s_waitcnt vmcnt(10)
	s_waitcnt lgkmcnt(0)
	s_barrier
	v_mfma_f32_16x16x32_bf16 v[62:65], v[146:149], v[162:165], v[62:65]
	v_mfma_f32_16x16x32_bf16 v[58:61], v[154:157], v[162:165], v[58:61]
	v_mfma_f32_16x16x32_bf16 v[54:57], v[146:149], v[170:173], v[54:57]
	v_mfma_f32_16x16x32_bf16 v[50:53], v[154:157], v[170:173], v[50:53]
	v_mfma_f32_16x16x32_bf16 v[38:41], v[146:149], v[192:195], v[38:41]
	v_mfma_f32_16x16x32_bf16 v[34:37], v[154:157], v[192:195], v[34:37]
	v_mfma_f32_16x16x32_bf16 v[22:25], v[146:149], v[200:203], v[22:25]
	v_mfma_f32_16x16x32_bf16 v[18:21], v[154:157], v[200:203], v[18:21]
	v_mfma_f32_16x16x32_bf16 v[62:65], v[150:153], v[166:169], v[62:65]
	v_mfma_f32_16x16x32_bf16 v[58:61], v[158:161], v[166:169], v[58:61]
	v_mfma_f32_16x16x32_bf16 v[54:57], v[150:153], v[174:177], v[54:57]
	v_mfma_f32_16x16x32_bf16 v[50:53], v[158:161], v[174:177], v[50:53]
	v_mfma_f32_16x16x32_bf16 v[38:41], v[150:153], v[196:199], v[38:41]
	v_mfma_f32_16x16x32_bf16 v[34:37], v[158:161], v[196:199], v[34:37]
	v_mfma_f32_16x16x32_bf16 v[22:25], v[150:153], v[204:207], v[22:25]
	v_mfma_f32_16x16x32_bf16 v[18:21], v[158:161], v[204:207], v[18:21]
	s_barrier
	s_add_u32 s22, s84, 0x20080
	s_addc_u32 s23, s85, 0
	s_add_i32 s52, s53, s26
	s_mov_b32 m0, s52
	v_lshl_add_u64 v[146:147], s[22:23], 0, v[134:135]
	global_load_lds_dwordx4 v[146:147], off
	s_add_i32 m0, s52, 0x2000
	v_lshl_add_u64 v[146:147], s[22:23], 0, v[130:131]
	global_load_lds_dwordx4 v[146:147], off
	v_add_u32_e32 v145, 0x10000, v142
	ds_read_b128 v[146:149], v145
	ds_read_b128 v[150:153], v145 offset:1024
	ds_read_b128 v[154:157], v145 offset:2048
	ds_read_b128 v[158:161], v145 offset:3072
	s_add_i32 s51, s51, 2
	s_add_u32 s20, s20, 0x100
	s_addc_u32 s21, s21, 0
	s_add_u32 s49, s49, 0x100
	s_addc_u32 s50, s50, 0
	s_cmp_gt_u32 s51, 5
	s_waitcnt vmcnt(6)
	s_barrier
	v_mfma_f32_16x16x32_bf16 v[46:49], v[208:211], v[162:165], v[46:49]
	v_mfma_f32_16x16x32_bf16 v[42:45], v[228:231], v[162:165], v[42:45]
	v_mfma_f32_16x16x32_bf16 v[30:33], v[208:211], v[170:173], v[30:33]
	v_mfma_f32_16x16x32_bf16 v[26:29], v[228:231], v[170:173], v[26:29]
	v_mfma_f32_16x16x32_bf16 v[14:17], v[208:211], v[192:195], v[14:17]
	v_mfma_f32_16x16x32_bf16 v[10:13], v[228:231], v[192:195], v[10:13]
	v_mfma_f32_16x16x32_bf16 v[6:9], v[208:211], v[200:203], v[6:9]
	v_mfma_f32_16x16x32_bf16 v[2:5], v[228:231], v[200:203], v[2:5]
	v_mfma_f32_16x16x32_bf16 v[46:49], v[224:227], v[166:169], v[46:49]
	v_mfma_f32_16x16x32_bf16 v[42:45], v[232:235], v[166:169], v[42:45]
	v_mfma_f32_16x16x32_bf16 v[30:33], v[224:227], v[174:177], v[30:33]
	v_mfma_f32_16x16x32_bf16 v[26:29], v[232:235], v[174:177], v[26:29]
	v_mfma_f32_16x16x32_bf16 v[14:17], v[224:227], v[196:199], v[14:17]
	v_mfma_f32_16x16x32_bf16 v[10:13], v[232:235], v[196:199], v[10:13]
	v_mfma_f32_16x16x32_bf16 v[6:9], v[224:227], v[204:207], v[6:9]
	v_mfma_f32_16x16x32_bf16 v[2:5], v[232:235], v[204:207], v[2:5]
	s_barrier
	s_cbranch_scc0 .LBB0_357
	s_waitcnt lgkmcnt(0)
	v_lshl_add_u32 v146, s46, 8, v1
	v_lshl_or_b32 v148, s45, 8, v143
	v_ashrrev_i32_e32 v147, 31, v146
	v_readlane_b32 s48, v254, 40
	v_ashrrev_i32_e32 v149, 31, v148
	v_lshlrev_b64 v[150:151], 12, v[146:147]
	v_readlane_b32 s60, v254, 52
	v_readlane_b32 s61, v254, 53
	v_lshlrev_b64 v[148:149], 1, v[148:149]
	s_mov_b32 s19, 0x80000
	v_lshl_add_u64 v[150:151], s[60:61], 0, v[150:151]
	v_lshl_add_u64 v[150:151], v[150:151], 0, v[148:149]
	s_mov_b64 s[20:21], 0x80000
	v_cvt_pk_bf16_f32 v62, v62, v63
	v_cvt_pk_bf16_f32 v63, v64, v65
	v_cvt_pk_bf16_f32 v64, v58, v59
	v_add_co_u32_e32 v58, vcc, s19, v150
	v_cvt_pk_bf16_f32 v70, v70, v71
	v_cvt_pk_bf16_f32 v71, v72, v73
	v_cvt_pk_bf16_f32 v72, v66, v67
	v_lshl_add_u64 v[66:67], v[150:151], 0, s[20:21]
	v_addc_co_u32_e32 v59, vcc, 0, v151, vcc
	v_cvt_pk_bf16_f32 v46, v46, v47
	v_cvt_pk_bf16_f32 v47, v48, v49
	v_cvt_pk_bf16_f32 v48, v42, v43
	v_cvt_pk_bf16_f32 v49, v44, v45
	s_mov_b32 s19, 0x90000
	v_cvt_pk_bf16_f32 v110, v110, v111
	v_cvt_pk_bf16_f32 v111, v112, v113
	v_cvt_pk_bf16_f32 v112, v106, v107
	v_or_b32_e32 v106, 16, v146
	global_store_dwordx4 v[66:67], v[46:49], off offset:256
	s_mov_b64 s[20:21], 0x90000
	v_ashrrev_i32_e32 v107, 31, v106
	v_add_co_u32_e32 v48, vcc, s19, v150
	v_cvt_pk_bf16_f32 v94, v94, v95
	v_cvt_pk_bf16_f32 v95, v96, v97
	v_cvt_pk_bf16_f32 v96, v90, v91
	v_or_b32_e32 v90, 32, v146
	v_lshl_add_u64 v[46:47], v[150:151], 0, s[20:21]
	v_addc_co_u32_e32 v49, vcc, 0, v151, vcc
	v_cvt_pk_bf16_f32 v30, v30, v31
	v_cvt_pk_bf16_f32 v31, v32, v33
	v_cvt_pk_bf16_f32 v32, v26, v27
	v_cvt_pk_bf16_f32 v33, v28, v29
	s_mov_b32 s19, 0xa0000
	v_lshlrev_b64 v[106:107], 12, v[106:107]
	v_ashrrev_i32_e32 v91, 31, v90
	v_cvt_pk_bf16_f32 v78, v78, v79
	v_cvt_pk_bf16_f32 v79, v80, v81
	v_cvt_pk_bf16_f32 v80, v74, v75
	v_or_b32_e32 v74, 48, v146
	global_store_dwordx4 v[46:47], v[30:33], off offset:256
	s_mov_b64 s[20:21], 0xa0000
	v_cvt_pk_bf16_f32 v113, v108, v109
	v_add_co_u32_e32 v32, vcc, s19, v150
	v_lshl_add_u64 v[106:107], s[60:61], 0, v[106:107]
	v_lshlrev_b64 v[90:91], 12, v[90:91]
	v_ashrrev_i32_e32 v75, 31, v74
	v_lshl_add_u64 v[30:31], v[150:151], 0, s[20:21]
	v_addc_co_u32_e32 v33, vcc, 0, v151, vcc
	v_cvt_pk_bf16_f32 v14, v14, v15
	v_cvt_pk_bf16_f32 v15, v16, v17
	v_cvt_pk_bf16_f32 v16, v10, v11
	v_cvt_pk_bf16_f32 v17, v12, v13
	s_mov_b32 s19, 0xb0000
	global_store_dwordx4 v[150:151], v[110:113], off offset:256
	v_cvt_pk_bf16_f32 v97, v92, v93
	v_lshl_add_u64 v[90:91], s[60:61], 0, v[90:91]
	v_lshl_add_u64 v[110:111], v[106:107], 0, v[148:149]
	v_lshlrev_b64 v[74:75], 12, v[74:75]
	global_store_dwordx4 v[30:31], v[14:17], off offset:256
	global_store_dwordx4 v[110:111], v[94:97], off offset:256
	v_cvt_pk_bf16_f32 v81, v76, v77
	v_add_co_u32_e32 v16, vcc, s19, v150
	v_lshl_add_u64 v[94:95], v[90:91], 0, v[148:149]
	v_lshl_add_u64 v[74:75], s[60:61], 0, v[74:75]
	s_mov_b64 s[20:21], 0xb0000
	v_addc_co_u32_e32 v17, vcc, 0, v151, vcc
	v_cvt_pk_bf16_f32 v126, v126, v127
	v_cvt_pk_bf16_f32 v127, v128, v129
	v_cvt_pk_bf16_f32 v128, v122, v123
	v_cvt_pk_bf16_f32 v129, v124, v125
	v_cvt_pk_bf16_f32 v106, v118, v119
	v_cvt_pk_bf16_f32 v107, v120, v121
	v_cvt_pk_bf16_f32 v108, v114, v115
	v_cvt_pk_bf16_f32 v109, v116, v117
	v_cvt_pk_bf16_f32 v90, v102, v103
	v_cvt_pk_bf16_f32 v91, v104, v105
	v_cvt_pk_bf16_f32 v92, v98, v99
	v_cvt_pk_bf16_f32 v93, v100, v101
	global_store_dwordx4 v[94:95], v[78:81], off offset:256
	v_cvt_pk_bf16_f32 v76, v82, v83
	v_cvt_pk_bf16_f32 v77, v84, v85
	v_lshl_add_u64 v[78:79], v[74:75], 0, v[148:149]
	v_cvt_pk_bf16_f32 v74, v86, v87
	v_cvt_pk_bf16_f32 v75, v88, v89
	v_cvt_pk_bf16_f32 v73, v68, v69
	v_cvt_pk_bf16_f32 v65, v60, v61
	v_cvt_pk_bf16_f32 v42, v54, v55
	v_cvt_pk_bf16_f32 v43, v56, v57
	v_cvt_pk_bf16_f32 v44, v50, v51
	v_cvt_pk_bf16_f32 v45, v52, v53
	v_cvt_pk_bf16_f32 v26, v38, v39
	v_cvt_pk_bf16_f32 v27, v40, v41
	v_cvt_pk_bf16_f32 v28, v34, v35
	v_cvt_pk_bf16_f32 v29, v36, v37
	v_lshl_add_u64 v[14:15], v[150:151], 0, s[20:21]
	v_cvt_pk_bf16_f32 v10, v22, v23
	v_cvt_pk_bf16_f32 v11, v24, v25
	v_cvt_pk_bf16_f32 v12, v18, v19
	v_cvt_pk_bf16_f32 v13, v20, v21
	v_cvt_pk_bf16_f32 v6, v6, v7
	v_cvt_pk_bf16_f32 v7, v8, v9
	v_cvt_pk_bf16_f32 v8, v2, v3
	v_cvt_pk_bf16_f32 v9, v4, v5
	s_and_b64 vcc, exec, s[38:39]
	s_mov_b32 s45, s18
	s_mov_b32 s46, s30
	s_mov_b64 s[22:23], s[82:83]
	s_mov_b64 s[20:21], s[80:81]
	s_mov_b32 s64, 0x800000
	s_movk_i32 s65, 0x1fff
	v_readlane_b32 s49, v254, 41
	v_readlane_b32 s50, v254, 42
	v_readlane_b32 s51, v254, 43
	v_readlane_b32 s52, v254, 44
	v_readlane_b32 s53, v254, 45
	v_readlane_b32 s54, v254, 46
	v_readlane_b32 s55, v254, 47
	v_readlane_b32 s56, v254, 48
	v_readlane_b32 s57, v254, 49
	v_readlane_b32 s58, v254, 50
	v_readlane_b32 s59, v254, 51
	v_readlane_b32 s62, v254, 54
	v_readlane_b32 s63, v254, 55
	global_store_dwordx4 v[150:151], v[126:129], off
	global_store_dwordx4 v[110:111], v[106:109], off
	global_store_dwordx4 v[94:95], v[90:93], off
	global_store_dwordx4 v[78:79], v[74:77], off
	global_store_dwordx4 v[78:79], v[70:73], off offset:256
	global_store_dwordx4 v[58:59], v[62:65], off
	global_store_dwordx4 v[48:49], v[42:45], off
	global_store_dwordx4 v[32:33], v[26:29], off
	global_store_dwordx4 v[16:17], v[10:13], off
	global_store_dwordx4 v[14:15], v[6:9], off offset:256
	s_cbranch_vccz .LBB0_350
	s_waitcnt vmcnt(0)
	v_readlane_b32 s44, v255, 30
	s_mov_b32 s66, s90
	s_cmpk_gt_u32 s25, 0xff
	v_readlane_b32 s45, v255, 31
	v_readlane_b32 s42, v255, 32
	s_cbranch_scc1 .LBB0_361
	s_barrier

.LBB0_373:
	s_add_u32 s22, s20, 0xfffe0080
	s_addc_u32 s23, s21, -1
	s_add_i32 s52, 0, 0x10000
	s_cmp_eq_u32 s51, 4
	s_cselect_b32 s23, s31, s23
	s_cselect_b32 s22, s47, s22
	s_cselect_b32 s83, s19, s50
	s_cselect_b32 s82, s48, s49
	v_lshl_add_u64 v[178:179], s[20:21], 0, v[138:139]
	s_add_i32 m0, s27, 0xc000
	ds_read_b128 v[162:165], v144
	ds_read_b128 v[166:169], v144 offset:1024
	ds_read_b128 v[170:173], v144 offset:2048
	ds_read_b128 v[174:177], v144 offset:3072
	ds_read_b128 v[192:195], v144 offset:4096
	ds_read_b128 v[196:199], v144 offset:5120
	ds_read_b128 v[200:203], v144 offset:6144
	ds_read_b128 v[204:207], v144 offset:7168
	global_load_lds_dwordx4 v[178:179], off
	s_add_i32 m0, s27, 0xe000
	v_lshl_add_u64 v[178:179], s[20:21], 0, v[140:141]
	global_load_lds_dwordx4 v[178:179], off
	s_barrier
	s_waitcnt lgkmcnt(0)
	v_mfma_f32_16x16x32_bf16 v[126:129], v[146:149], v[162:165], v[126:129]
	v_mfma_f32_16x16x32_bf16 v[122:125], v[154:157], v[162:165], v[122:125]
	v_mfma_f32_16x16x32_bf16 v[118:121], v[146:149], v[170:173], v[118:121]
	v_mfma_f32_16x16x32_bf16 v[114:117], v[154:157], v[170:173], v[114:117]
	v_mfma_f32_16x16x32_bf16 v[102:105], v[146:149], v[192:195], v[102:105]
	v_mfma_f32_16x16x32_bf16 v[98:101], v[154:157], v[192:195], v[98:101]
	v_mfma_f32_16x16x32_bf16 v[86:89], v[146:149], v[200:203], v[86:89]
	v_mfma_f32_16x16x32_bf16 v[82:85], v[154:157], v[200:203], v[82:85]
	v_mfma_f32_16x16x32_bf16 v[126:129], v[150:153], v[166:169], v[126:129]
	v_mfma_f32_16x16x32_bf16 v[122:125], v[158:161], v[166:169], v[122:125]
	v_mfma_f32_16x16x32_bf16 v[118:121], v[150:153], v[174:177], v[118:121]
	v_mfma_f32_16x16x32_bf16 v[114:117], v[158:161], v[174:177], v[114:117]
	v_mfma_f32_16x16x32_bf16 v[102:105], v[150:153], v[196:199], v[102:105]
	v_mfma_f32_16x16x32_bf16 v[98:101], v[158:161], v[196:199], v[98:101]
	v_mfma_f32_16x16x32_bf16 v[86:89], v[150:153], v[204:207], v[86:89]
	v_mfma_f32_16x16x32_bf16 v[82:85], v[158:161], v[204:207], v[82:85]
	s_barrier
	s_add_i32 s54, 0, 0x14000
	s_add_i32 s52, s52, s26
	v_add_u32_e32 v145, s54, v142
	v_lshl_add_u64 v[178:179], s[82:83], 0, v[134:135]
	s_mov_b32 m0, s52
	ds_read_b128 v[208:211], v145
	ds_read_b128 v[224:227], v145 offset:1024
	ds_read_b128 v[228:231], v145 offset:2048
	ds_read_b128 v[232:235], v145 offset:3072
	global_load_lds_dwordx4 v[178:179], off
	s_add_i32 m0, s52, 0x2000
	v_lshl_add_u64 v[212:213], s[82:83], 0, v[130:131]
	global_load_lds_dwordx4 v[212:213], off
	s_mov_b32 m0, s27
	v_lshl_add_u64 v[236:237], s[22:23], 0, v[136:137]
	s_waitcnt lgkmcnt(0)
	s_barrier
	v_mfma_f32_16x16x32_bf16 v[110:113], v[208:211], v[162:165], v[110:113]
	v_mfma_f32_16x16x32_bf16 v[106:109], v[228:231], v[162:165], v[106:109]
	v_mfma_f32_16x16x32_bf16 v[94:97], v[208:211], v[170:173], v[94:97]
	v_mfma_f32_16x16x32_bf16 v[90:93], v[228:231], v[170:173], v[90:93]
	v_mfma_f32_16x16x32_bf16 v[78:81], v[208:211], v[192:195], v[78:81]
	v_mfma_f32_16x16x32_bf16 v[74:77], v[228:231], v[192:195], v[74:77]
	v_mfma_f32_16x16x32_bf16 v[70:73], v[208:211], v[200:203], v[70:73]
	v_mfma_f32_16x16x32_bf16 v[66:69], v[228:231], v[200:203], v[66:69]
	v_mfma_f32_16x16x32_bf16 v[110:113], v[224:227], v[166:169], v[110:113]
	v_mfma_f32_16x16x32_bf16 v[106:109], v[232:235], v[166:169], v[106:109]
	v_mfma_f32_16x16x32_bf16 v[94:97], v[224:227], v[174:177], v[94:97]
	v_mfma_f32_16x16x32_bf16 v[90:93], v[232:235], v[174:177], v[90:93]
	v_mfma_f32_16x16x32_bf16 v[78:81], v[224:227], v[196:199], v[78:81]
	v_mfma_f32_16x16x32_bf16 v[74:77], v[232:235], v[196:199], v[74:77]
	v_mfma_f32_16x16x32_bf16 v[70:73], v[224:227], v[204:207], v[70:73]
	v_mfma_f32_16x16x32_bf16 v[66:69], v[232:235], v[204:207], v[66:69]
	s_barrier
	ds_read_b128 v[162:165], v144 offset:16384
	ds_read_b128 v[166:169], v144 offset:17408
	ds_read_b128 v[170:173], v144 offset:18432
	ds_read_b128 v[174:177], v144 offset:19456
	ds_read_b128 v[192:195], v144 offset:20480
	ds_read_b128 v[196:199], v144 offset:21504
	ds_read_b128 v[200:203], v144 offset:22528
	ds_read_b128 v[204:207], v144 offset:23552
	global_load_lds_dwordx4 v[236:237], off
	s_mov_b32 m0, s28
	v_lshl_add_u64 v[238:239], s[22:23], 0, v[132:133]
	global_load_lds_dwordx4 v[238:239], off
	s_waitcnt vmcnt(10)
	s_waitcnt lgkmcnt(0)
	s_barrier
	v_mfma_f32_16x16x32_bf16 v[62:65], v[146:149], v[162:165], v[62:65]
	v_mfma_f32_16x16x32_bf16 v[58:61], v[154:157], v[162:165], v[58:61]
	v_mfma_f32_16x16x32_bf16 v[54:57], v[146:149], v[170:173], v[54:57]
	v_mfma_f32_16x16x32_bf16 v[50:53], v[154:157], v[170:173], v[50:53]
	v_mfma_f32_16x16x32_bf16 v[38:41], v[146:149], v[192:195], v[38:41]
	v_mfma_f32_16x16x32_bf16 v[34:37], v[154:157], v[192:195], v[34:37]
	v_mfma_f32_16x16x32_bf16 v[22:25], v[146:149], v[200:203], v[22:25]
	v_mfma_f32_16x16x32_bf16 v[18:21], v[154:157], v[200:203], v[18:21]
	v_mfma_f32_16x16x32_bf16 v[62:65], v[150:153], v[166:169], v[62:65]
	v_mfma_f32_16x16x32_bf16 v[58:61], v[158:161], v[166:169], v[58:61]
	v_mfma_f32_16x16x32_bf16 v[54:57], v[150:153], v[174:177], v[54:57]
	v_mfma_f32_16x16x32_bf16 v[50:53], v[158:161], v[174:177], v[50:53]
	v_mfma_f32_16x16x32_bf16 v[38:41], v[150:153], v[196:199], v[38:41]
	v_mfma_f32_16x16x32_bf16 v[34:37], v[158:161], v[196:199], v[34:37]
	v_mfma_f32_16x16x32_bf16 v[22:25], v[150:153], v[204:207], v[22:25]
	v_mfma_f32_16x16x32_bf16 v[18:21], v[158:161], v[204:207], v[18:21]
	s_barrier
	s_add_u32 s52, s82, 0x20000
	s_addc_u32 s53, s83, 0
	s_add_i32 s54, s54, s26
	s_mov_b32 m0, s54
	v_lshl_add_u64 v[146:147], s[52:53], 0, v[134:135]
	global_load_lds_dwordx4 v[146:147], off
	s_add_i32 m0, s54, 0x2000
	v_lshl_add_u64 v[146:147], s[52:53], 0, v[130:131]
	global_load_lds_dwordx4 v[146:147], off
	v_add_u32_e32 v145, 0x18000, v142
	ds_read_b128 v[146:149], v145
	ds_read_b128 v[150:153], v145 offset:1024
	ds_read_b128 v[154:157], v145 offset:2048
	ds_read_b128 v[158:161], v145 offset:3072
	s_add_i32 s52, 0, 0x18000
	s_waitcnt vmcnt(6)
	s_barrier
	v_mfma_f32_16x16x32_bf16 v[46:49], v[208:211], v[162:165], v[46:49]
	v_mfma_f32_16x16x32_bf16 v[42:45], v[228:231], v[162:165], v[42:45]
	v_mfma_f32_16x16x32_bf16 v[30:33], v[208:211], v[170:173], v[30:33]
	v_mfma_f32_16x16x32_bf16 v[26:29], v[228:231], v[170:173], v[26:29]
	v_mfma_f32_16x16x32_bf16 v[14:17], v[208:211], v[192:195], v[14:17]
	v_mfma_f32_16x16x32_bf16 v[10:13], v[228:231], v[192:195], v[10:13]
	v_mfma_f32_16x16x32_bf16 v[6:9], v[208:211], v[200:203], v[6:9]
	v_mfma_f32_16x16x32_bf16 v[2:5], v[228:231], v[200:203], v[2:5]
	v_mfma_f32_16x16x32_bf16 v[46:49], v[224:227], v[166:169], v[46:49]
	v_mfma_f32_16x16x32_bf16 v[42:45], v[232:235], v[166:169], v[42:45]
	v_mfma_f32_16x16x32_bf16 v[30:33], v[224:227], v[174:177], v[30:33]
	v_mfma_f32_16x16x32_bf16 v[26:29], v[232:235], v[174:177], v[26:29]
	v_mfma_f32_16x16x32_bf16 v[14:17], v[224:227], v[196:199], v[14:17]
	v_mfma_f32_16x16x32_bf16 v[10:13], v[232:235], v[196:199], v[10:13]
	v_mfma_f32_16x16x32_bf16 v[6:9], v[224:227], v[204:207], v[6:9]
	v_mfma_f32_16x16x32_bf16 v[2:5], v[232:235], v[204:207], v[2:5]
	s_barrier
	s_add_u32 s22, s22, 0x20000
	s_addc_u32 s23, s23, 0
	s_mov_b32 m0, s29
	v_lshl_add_u64 v[208:209], s[22:23], 0, v[136:137]
	ds_read_b128 v[162:165], v144 offset:32768
	ds_read_b128 v[166:169], v144 offset:33792
	ds_read_b128 v[170:173], v144 offset:34816
	ds_read_b128 v[174:177], v144 offset:35840
	ds_read_b128 v[192:195], v144 offset:36864
	ds_read_b128 v[196:199], v144 offset:37888
	ds_read_b128 v[200:203], v144 offset:38912
	ds_read_b128 v[204:207], v144 offset:39936
	global_load_lds_dwordx4 v[208:209], off
	s_mov_b32 m0, s36
	v_lshl_add_u64 v[208:209], s[22:23], 0, v[132:133]
	global_load_lds_dwordx4 v[208:209], off
	s_barrier
	s_waitcnt lgkmcnt(0)
	v_mfma_f32_16x16x32_bf16 v[126:129], v[146:149], v[162:165], v[126:129]
	v_mfma_f32_16x16x32_bf16 v[122:125], v[154:157], v[162:165], v[122:125]
	v_mfma_f32_16x16x32_bf16 v[118:121], v[146:149], v[170:173], v[118:121]
	v_mfma_f32_16x16x32_bf16 v[114:117], v[154:157], v[170:173], v[114:117]
	v_mfma_f32_16x16x32_bf16 v[102:105], v[146:149], v[192:195], v[102:105]
	v_mfma_f32_16x16x32_bf16 v[98:101], v[154:157], v[192:195], v[98:101]
	v_mfma_f32_16x16x32_bf16 v[86:89], v[146:149], v[200:203], v[86:89]
	v_mfma_f32_16x16x32_bf16 v[82:85], v[154:157], v[200:203], v[82:85]
	v_mfma_f32_16x16x32_bf16 v[126:129], v[150:153], v[166:169], v[126:129]
	v_mfma_f32_16x16x32_bf16 v[122:125], v[158:161], v[166:169], v[122:125]
	v_mfma_f32_16x16x32_bf16 v[118:121], v[150:153], v[174:177], v[118:121]
	v_mfma_f32_16x16x32_bf16 v[114:117], v[158:161], v[174:177], v[114:117]
	v_mfma_f32_16x16x32_bf16 v[102:105], v[150:153], v[196:199], v[102:105]
	v_mfma_f32_16x16x32_bf16 v[98:101], v[158:161], v[196:199], v[98:101]
	v_mfma_f32_16x16x32_bf16 v[86:89], v[150:153], v[204:207], v[86:89]
	v_mfma_f32_16x16x32_bf16 v[82:85], v[158:161], v[204:207], v[82:85]
	s_barrier
	s_add_i32 s53, 0, 0x1c000
	s_add_i32 s22, s52, s26
	v_add_u32_e32 v145, s53, v142
	v_lshl_add_u64 v[178:179], v[178:179], 0, s[78:79]
	s_mov_b32 m0, s22
	ds_read_b128 v[208:211], v145
	ds_read_b128 v[224:227], v145 offset:1024
	ds_read_b128 v[228:231], v145 offset:2048
	ds_read_b128 v[232:235], v145 offset:3072
	global_load_lds_dwordx4 v[178:179], off
	s_add_i32 m0, s22, 0x2000
	v_lshl_add_u64 v[178:179], v[212:213], 0, s[78:79]
	global_load_lds_dwordx4 v[178:179], off
	s_mov_b32 m0, s42
	v_lshl_add_u64 v[178:179], v[236:237], 0, s[78:79]
	s_waitcnt lgkmcnt(0)
	s_barrier
	v_mfma_f32_16x16x32_bf16 v[110:113], v[208:211], v[162:165], v[110:113]
	v_mfma_f32_16x16x32_bf16 v[106:109], v[228:231], v[162:165], v[106:109]
	v_mfma_f32_16x16x32_bf16 v[94:97], v[208:211], v[170:173], v[94:97]
	v_mfma_f32_16x16x32_bf16 v[90:93], v[228:231], v[170:173], v[90:93]
	v_mfma_f32_16x16x32_bf16 v[78:81], v[208:211], v[192:195], v[78:81]
	v_mfma_f32_16x16x32_bf16 v[74:77], v[228:231], v[192:195], v[74:77]
	v_mfma_f32_16x16x32_bf16 v[70:73], v[208:211], v[200:203], v[70:73]
	v_mfma_f32_16x16x32_bf16 v[66:69], v[228:231], v[200:203], v[66:69]
	v_mfma_f32_16x16x32_bf16 v[110:113], v[224:227], v[166:169], v[110:113]
	v_mfma_f32_16x16x32_bf16 v[106:109], v[232:235], v[166:169], v[106:109]
	v_mfma_f32_16x16x32_bf16 v[94:97], v[224:227], v[174:177], v[94:97]
	v_mfma_f32_16x16x32_bf16 v[90:93], v[232:235], v[174:177], v[90:93]
	v_mfma_f32_16x16x32_bf16 v[78:81], v[224:227], v[196:199], v[78:81]
	v_mfma_f32_16x16x32_bf16 v[74:77], v[232:235], v[196:199], v[74:77]
	v_mfma_f32_16x16x32_bf16 v[70:73], v[224:227], v[204:207], v[70:73]
	v_mfma_f32_16x16x32_bf16 v[66:69], v[232:235], v[204:207], v[66:69]
	s_barrier
	ds_read_b128 v[162:165], v144 offset:49152
	ds_read_b128 v[166:169], v144 offset:50176
	ds_read_b128 v[170:173], v144 offset:51200
	ds_read_b128 v[174:177], v144 offset:52224
	ds_read_b128 v[192:195], v144 offset:53248
	ds_read_b128 v[196:199], v144 offset:54272
	ds_read_b128 v[200:203], v144 offset:55296
	ds_read_b128 v[204:207], v144 offset:56320
	global_load_lds_dwordx4 v[178:179], off
	s_mov_b32 m0, s43
	v_lshl_add_u64 v[178:179], v[238:239], 0, s[78:79]
	global_load_lds_dwordx4 v[178:179], off
	s_waitcnt vmcnt(10)
	s_waitcnt lgkmcnt(0)
	s_barrier
	v_mfma_f32_16x16x32_bf16 v[62:65], v[146:149], v[162:165], v[62:65]
	v_mfma_f32_16x16x32_bf16 v[58:61], v[154:157], v[162:165], v[58:61]
	v_mfma_f32_16x16x32_bf16 v[54:57], v[146:149], v[170:173], v[54:57]
	v_mfma_f32_16x16x32_bf16 v[50:53], v[154:157], v[170:173], v[50:53]
	v_mfma_f32_16x16x32_bf16 v[38:41], v[146:149], v[192:195], v[38:41]
	v_mfma_f32_16x16x32_bf16 v[34:37], v[154:157], v[192:195], v[34:37]
	v_mfma_f32_16x16x32_bf16 v[22:25], v[146:149], v[200:203], v[22:25]
	v_mfma_f32_16x16x32_bf16 v[18:21], v[154:157], v[200:203], v[18:21]
	v_mfma_f32_16x16x32_bf16 v[62:65], v[150:153], v[166:169], v[62:65]
	v_mfma_f32_16x16x32_bf16 v[58:61], v[158:161], v[166:169], v[58:61]
	v_mfma_f32_16x16x32_bf16 v[54:57], v[150:153], v[174:177], v[54:57]
	v_mfma_f32_16x16x32_bf16 v[50:53], v[158:161], v[174:177], v[50:53]
	v_mfma_f32_16x16x32_bf16 v[38:41], v[150:153], v[196:199], v[38:41]
	v_mfma_f32_16x16x32_bf16 v[34:37], v[158:161], v[196:199], v[34:37]
	v_mfma_f32_16x16x32_bf16 v[22:25], v[150:153], v[204:207], v[22:25]
	v_mfma_f32_16x16x32_bf16 v[18:21], v[158:161], v[204:207], v[18:21]
	s_barrier
	s_add_u32 s22, s82, 0x20080
	s_addc_u32 s23, s83, 0
	s_add_i32 s52, s53, s26
	s_mov_b32 m0, s52
	v_lshl_add_u64 v[146:147], s[22:23], 0, v[134:135]
	global_load_lds_dwordx4 v[146:147], off
	s_add_i32 m0, s52, 0x2000
	v_lshl_add_u64 v[146:147], s[22:23], 0, v[130:131]
	global_load_lds_dwordx4 v[146:147], off
	v_add_u32_e32 v145, 0x10000, v142
	ds_read_b128 v[146:149], v145
	ds_read_b128 v[150:153], v145 offset:1024
	ds_read_b128 v[154:157], v145 offset:2048
	ds_read_b128 v[158:161], v145 offset:3072
	s_add_i32 s51, s51, 2
	s_add_u32 s20, s20, 0x100
	s_addc_u32 s21, s21, 0
	s_add_u32 s49, s49, 0x100
	s_addc_u32 s50, s50, 0
	s_cmp_gt_u32 s51, 5
	s_waitcnt vmcnt(6)
	s_barrier
	v_mfma_f32_16x16x32_bf16 v[46:49], v[208:211], v[162:165], v[46:49]
	v_mfma_f32_16x16x32_bf16 v[42:45], v[228:231], v[162:165], v[42:45]
	v_mfma_f32_16x16x32_bf16 v[30:33], v[208:211], v[170:173], v[30:33]
	v_mfma_f32_16x16x32_bf16 v[26:29], v[228:231], v[170:173], v[26:29]
	v_mfma_f32_16x16x32_bf16 v[14:17], v[208:211], v[192:195], v[14:17]
	v_mfma_f32_16x16x32_bf16 v[10:13], v[228:231], v[192:195], v[10:13]
	v_mfma_f32_16x16x32_bf16 v[6:9], v[208:211], v[200:203], v[6:9]
	v_mfma_f32_16x16x32_bf16 v[2:5], v[228:231], v[200:203], v[2:5]
	v_mfma_f32_16x16x32_bf16 v[46:49], v[224:227], v[166:169], v[46:49]
	v_mfma_f32_16x16x32_bf16 v[42:45], v[232:235], v[166:169], v[42:45]
	v_mfma_f32_16x16x32_bf16 v[30:33], v[224:227], v[174:177], v[30:33]
	v_mfma_f32_16x16x32_bf16 v[26:29], v[232:235], v[174:177], v[26:29]
	v_mfma_f32_16x16x32_bf16 v[14:17], v[224:227], v[196:199], v[14:17]
	v_mfma_f32_16x16x32_bf16 v[10:13], v[232:235], v[196:199], v[10:13]
	v_mfma_f32_16x16x32_bf16 v[6:9], v[224:227], v[204:207], v[6:9]
	v_mfma_f32_16x16x32_bf16 v[2:5], v[232:235], v[204:207], v[2:5]
	s_barrier
	s_cbranch_scc0 .LBB0_373
	s_waitcnt lgkmcnt(0)
	v_lshl_add_u32 v146, s46, 8, v1
	v_lshl_or_b32 v148, s45, 8, v143
	v_ashrrev_i32_e32 v147, 31, v146
	v_readlane_b32 s48, v254, 40
	v_ashrrev_i32_e32 v149, 31, v148
	v_lshlrev_b64 v[150:151], 14, v[146:147]
	v_readlane_b32 s62, v254, 54
	v_readlane_b32 s63, v254, 55
	v_lshlrev_b64 v[148:149], 1, v[148:149]
	s_mov_b32 s19, 0x200000
	v_lshl_add_u64 v[150:151], s[62:63], 0, v[150:151]
	v_lshl_add_u64 v[150:151], v[150:151], 0, v[148:149]
	s_mov_b64 s[20:21], 0x200000
	v_cvt_pk_bf16_f32 v62, v62, v63
	v_cvt_pk_bf16_f32 v63, v64, v65
	v_cvt_pk_bf16_f32 v64, v58, v59
	v_add_co_u32_e32 v58, vcc, s19, v150
	v_cvt_pk_bf16_f32 v70, v70, v71
	v_cvt_pk_bf16_f32 v71, v72, v73
	v_cvt_pk_bf16_f32 v72, v66, v67
	v_lshl_add_u64 v[66:67], v[150:151], 0, s[20:21]
	v_addc_co_u32_e32 v59, vcc, 0, v151, vcc
	v_cvt_pk_bf16_f32 v46, v46, v47
	v_cvt_pk_bf16_f32 v47, v48, v49
	v_cvt_pk_bf16_f32 v48, v42, v43
	v_cvt_pk_bf16_f32 v49, v44, v45
	s_mov_b32 s19, 0x240000
	v_cvt_pk_bf16_f32 v110, v110, v111
	v_cvt_pk_bf16_f32 v111, v112, v113
	v_cvt_pk_bf16_f32 v112, v106, v107
	v_or_b32_e32 v106, 16, v146
	global_store_dwordx4 v[66:67], v[46:49], off offset:256
	s_mov_b64 s[20:21], 0x240000
	v_ashrrev_i32_e32 v107, 31, v106
	v_add_co_u32_e32 v48, vcc, s19, v150
	v_cvt_pk_bf16_f32 v94, v94, v95
	v_cvt_pk_bf16_f32 v95, v96, v97
	v_cvt_pk_bf16_f32 v96, v90, v91
	v_or_b32_e32 v90, 32, v146
	v_lshl_add_u64 v[46:47], v[150:151], 0, s[20:21]
	v_addc_co_u32_e32 v49, vcc, 0, v151, vcc
	v_cvt_pk_bf16_f32 v30, v30, v31
	v_cvt_pk_bf16_f32 v31, v32, v33
	v_cvt_pk_bf16_f32 v32, v26, v27
	v_cvt_pk_bf16_f32 v33, v28, v29
	s_mov_b32 s19, 0x280000
	v_lshlrev_b64 v[106:107], 14, v[106:107]
	v_ashrrev_i32_e32 v91, 31, v90
	v_cvt_pk_bf16_f32 v78, v78, v79
	v_cvt_pk_bf16_f32 v79, v80, v81
	v_cvt_pk_bf16_f32 v80, v74, v75
	v_or_b32_e32 v74, 48, v146
	global_store_dwordx4 v[46:47], v[30:33], off offset:256
	s_mov_b64 s[20:21], 0x280000
	v_cvt_pk_bf16_f32 v113, v108, v109
	v_add_co_u32_e32 v32, vcc, s19, v150
	v_lshl_add_u64 v[106:107], s[62:63], 0, v[106:107]
	v_lshlrev_b64 v[90:91], 14, v[90:91]
	v_ashrrev_i32_e32 v75, 31, v74
	v_lshl_add_u64 v[30:31], v[150:151], 0, s[20:21]
	v_addc_co_u32_e32 v33, vcc, 0, v151, vcc
	v_cvt_pk_bf16_f32 v14, v14, v15
	v_cvt_pk_bf16_f32 v15, v16, v17
	v_cvt_pk_bf16_f32 v16, v10, v11
	v_cvt_pk_bf16_f32 v17, v12, v13
	s_mov_b32 s19, 0x2c0000
	global_store_dwordx4 v[150:151], v[110:113], off offset:256
	v_cvt_pk_bf16_f32 v97, v92, v93
	v_lshl_add_u64 v[90:91], s[62:63], 0, v[90:91]
	v_lshl_add_u64 v[110:111], v[106:107], 0, v[148:149]
	v_lshlrev_b64 v[74:75], 14, v[74:75]
	global_store_dwordx4 v[30:31], v[14:17], off offset:256
	global_store_dwordx4 v[110:111], v[94:97], off offset:256
	v_cvt_pk_bf16_f32 v81, v76, v77
	v_add_co_u32_e32 v16, vcc, s19, v150
	v_lshl_add_u64 v[94:95], v[90:91], 0, v[148:149]
	v_lshl_add_u64 v[74:75], s[62:63], 0, v[74:75]
	s_mov_b64 s[20:21], 0x2c0000
	v_addc_co_u32_e32 v17, vcc, 0, v151, vcc
	v_cvt_pk_bf16_f32 v126, v126, v127
	v_cvt_pk_bf16_f32 v127, v128, v129
	v_cvt_pk_bf16_f32 v128, v122, v123
	v_cvt_pk_bf16_f32 v129, v124, v125
	v_cvt_pk_bf16_f32 v106, v118, v119
	v_cvt_pk_bf16_f32 v107, v120, v121
	v_cvt_pk_bf16_f32 v108, v114, v115
	v_cvt_pk_bf16_f32 v109, v116, v117
	v_cvt_pk_bf16_f32 v90, v102, v103
	v_cvt_pk_bf16_f32 v91, v104, v105
	v_cvt_pk_bf16_f32 v92, v98, v99
	v_cvt_pk_bf16_f32 v93, v100, v101
	global_store_dwordx4 v[94:95], v[78:81], off offset:256
	v_cvt_pk_bf16_f32 v76, v82, v83
	v_cvt_pk_bf16_f32 v77, v84, v85
	v_lshl_add_u64 v[78:79], v[74:75], 0, v[148:149]
	v_cvt_pk_bf16_f32 v74, v86, v87
	v_cvt_pk_bf16_f32 v75, v88, v89
	v_cvt_pk_bf16_f32 v73, v68, v69
	v_cvt_pk_bf16_f32 v65, v60, v61
	v_cvt_pk_bf16_f32 v42, v54, v55
	v_cvt_pk_bf16_f32 v43, v56, v57
	v_cvt_pk_bf16_f32 v44, v50, v51
	v_cvt_pk_bf16_f32 v45, v52, v53
	v_cvt_pk_bf16_f32 v26, v38, v39
	v_cvt_pk_bf16_f32 v27, v40, v41
	v_cvt_pk_bf16_f32 v28, v34, v35
	v_cvt_pk_bf16_f32 v29, v36, v37
	v_lshl_add_u64 v[14:15], v[150:151], 0, s[20:21]
	v_cvt_pk_bf16_f32 v10, v22, v23
	v_cvt_pk_bf16_f32 v11, v24, v25
	v_cvt_pk_bf16_f32 v12, v18, v19
	v_cvt_pk_bf16_f32 v13, v20, v21
	v_cvt_pk_bf16_f32 v6, v6, v7
	v_cvt_pk_bf16_f32 v7, v8, v9
	v_cvt_pk_bf16_f32 v8, v2, v3
	v_cvt_pk_bf16_f32 v9, v4, v5
	s_and_b64 vcc, exec, s[0:1]
	s_mov_b32 s45, s18
	s_mov_b32 s46, s30
	s_mov_b64 s[22:23], s[80:81]
	s_mov_b64 s[20:21], s[38:39]
	s_mov_b32 s64, 0x800000
	s_movk_i32 s65, 0x1fff
	v_readlane_b32 s49, v254, 41
	v_readlane_b32 s50, v254, 42
	v_readlane_b32 s51, v254, 43
	v_readlane_b32 s52, v254, 44
	v_readlane_b32 s53, v254, 45
	v_readlane_b32 s54, v254, 46
	v_readlane_b32 s55, v254, 47
	v_readlane_b32 s56, v254, 48
	v_readlane_b32 s57, v254, 49
	v_readlane_b32 s58, v254, 50
	v_readlane_b32 s59, v254, 51
	v_readlane_b32 s60, v254, 52
	v_readlane_b32 s61, v254, 53
	global_store_dwordx4 v[150:151], v[126:129], off
	global_store_dwordx4 v[110:111], v[106:109], off
	global_store_dwordx4 v[94:95], v[90:93], off
	global_store_dwordx4 v[78:79], v[74:77], off
	global_store_dwordx4 v[78:79], v[70:73], off offset:256
	global_store_dwordx4 v[58:59], v[62:65], off
	global_store_dwordx4 v[48:49], v[42:45], off
	global_store_dwordx4 v[32:33], v[26:29], off
	global_store_dwordx4 v[16:17], v[10:13], off
	global_store_dwordx4 v[14:15], v[6:9], off offset:256
	s_cbranch_vccz .LBB0_366
	s_waitcnt vmcnt(0)
	v_readlane_b32 s44, v255, 30
	s_mov_b32 s66, s90
	s_cmpk_gt_u32 s25, 0xff
	v_readlane_b32 s45, v255, 31
	v_readlane_b32 s42, v255, 32
	s_cbranch_scc1 .LBB0_377
	s_barrier

.LBB0_386:
	s_add_u32 s20, s18, 0xfffe0080
	s_addc_u32 s21, s19, -1
	s_add_i32 s50, 0, 0x10000
	s_cmp_eq_u32 s49, 4
	s_cselect_b32 s23, s44, s21
	s_cselect_b32 s22, s45, s20
	s_cselect_b32 s21, s39, s48
	s_cselect_b32 s20, s46, s47
	v_lshl_add_u64 v[178:179], s[18:19], 0, v[146:147]
	s_add_i32 m0, s90, 0xc000
	ds_read_b128 v[162:165], v156
	ds_read_b128 v[166:169], v156 offset:1024
	ds_read_b128 v[170:173], v156 offset:2048
	ds_read_b128 v[174:177], v156 offset:3072
	ds_read_b128 v[192:195], v156 offset:4096
	ds_read_b128 v[196:199], v156 offset:5120
	ds_read_b128 v[200:203], v156 offset:6144
	ds_read_b128 v[204:207], v156 offset:7168
	global_load_lds_dwordx4 v[178:179], off
	s_add_i32 m0, s90, 0xe000
	v_lshl_add_u64 v[178:179], s[18:19], 0, v[148:149]
	global_load_lds_dwordx4 v[178:179], off
	s_barrier
	s_waitcnt lgkmcnt(0)
	v_mfma_f32_16x16x32_bf16 v[126:129], v[130:133], v[162:165], v[126:129]
	v_mfma_f32_16x16x32_bf16 v[122:125], v[150:153], v[162:165], v[122:125]
	v_mfma_f32_16x16x32_bf16 v[118:121], v[130:133], v[170:173], v[118:121]
	v_mfma_f32_16x16x32_bf16 v[110:113], v[150:153], v[170:173], v[110:113]
	v_mfma_f32_16x16x32_bf16 v[102:105], v[130:133], v[192:195], v[102:105]
	v_mfma_f32_16x16x32_bf16 v[94:97], v[150:153], v[192:195], v[94:97]
	v_mfma_f32_16x16x32_bf16 v[86:89], v[130:133], v[200:203], v[86:89]
	v_mfma_f32_16x16x32_bf16 v[78:81], v[150:153], v[200:203], v[78:81]
	v_mfma_f32_16x16x32_bf16 v[126:129], v[134:137], v[166:169], v[126:129]
	v_mfma_f32_16x16x32_bf16 v[122:125], v[158:161], v[166:169], v[122:125]
	v_mfma_f32_16x16x32_bf16 v[118:121], v[134:137], v[174:177], v[118:121]
	v_mfma_f32_16x16x32_bf16 v[110:113], v[158:161], v[174:177], v[110:113]
	v_mfma_f32_16x16x32_bf16 v[102:105], v[134:137], v[196:199], v[102:105]
	v_mfma_f32_16x16x32_bf16 v[94:97], v[158:161], v[196:199], v[94:97]
	v_mfma_f32_16x16x32_bf16 v[86:89], v[134:137], v[204:207], v[86:89]
	v_mfma_f32_16x16x32_bf16 v[78:81], v[158:161], v[204:207], v[78:81]
	s_barrier
	s_add_i32 s52, 0, 0x14000
	s_add_i32 s50, s50, s36
	v_add_u32_e32 v157, s52, v154
	v_lshl_add_u64 v[178:179], s[20:21], 0, v[142:143]
	s_mov_b32 m0, s50
	ds_read_b128 v[208:211], v157
	ds_read_b128 v[224:227], v157 offset:1024
	ds_read_b128 v[228:231], v157 offset:2048
	ds_read_b128 v[232:235], v157 offset:3072
	global_load_lds_dwordx4 v[178:179], off
	s_add_i32 m0, s50, 0x2000
	v_lshl_add_u64 v[212:213], s[20:21], 0, v[138:139]
	global_load_lds_dwordx4 v[212:213], off
	s_mov_b32 m0, s90
	v_lshl_add_u64 v[236:237], s[22:23], 0, v[144:145]
	s_waitcnt lgkmcnt(0)
	s_barrier
	v_mfma_f32_16x16x32_bf16 v[114:117], v[208:211], v[162:165], v[114:117]
	v_mfma_f32_16x16x32_bf16 v[106:109], v[228:231], v[162:165], v[106:109]
	v_mfma_f32_16x16x32_bf16 v[98:101], v[208:211], v[170:173], v[98:101]
	v_mfma_f32_16x16x32_bf16 v[90:93], v[228:231], v[170:173], v[90:93]
	v_mfma_f32_16x16x32_bf16 v[82:85], v[208:211], v[192:195], v[82:85]
	v_mfma_f32_16x16x32_bf16 v[74:77], v[228:231], v[192:195], v[74:77]
	v_mfma_f32_16x16x32_bf16 v[70:73], v[208:211], v[200:203], v[70:73]
	v_mfma_f32_16x16x32_bf16 v[66:69], v[228:231], v[200:203], v[66:69]
	v_mfma_f32_16x16x32_bf16 v[114:117], v[224:227], v[166:169], v[114:117]
	v_mfma_f32_16x16x32_bf16 v[106:109], v[232:235], v[166:169], v[106:109]
	v_mfma_f32_16x16x32_bf16 v[98:101], v[224:227], v[174:177], v[98:101]
	v_mfma_f32_16x16x32_bf16 v[90:93], v[232:235], v[174:177], v[90:93]
	v_mfma_f32_16x16x32_bf16 v[82:85], v[224:227], v[196:199], v[82:85]
	v_mfma_f32_16x16x32_bf16 v[74:77], v[232:235], v[196:199], v[74:77]
	v_mfma_f32_16x16x32_bf16 v[70:73], v[224:227], v[204:207], v[70:73]
	v_mfma_f32_16x16x32_bf16 v[66:69], v[232:235], v[204:207], v[66:69]
	s_barrier
	ds_read_b128 v[162:165], v156 offset:16384
	ds_read_b128 v[166:169], v156 offset:17408
	ds_read_b128 v[170:173], v156 offset:18432
	ds_read_b128 v[174:177], v156 offset:19456
	ds_read_b128 v[192:195], v156 offset:20480
	ds_read_b128 v[196:199], v156 offset:21504
	ds_read_b128 v[200:203], v156 offset:22528
	ds_read_b128 v[204:207], v156 offset:23552
	global_load_lds_dwordx4 v[236:237], off
	s_mov_b32 m0, s91
	v_lshl_add_u64 v[238:239], s[22:23], 0, v[140:141]
	global_load_lds_dwordx4 v[238:239], off
	s_waitcnt vmcnt(10)
	s_waitcnt lgkmcnt(0)
	s_barrier
	v_mfma_f32_16x16x32_bf16 v[62:65], v[130:133], v[162:165], v[62:65]
	v_mfma_f32_16x16x32_bf16 v[58:61], v[150:153], v[162:165], v[58:61]
	v_mfma_f32_16x16x32_bf16 v[54:57], v[130:133], v[170:173], v[54:57]
	v_mfma_f32_16x16x32_bf16 v[46:49], v[150:153], v[170:173], v[46:49]
	v_mfma_f32_16x16x32_bf16 v[38:41], v[130:133], v[192:195], v[38:41]
	v_mfma_f32_16x16x32_bf16 v[30:33], v[150:153], v[192:195], v[30:33]
	v_mfma_f32_16x16x32_bf16 v[22:25], v[130:133], v[200:203], v[22:25]
	v_mfma_f32_16x16x32_bf16 v[14:17], v[150:153], v[200:203], v[14:17]
	v_mfma_f32_16x16x32_bf16 v[62:65], v[134:137], v[166:169], v[62:65]
	v_mfma_f32_16x16x32_bf16 v[58:61], v[158:161], v[166:169], v[58:61]
	v_mfma_f32_16x16x32_bf16 v[54:57], v[134:137], v[174:177], v[54:57]
	v_mfma_f32_16x16x32_bf16 v[46:49], v[158:161], v[174:177], v[46:49]
	v_mfma_f32_16x16x32_bf16 v[38:41], v[134:137], v[196:199], v[38:41]
	v_mfma_f32_16x16x32_bf16 v[30:33], v[158:161], v[196:199], v[30:33]
	v_mfma_f32_16x16x32_bf16 v[22:25], v[134:137], v[204:207], v[22:25]
	v_mfma_f32_16x16x32_bf16 v[14:17], v[158:161], v[204:207], v[14:17]
	s_barrier
	s_add_u32 s50, s20, 0x20000
	s_addc_u32 s51, s21, 0
	s_add_i32 s52, s52, s36
	s_mov_b32 m0, s52
	v_lshl_add_u64 v[130:131], s[50:51], 0, v[142:143]
	global_load_lds_dwordx4 v[130:131], off
	s_add_i32 m0, s52, 0x2000
	v_lshl_add_u64 v[130:131], s[50:51], 0, v[138:139]
	global_load_lds_dwordx4 v[130:131], off
	v_add_u32_e32 v157, 0x18000, v154
	ds_read_b128 v[130:133], v157
	ds_read_b128 v[134:137], v157 offset:1024
	ds_read_b128 v[150:153], v157 offset:2048
	ds_read_b128 v[158:161], v157 offset:3072
	s_add_i32 s50, 0, 0x18000
	s_waitcnt vmcnt(6)
	s_barrier
	v_mfma_f32_16x16x32_bf16 v[50:53], v[208:211], v[162:165], v[50:53]
	v_mfma_f32_16x16x32_bf16 v[42:45], v[228:231], v[162:165], v[42:45]
	v_mfma_f32_16x16x32_bf16 v[34:37], v[208:211], v[170:173], v[34:37]
	v_mfma_f32_16x16x32_bf16 v[26:29], v[228:231], v[170:173], v[26:29]
	v_mfma_f32_16x16x32_bf16 v[18:21], v[208:211], v[192:195], v[18:21]
	v_mfma_f32_16x16x32_bf16 v[10:13], v[228:231], v[192:195], v[10:13]
	v_mfma_f32_16x16x32_bf16 v[6:9], v[208:211], v[200:203], v[6:9]
	v_mfma_f32_16x16x32_bf16 v[2:5], v[228:231], v[200:203], v[2:5]
	v_mfma_f32_16x16x32_bf16 v[50:53], v[224:227], v[166:169], v[50:53]
	v_mfma_f32_16x16x32_bf16 v[42:45], v[232:235], v[166:169], v[42:45]
	v_mfma_f32_16x16x32_bf16 v[34:37], v[224:227], v[174:177], v[34:37]
	v_mfma_f32_16x16x32_bf16 v[26:29], v[232:235], v[174:177], v[26:29]
	v_mfma_f32_16x16x32_bf16 v[18:21], v[224:227], v[196:199], v[18:21]
	v_mfma_f32_16x16x32_bf16 v[10:13], v[232:235], v[196:199], v[10:13]
	v_mfma_f32_16x16x32_bf16 v[6:9], v[224:227], v[204:207], v[6:9]
	v_mfma_f32_16x16x32_bf16 v[2:5], v[232:235], v[204:207], v[2:5]
	s_barrier
	s_add_u32 s22, s22, 0x20000
	s_addc_u32 s23, s23, 0
	s_mov_b32 m0, s42
	v_lshl_add_u64 v[208:209], s[22:23], 0, v[144:145]
	ds_read_b128 v[162:165], v156 offset:32768
	ds_read_b128 v[166:169], v156 offset:33792
	ds_read_b128 v[170:173], v156 offset:34816
	ds_read_b128 v[174:177], v156 offset:35840
	ds_read_b128 v[192:195], v156 offset:36864
	ds_read_b128 v[196:199], v156 offset:37888
	ds_read_b128 v[200:203], v156 offset:38912
	ds_read_b128 v[204:207], v156 offset:39936
	global_load_lds_dwordx4 v[208:209], off
	s_mov_b32 m0, s43
	v_lshl_add_u64 v[208:209], s[22:23], 0, v[140:141]
	global_load_lds_dwordx4 v[208:209], off
	s_barrier
	s_waitcnt lgkmcnt(0)
	v_mfma_f32_16x16x32_bf16 v[126:129], v[130:133], v[162:165], v[126:129]
	v_mfma_f32_16x16x32_bf16 v[122:125], v[150:153], v[162:165], v[122:125]
	v_mfma_f32_16x16x32_bf16 v[118:121], v[130:133], v[170:173], v[118:121]
	v_mfma_f32_16x16x32_bf16 v[110:113], v[150:153], v[170:173], v[110:113]
	v_mfma_f32_16x16x32_bf16 v[102:105], v[130:133], v[192:195], v[102:105]
	v_mfma_f32_16x16x32_bf16 v[94:97], v[150:153], v[192:195], v[94:97]
	v_mfma_f32_16x16x32_bf16 v[86:89], v[130:133], v[200:203], v[86:89]
	v_mfma_f32_16x16x32_bf16 v[78:81], v[150:153], v[200:203], v[78:81]
	v_mfma_f32_16x16x32_bf16 v[126:129], v[134:137], v[166:169], v[126:129]
	v_mfma_f32_16x16x32_bf16 v[122:125], v[158:161], v[166:169], v[122:125]
	v_mfma_f32_16x16x32_bf16 v[118:121], v[134:137], v[174:177], v[118:121]
	v_mfma_f32_16x16x32_bf16 v[110:113], v[158:161], v[174:177], v[110:113]
	v_mfma_f32_16x16x32_bf16 v[102:105], v[134:137], v[196:199], v[102:105]
	v_mfma_f32_16x16x32_bf16 v[94:97], v[158:161], v[196:199], v[94:97]
	v_mfma_f32_16x16x32_bf16 v[86:89], v[134:137], v[204:207], v[86:89]
	v_mfma_f32_16x16x32_bf16 v[78:81], v[158:161], v[204:207], v[78:81]
	s_barrier
	s_add_i32 s22, 0, 0x1c000
	s_add_i32 s23, s50, s36
	v_add_u32_e32 v157, s22, v154
	v_lshl_add_u64 v[178:179], v[178:179], 0, s[78:79]
	s_mov_b32 m0, s23
	ds_read_b128 v[208:211], v157
	ds_read_b128 v[224:227], v157 offset:1024
	ds_read_b128 v[228:231], v157 offset:2048
	ds_read_b128 v[232:235], v157 offset:3072
	global_load_lds_dwordx4 v[178:179], off
	s_add_i32 m0, s23, 0x2000
	v_lshl_add_u64 v[178:179], v[212:213], 0, s[78:79]
	global_load_lds_dwordx4 v[178:179], off
	s_mov_b32 m0, s25
	v_lshl_add_u64 v[178:179], v[236:237], 0, s[78:79]
	s_waitcnt lgkmcnt(0)
	s_barrier
	v_mfma_f32_16x16x32_bf16 v[114:117], v[208:211], v[162:165], v[114:117]
	v_mfma_f32_16x16x32_bf16 v[106:109], v[228:231], v[162:165], v[106:109]
	v_mfma_f32_16x16x32_bf16 v[98:101], v[208:211], v[170:173], v[98:101]
	v_mfma_f32_16x16x32_bf16 v[90:93], v[228:231], v[170:173], v[90:93]
	v_mfma_f32_16x16x32_bf16 v[82:85], v[208:211], v[192:195], v[82:85]
	v_mfma_f32_16x16x32_bf16 v[74:77], v[228:231], v[192:195], v[74:77]
	v_mfma_f32_16x16x32_bf16 v[70:73], v[208:211], v[200:203], v[70:73]
	v_mfma_f32_16x16x32_bf16 v[66:69], v[228:231], v[200:203], v[66:69]
	v_mfma_f32_16x16x32_bf16 v[114:117], v[224:227], v[166:169], v[114:117]
	v_mfma_f32_16x16x32_bf16 v[106:109], v[232:235], v[166:169], v[106:109]
	v_mfma_f32_16x16x32_bf16 v[98:101], v[224:227], v[174:177], v[98:101]
	v_mfma_f32_16x16x32_bf16 v[90:93], v[232:235], v[174:177], v[90:93]
	v_mfma_f32_16x16x32_bf16 v[82:85], v[224:227], v[196:199], v[82:85]
	v_mfma_f32_16x16x32_bf16 v[74:77], v[232:235], v[196:199], v[74:77]
	v_mfma_f32_16x16x32_bf16 v[70:73], v[224:227], v[204:207], v[70:73]
	v_mfma_f32_16x16x32_bf16 v[66:69], v[232:235], v[204:207], v[66:69]
	s_barrier
	ds_read_b128 v[162:165], v156 offset:49152
	ds_read_b128 v[166:169], v156 offset:50176
	ds_read_b128 v[170:173], v156 offset:51200
	ds_read_b128 v[174:177], v156 offset:52224
	ds_read_b128 v[192:195], v156 offset:53248
	ds_read_b128 v[196:199], v156 offset:54272
	ds_read_b128 v[200:203], v156 offset:55296
	ds_read_b128 v[204:207], v156 offset:56320
	global_load_lds_dwordx4 v[178:179], off
	s_mov_b32 m0, s26
	v_lshl_add_u64 v[178:179], v[238:239], 0, s[78:79]
	global_load_lds_dwordx4 v[178:179], off
	s_waitcnt vmcnt(10)
	s_waitcnt lgkmcnt(0)
	s_barrier
	v_mfma_f32_16x16x32_bf16 v[62:65], v[130:133], v[162:165], v[62:65]
	v_mfma_f32_16x16x32_bf16 v[58:61], v[150:153], v[162:165], v[58:61]
	v_mfma_f32_16x16x32_bf16 v[54:57], v[130:133], v[170:173], v[54:57]
	v_mfma_f32_16x16x32_bf16 v[46:49], v[150:153], v[170:173], v[46:49]
	v_mfma_f32_16x16x32_bf16 v[38:41], v[130:133], v[192:195], v[38:41]
	v_mfma_f32_16x16x32_bf16 v[30:33], v[150:153], v[192:195], v[30:33]
	v_mfma_f32_16x16x32_bf16 v[22:25], v[130:133], v[200:203], v[22:25]
	v_mfma_f32_16x16x32_bf16 v[14:17], v[150:153], v[200:203], v[14:17]
	v_mfma_f32_16x16x32_bf16 v[62:65], v[134:137], v[166:169], v[62:65]
	v_mfma_f32_16x16x32_bf16 v[58:61], v[158:161], v[166:169], v[58:61]
	v_mfma_f32_16x16x32_bf16 v[54:57], v[134:137], v[174:177], v[54:57]
	v_mfma_f32_16x16x32_bf16 v[46:49], v[158:161], v[174:177], v[46:49]
	v_mfma_f32_16x16x32_bf16 v[38:41], v[134:137], v[196:199], v[38:41]
	v_mfma_f32_16x16x32_bf16 v[30:33], v[158:161], v[196:199], v[30:33]
	v_mfma_f32_16x16x32_bf16 v[22:25], v[134:137], v[204:207], v[22:25]
	v_mfma_f32_16x16x32_bf16 v[14:17], v[158:161], v[204:207], v[14:17]
	s_barrier
	s_add_u32 s20, s20, 0x20080
	s_addc_u32 s21, s21, 0
	s_add_i32 s22, s22, s36
	s_mov_b32 m0, s22
	v_lshl_add_u64 v[130:131], s[20:21], 0, v[142:143]
	global_load_lds_dwordx4 v[130:131], off
	s_add_i32 m0, s22, 0x2000
	v_lshl_add_u64 v[130:131], s[20:21], 0, v[138:139]
	global_load_lds_dwordx4 v[130:131], off
	v_add_u32_e32 v157, 0x10000, v154
	ds_read_b128 v[130:133], v157
	ds_read_b128 v[134:137], v157 offset:1024
	ds_read_b128 v[150:153], v157 offset:2048
	ds_read_b128 v[158:161], v157 offset:3072
	s_add_i32 s49, s49, 2
	s_add_u32 s18, s18, 0x100
	s_addc_u32 s19, s19, 0
	s_add_u32 s47, s47, 0x100
	s_addc_u32 s48, s48, 0
	s_cmp_gt_u32 s49, 5
	s_waitcnt vmcnt(6)
	s_barrier
	v_mfma_f32_16x16x32_bf16 v[50:53], v[208:211], v[162:165], v[50:53]
	v_mfma_f32_16x16x32_bf16 v[42:45], v[228:231], v[162:165], v[42:45]
	v_mfma_f32_16x16x32_bf16 v[34:37], v[208:211], v[170:173], v[34:37]
	v_mfma_f32_16x16x32_bf16 v[26:29], v[228:231], v[170:173], v[26:29]
	v_mfma_f32_16x16x32_bf16 v[18:21], v[208:211], v[192:195], v[18:21]
	v_mfma_f32_16x16x32_bf16 v[10:13], v[228:231], v[192:195], v[10:13]
	v_mfma_f32_16x16x32_bf16 v[6:9], v[208:211], v[200:203], v[6:9]
	v_mfma_f32_16x16x32_bf16 v[2:5], v[228:231], v[200:203], v[2:5]
	v_mfma_f32_16x16x32_bf16 v[50:53], v[224:227], v[166:169], v[50:53]
	v_mfma_f32_16x16x32_bf16 v[42:45], v[232:235], v[166:169], v[42:45]
	v_mfma_f32_16x16x32_bf16 v[34:37], v[224:227], v[174:177], v[34:37]
	v_mfma_f32_16x16x32_bf16 v[26:29], v[232:235], v[174:177], v[26:29]
	v_mfma_f32_16x16x32_bf16 v[18:21], v[224:227], v[196:199], v[18:21]
	v_mfma_f32_16x16x32_bf16 v[10:13], v[232:235], v[196:199], v[10:13]
	v_mfma_f32_16x16x32_bf16 v[6:9], v[224:227], v[204:207], v[6:9]
	v_mfma_f32_16x16x32_bf16 v[2:5], v[232:235], v[204:207], v[2:5]
	s_barrier
	s_cbranch_scc0 .LBB0_386
	s_waitcnt lgkmcnt(0)
	v_lshl_add_u32 v164, s29, 8, v1
	v_lshl_or_b32 v150, s28, 8, v155
	s_mov_b64 s[18:19], -1
	s_cmp_lt_i32 s28, 8
	v_or_b32_e32 v163, 16, v164
	v_or_b32_e32 v162, 32, v164
	v_or_b32_e32 v161, 48, v164
	v_add_u32_e32 v160, 0x80, v164
	v_add_u32_e32 v159, 0x90, v164
	v_add_u32_e32 v158, 0xa0, v164
	v_add_u32_e32 v157, 0xb0, v164
	s_cbranch_scc1 .LBB0_389
	v_lshlrev_b32_e32 v130, 7, v164
	v_readlane_b32 s4, v255, 4
	v_and_b32_e32 v132, 0x3e780, v130
	v_mov_b32_e32 v133, v0
	v_readlane_b32 s5, v255, 5
	v_readlane_b32 s6, v255, 6
	v_readlane_b32 s7, v255, 7
	v_lshlrev_b32_e32 v130, 1, v150
	v_lshl_add_u64 v[134:135], s[4:5], 0, v[132:133]
	v_and_b32_e32 v130, 0x70, v130
	v_mov_b32_e32 v131, v0
	v_lshl_add_u64 v[132:133], s[6:7], 0, v[132:133]
	v_lshl_add_u64 v[152:153], v[132:133], 0, v[130:131]
	v_lshl_add_u64 v[136:137], v[134:135], 0, v[130:131]
	global_load_dwordx4 v[170:173], v[152:153], off
	global_load_dwordx4 v[166:169], v[136:137], off
	v_readlane_b32 s8, v255, 8
	v_readlane_b32 s9, v255, 9
	v_mov_b32_e32 v151, v0
	v_lshlrev_b64 v[134:135], 1, v[150:151]
	v_mov_b64_e32 v[132:133], s[8:9]
	v_mad_i64_i32 v[174:175], s[18:19], v164, s24, v[132:133]
	v_lshl_add_u64 v[174:175], v[174:175], 0, v[134:135]
	v_readlane_b32 s10, v255, 10
	v_readlane_b32 s11, v255, 11
	s_waitcnt vmcnt(0)
	v_pk_mul_f32 v[172:173], v[172:173], s[86:87] op_sel_hi:[1,0]
	v_pk_mul_f32 v[170:171], v[170:171], s[86:87] op_sel_hi:[1,0]
	v_pk_mul_f32 v[168:169], v[168:169], s[86:87] op_sel_hi:[1,0]
	v_pk_mul_f32 v[166:167], v[166:167], s[86:87] op_sel_hi:[1,0]
	v_pk_mul_f32 v[176:177], v[124:125], v[172:173]
	v_pk_mul_f32 v[178:179], v[122:123], v[170:171]
	v_pk_mul_f32 v[172:173], v[128:129], v[172:173]
	v_pk_mul_f32 v[170:171], v[126:127], v[170:171]
	v_pk_fma_f32 v[176:177], v[128:129], v[168:169], v[176:177] neg_lo:[0,0,1] neg_hi:[0,0,1]
	v_pk_fma_f32 v[178:179], v[126:127], v[166:167], v[178:179] neg_lo:[0,0,1] neg_hi:[0,0,1]
	v_pk_fma_f32 v[172:173], v[124:125], v[168:169], v[172:173]
	v_pk_fma_f32 v[168:169], v[122:123], v[166:167], v[170:171]
	v_cvt_pk_bf16_f32 v166, v178, v179
	v_cvt_pk_bf16_f32 v167, v176, v177
	v_cvt_pk_bf16_f32 v168, v168, v169
	v_cvt_pk_bf16_f32 v169, v172, v173
	global_store_dwordx4 v[174:175], v[166:169], off
	global_load_dwordx4 v[166:169], v[136:137], off
	s_nop 0
	global_load_dwordx4 v[170:173], v[152:153], off
	v_lshlrev_b32_e32 v136, 7, v163
	v_mov_b32_e32 v137, v0
	v_and_b32_e32 v136, 0x3ef80, v136
	v_lshl_add_u64 v[152:153], s[4:5], 0, v[136:137]
	v_lshl_add_u64 v[136:137], s[6:7], 0, v[136:137]
	v_lshl_add_u64 v[136:137], v[136:137], 0, v[130:131]
	v_lshl_add_u64 v[152:153], v[152:153], 0, v[130:131]
	s_waitcnt vmcnt(0)
	v_pk_mul_f32 v[168:169], v[168:169], s[86:87] op_sel_hi:[1,0]
	v_pk_mul_f32 v[172:173], v[172:173], s[86:87] op_sel_hi:[1,0]
	v_pk_mul_f32 v[170:171], v[170:171], s[86:87] op_sel_hi:[1,0]
	v_pk_mul_f32 v[166:167], v[166:167], s[86:87] op_sel_hi:[1,0]
	v_pk_mul_f32 v[176:177], v[108:109], v[172:173]
	v_pk_mul_f32 v[178:179], v[106:107], v[170:171]
	v_pk_mul_f32 v[172:173], v[116:117], v[172:173]
	v_pk_mul_f32 v[170:171], v[114:115], v[170:171]
	v_pk_fma_f32 v[176:177], v[116:117], v[168:169], v[176:177] neg_lo:[0,0,1] neg_hi:[0,0,1]
	v_pk_fma_f32 v[178:179], v[114:115], v[166:167], v[178:179] neg_lo:[0,0,1] neg_hi:[0,0,1]
	v_pk_fma_f32 v[172:173], v[108:109], v[168:169], v[172:173]
	v_pk_fma_f32 v[168:169], v[106:107], v[166:167], v[170:171]
	v_cvt_pk_bf16_f32 v166, v178, v179
	v_cvt_pk_bf16_f32 v167, v176, v177
	v_cvt_pk_bf16_f32 v168, v168, v169
	v_cvt_pk_bf16_f32 v169, v172, v173
	global_store_dwordx4 v[174:175], v[166:169], off offset:256
	global_load_dwordx4 v[170:173], v[136:137], off
	v_mad_i64_i32 v[174:175], s[18:19], v163, s24, v[132:133]
	global_load_dwordx4 v[166:169], v[152:153], off
	v_lshl_add_u64 v[174:175], v[174:175], 0, v[134:135]
	s_waitcnt vmcnt(0)
	v_pk_mul_f32 v[172:173], v[172:173], s[86:87] op_sel_hi:[1,0]
	v_pk_mul_f32 v[170:171], v[170:171], s[86:87] op_sel_hi:[1,0]
	v_pk_mul_f32 v[176:177], v[112:113], v[172:173]
	v_pk_mul_f32 v[168:169], v[168:169], s[86:87] op_sel_hi:[1,0]
	v_pk_mul_f32 v[166:167], v[166:167], s[86:87] op_sel_hi:[1,0]
	v_pk_mul_f32 v[178:179], v[110:111], v[170:171]
	v_pk_mul_f32 v[172:173], v[120:121], v[172:173]
	v_pk_mul_f32 v[170:171], v[118:119], v[170:171]
	v_pk_fma_f32 v[176:177], v[120:121], v[168:169], v[176:177] neg_lo:[0,0,1] neg_hi:[0,0,1]
	v_pk_fma_f32 v[178:179], v[118:119], v[166:167], v[178:179] neg_lo:[0,0,1] neg_hi:[0,0,1]
	v_pk_fma_f32 v[172:173], v[112:113], v[168:169], v[172:173]
	v_pk_fma_f32 v[168:169], v[110:111], v[166:167], v[170:171]
	v_cvt_pk_bf16_f32 v166, v178, v179
	v_cvt_pk_bf16_f32 v167, v176, v177
	v_cvt_pk_bf16_f32 v168, v168, v169
	v_cvt_pk_bf16_f32 v169, v172, v173
	global_store_dwordx4 v[174:175], v[166:169], off
	global_load_dwordx4 v[166:169], v[152:153], off
	s_nop 0
	global_load_dwordx4 v[170:173], v[136:137], off
	v_lshlrev_b32_e32 v136, 7, v162
	v_mov_b32_e32 v137, v0
	v_and_b32_e32 v136, 0x3f780, v136
	v_lshl_add_u64 v[152:153], s[4:5], 0, v[136:137]
	v_lshl_add_u64 v[136:137], s[6:7], 0, v[136:137]
	v_lshl_add_u64 v[136:137], v[136:137], 0, v[130:131]
	v_lshl_add_u64 v[152:153], v[152:153], 0, v[130:131]
	s_waitcnt vmcnt(0)
	v_pk_mul_f32 v[168:169], v[168:169], s[86:87] op_sel_hi:[1,0]
	v_pk_mul_f32 v[172:173], v[172:173], s[86:87] op_sel_hi:[1,0]
	v_pk_mul_f32 v[170:171], v[170:171], s[86:87] op_sel_hi:[1,0]
	v_pk_mul_f32 v[166:167], v[166:167], s[86:87] op_sel_hi:[1,0]
	v_pk_mul_f32 v[176:177], v[92:93], v[172:173]
	v_pk_mul_f32 v[178:179], v[90:91], v[170:171]
	v_pk_mul_f32 v[172:173], v[100:101], v[172:173]
	v_pk_mul_f32 v[170:171], v[98:99], v[170:171]
	v_pk_fma_f32 v[176:177], v[100:101], v[168:169], v[176:177] neg_lo:[0,0,1] neg_hi:[0,0,1]
	v_pk_fma_f32 v[178:179], v[98:99], v[166:167], v[178:179] neg_lo:[0,0,1] neg_hi:[0,0,1]
	v_pk_fma_f32 v[172:173], v[92:93], v[168:169], v[172:173]
	v_pk_fma_f32 v[168:169], v[90:91], v[166:167], v[170:171]
	v_cvt_pk_bf16_f32 v166, v178, v179
	v_cvt_pk_bf16_f32 v167, v176, v177
	v_cvt_pk_bf16_f32 v168, v168, v169
	v_cvt_pk_bf16_f32 v169, v172, v173
	global_store_dwordx4 v[174:175], v[166:169], off offset:256
	global_load_dwordx4 v[170:173], v[136:137], off
	v_mad_i64_i32 v[174:175], s[18:19], v162, s24, v[132:133]
	global_load_dwordx4 v[166:169], v[152:153], off
	v_lshl_add_u64 v[174:175], v[174:175], 0, v[134:135]
	s_waitcnt vmcnt(0)
	v_pk_mul_f32 v[172:173], v[172:173], s[86:87] op_sel_hi:[1,0]
	v_pk_mul_f32 v[170:171], v[170:171], s[86:87] op_sel_hi:[1,0]
	v_pk_mul_f32 v[176:177], v[96:97], v[172:173]
	v_pk_mul_f32 v[168:169], v[168:169], s[86:87] op_sel_hi:[1,0]
	v_pk_mul_f32 v[166:167], v[166:167], s[86:87] op_sel_hi:[1,0]
	v_pk_mul_f32 v[178:179], v[94:95], v[170:171]
	v_pk_mul_f32 v[172:173], v[104:105], v[172:173]
	v_pk_mul_f32 v[170:171], v[102:103], v[170:171]
	v_pk_fma_f32 v[176:177], v[104:105], v[168:169], v[176:177] neg_lo:[0,0,1] neg_hi:[0,0,1]
	v_pk_fma_f32 v[178:179], v[102:103], v[166:167], v[178:179] neg_lo:[0,0,1] neg_hi:[0,0,1]
	v_pk_fma_f32 v[172:173], v[96:97], v[168:169], v[172:173]
	v_pk_fma_f32 v[168:169], v[94:95], v[166:167], v[170:171]
	v_cvt_pk_bf16_f32 v166, v178, v179
	v_cvt_pk_bf16_f32 v167, v176, v177
	v_cvt_pk_bf16_f32 v168, v168, v169
	v_cvt_pk_bf16_f32 v169, v172, v173
	global_store_dwordx4 v[174:175], v[166:169], off
	global_load_dwordx4 v[166:169], v[152:153], off
	s_nop 0
	global_load_dwordx4 v[170:173], v[136:137], off
	v_lshlrev_b32_e32 v136, 7, v161
	v_mov_b32_e32 v137, v0
	v_and_b32_e32 v136, 0x3ff80, v136
	v_lshl_add_u64 v[152:153], s[4:5], 0, v[136:137]
	v_lshl_add_u64 v[136:137], s[6:7], 0, v[136:137]
	v_lshl_add_u64 v[136:137], v[136:137], 0, v[130:131]
	v_lshl_add_u64 v[152:153], v[152:153], 0, v[130:131]
	s_waitcnt vmcnt(0)
	v_pk_mul_f32 v[168:169], v[168:169], s[86:87] op_sel_hi:[1,0]
	v_pk_mul_f32 v[172:173], v[172:173], s[86:87] op_sel_hi:[1,0]
	v_pk_mul_f32 v[170:171], v[170:171], s[86:87] op_sel_hi:[1,0]
	v_pk_mul_f32 v[166:167], v[166:167], s[86:87] op_sel_hi:[1,0]
	v_pk_mul_f32 v[176:177], v[76:77], v[172:173]
	v_pk_mul_f32 v[178:179], v[74:75], v[170:171]
	v_pk_mul_f32 v[172:173], v[84:85], v[172:173]
	v_pk_mul_f32 v[170:171], v[82:83], v[170:171]
	v_pk_fma_f32 v[176:177], v[84:85], v[168:169], v[176:177] neg_lo:[0,0,1] neg_hi:[0,0,1]
	v_pk_fma_f32 v[178:179], v[82:83], v[166:167], v[178:179] neg_lo:[0,0,1] neg_hi:[0,0,1]
	v_pk_fma_f32 v[172:173], v[76:77], v[168:169], v[172:173]
	v_pk_fma_f32 v[168:169], v[74:75], v[166:167], v[170:171]
	v_cvt_pk_bf16_f32 v166, v178, v179
	v_cvt_pk_bf16_f32 v167, v176, v177
	v_cvt_pk_bf16_f32 v168, v168, v169
	v_cvt_pk_bf16_f32 v169, v172, v173
	global_store_dwordx4 v[174:175], v[166:169], off offset:256
	global_load_dwordx4 v[170:173], v[136:137], off
	v_mad_i64_i32 v[174:175], s[18:19], v161, s24, v[132:133]
	global_load_dwordx4 v[166:169], v[152:153], off
	v_lshl_add_u64 v[174:175], v[174:175], 0, v[134:135]
	s_waitcnt vmcnt(0)
	v_pk_mul_f32 v[172:173], v[172:173], s[86:87] op_sel_hi:[1,0]
	v_pk_mul_f32 v[170:171], v[170:171], s[86:87] op_sel_hi:[1,0]
	v_pk_mul_f32 v[176:177], v[80:81], v[172:173]
	v_pk_mul_f32 v[168:169], v[168:169], s[86:87] op_sel_hi:[1,0]
	v_pk_mul_f32 v[166:167], v[166:167], s[86:87] op_sel_hi:[1,0]
	v_pk_mul_f32 v[178:179], v[78:79], v[170:171]
	v_pk_mul_f32 v[172:173], v[88:89], v[172:173]
	v_pk_mul_f32 v[170:171], v[86:87], v[170:171]
	v_pk_fma_f32 v[176:177], v[88:89], v[168:169], v[176:177] neg_lo:[0,0,1] neg_hi:[0,0,1]
	v_pk_fma_f32 v[178:179], v[86:87], v[166:167], v[178:179] neg_lo:[0,0,1] neg_hi:[0,0,1]
	v_pk_fma_f32 v[172:173], v[80:81], v[168:169], v[172:173]
	v_pk_fma_f32 v[168:169], v[78:79], v[166:167], v[170:171]
	v_cvt_pk_bf16_f32 v166, v178, v179
	v_cvt_pk_bf16_f32 v167, v176, v177
	v_cvt_pk_bf16_f32 v168, v168, v169
	v_cvt_pk_bf16_f32 v169, v172, v173
	global_store_dwordx4 v[174:175], v[166:169], off
	global_load_dwordx4 v[166:169], v[152:153], off
	s_nop 0
	global_load_dwordx4 v[170:173], v[136:137], off
	v_lshlrev_b32_e32 v136, 7, v160
	v_mov_b32_e32 v137, v0
	v_and_b32_e32 v136, 0x3e780, v136
	v_lshl_add_u64 v[152:153], s[4:5], 0, v[136:137]
	v_lshl_add_u64 v[136:137], s[6:7], 0, v[136:137]
	v_lshl_add_u64 v[136:137], v[136:137], 0, v[130:131]
	v_lshl_add_u64 v[152:153], v[152:153], 0, v[130:131]
	s_waitcnt vmcnt(0)
	v_pk_mul_f32 v[168:169], v[168:169], s[86:87] op_sel_hi:[1,0]
	v_pk_mul_f32 v[172:173], v[172:173], s[86:87] op_sel_hi:[1,0]
	v_pk_mul_f32 v[170:171], v[170:171], s[86:87] op_sel_hi:[1,0]
	v_pk_mul_f32 v[166:167], v[166:167], s[86:87] op_sel_hi:[1,0]
	v_pk_mul_f32 v[176:177], v[68:69], v[172:173]
	v_pk_mul_f32 v[178:179], v[66:67], v[170:171]
	v_pk_mul_f32 v[172:173], v[72:73], v[172:173]
	v_pk_mul_f32 v[170:171], v[70:71], v[170:171]
	v_pk_fma_f32 v[176:177], v[72:73], v[168:169], v[176:177] neg_lo:[0,0,1] neg_hi:[0,0,1]
	v_pk_fma_f32 v[178:179], v[70:71], v[166:167], v[178:179] neg_lo:[0,0,1] neg_hi:[0,0,1]
	v_pk_fma_f32 v[172:173], v[68:69], v[168:169], v[172:173]
	v_pk_fma_f32 v[168:169], v[66:67], v[166:167], v[170:171]
	v_cvt_pk_bf16_f32 v166, v178, v179
	v_cvt_pk_bf16_f32 v167, v176, v177
	v_cvt_pk_bf16_f32 v168, v168, v169
	v_cvt_pk_bf16_f32 v169, v172, v173
	global_store_dwordx4 v[174:175], v[166:169], off offset:256
	global_load_dwordx4 v[170:173], v[136:137], off
	v_mad_i64_i32 v[174:175], s[18:19], v160, s24, v[132:133]
	global_load_dwordx4 v[166:169], v[152:153], off
	v_lshl_add_u64 v[174:175], v[174:175], 0, v[134:135]
	s_waitcnt vmcnt(0)
	v_pk_mul_f32 v[172:173], v[172:173], s[86:87] op_sel_hi:[1,0]
	v_pk_mul_f32 v[170:171], v[170:171], s[86:87] op_sel_hi:[1,0]
	v_pk_mul_f32 v[176:177], v[60:61], v[172:173]
	v_pk_mul_f32 v[168:169], v[168:169], s[86:87] op_sel_hi:[1,0]
	v_pk_mul_f32 v[166:167], v[166:167], s[86:87] op_sel_hi:[1,0]
	v_pk_mul_f32 v[178:179], v[58:59], v[170:171]
	v_pk_mul_f32 v[172:173], v[64:65], v[172:173]
	v_pk_mul_f32 v[170:171], v[62:63], v[170:171]
	v_pk_fma_f32 v[176:177], v[64:65], v[168:169], v[176:177] neg_lo:[0,0,1] neg_hi:[0,0,1]
	v_pk_fma_f32 v[178:179], v[62:63], v[166:167], v[178:179] neg_lo:[0,0,1] neg_hi:[0,0,1]
	v_pk_fma_f32 v[172:173], v[60:61], v[168:169], v[172:173]
	v_pk_fma_f32 v[168:169], v[58:59], v[166:167], v[170:171]
	v_cvt_pk_bf16_f32 v166, v178, v179
	v_cvt_pk_bf16_f32 v167, v176, v177
	v_cvt_pk_bf16_f32 v168, v168, v169
	v_cvt_pk_bf16_f32 v169, v172, v173
	global_store_dwordx4 v[174:175], v[166:169], off
	global_load_dwordx4 v[166:169], v[152:153], off
	s_nop 0
	global_load_dwordx4 v[170:173], v[136:137], off
	v_lshlrev_b32_e32 v136, 7, v159
	v_mov_b32_e32 v137, v0
	v_and_b32_e32 v136, 0x3ef80, v136
	v_lshl_add_u64 v[152:153], s[4:5], 0, v[136:137]
	v_lshl_add_u64 v[136:137], s[6:7], 0, v[136:137]
	v_lshl_add_u64 v[136:137], v[136:137], 0, v[130:131]
	v_lshl_add_u64 v[152:153], v[152:153], 0, v[130:131]
	s_waitcnt vmcnt(0)
	v_pk_mul_f32 v[168:169], v[168:169], s[86:87] op_sel_hi:[1,0]
	v_pk_mul_f32 v[172:173], v[172:173], s[86:87] op_sel_hi:[1,0]
	v_pk_mul_f32 v[170:171], v[170:171], s[86:87] op_sel_hi:[1,0]
	v_pk_mul_f32 v[166:167], v[166:167], s[86:87] op_sel_hi:[1,0]
	v_pk_mul_f32 v[176:177], v[44:45], v[172:173]
	v_pk_mul_f32 v[178:179], v[42:43], v[170:171]
	v_pk_mul_f32 v[172:173], v[52:53], v[172:173]
	v_pk_mul_f32 v[170:171], v[50:51], v[170:171]
	v_pk_fma_f32 v[176:177], v[52:53], v[168:169], v[176:177] neg_lo:[0,0,1] neg_hi:[0,0,1]
	v_pk_fma_f32 v[178:179], v[50:51], v[166:167], v[178:179] neg_lo:[0,0,1] neg_hi:[0,0,1]
	v_pk_fma_f32 v[172:173], v[44:45], v[168:169], v[172:173]
	v_pk_fma_f32 v[168:169], v[42:43], v[166:167], v[170:171]
	v_cvt_pk_bf16_f32 v166, v178, v179
	v_cvt_pk_bf16_f32 v167, v176, v177
	v_cvt_pk_bf16_f32 v168, v168, v169
	v_cvt_pk_bf16_f32 v169, v172, v173
	global_store_dwordx4 v[174:175], v[166:169], off offset:256
	global_load_dwordx4 v[170:173], v[136:137], off
	v_mad_i64_i32 v[174:175], s[18:19], v159, s24, v[132:133]
	global_load_dwordx4 v[166:169], v[152:153], off
	v_lshl_add_u64 v[174:175], v[174:175], 0, v[134:135]
	s_waitcnt vmcnt(0)
	v_pk_mul_f32 v[172:173], v[172:173], s[86:87] op_sel_hi:[1,0]
	v_pk_mul_f32 v[170:171], v[170:171], s[86:87] op_sel_hi:[1,0]
	v_pk_mul_f32 v[176:177], v[48:49], v[172:173]
	v_pk_mul_f32 v[168:169], v[168:169], s[86:87] op_sel_hi:[1,0]
	v_pk_mul_f32 v[166:167], v[166:167], s[86:87] op_sel_hi:[1,0]
	v_pk_mul_f32 v[178:179], v[46:47], v[170:171]
	v_pk_mul_f32 v[172:173], v[56:57], v[172:173]
	v_pk_mul_f32 v[170:171], v[54:55], v[170:171]
	v_pk_fma_f32 v[176:177], v[56:57], v[168:169], v[176:177] neg_lo:[0,0,1] neg_hi:[0,0,1]
	v_pk_fma_f32 v[178:179], v[54:55], v[166:167], v[178:179] neg_lo:[0,0,1] neg_hi:[0,0,1]
	v_pk_fma_f32 v[172:173], v[48:49], v[168:169], v[172:173]
	v_pk_fma_f32 v[168:169], v[46:47], v[166:167], v[170:171]
	v_cvt_pk_bf16_f32 v166, v178, v179
	v_cvt_pk_bf16_f32 v167, v176, v177
	v_cvt_pk_bf16_f32 v168, v168, v169
	v_cvt_pk_bf16_f32 v169, v172, v173
	global_store_dwordx4 v[174:175], v[166:169], off
	global_load_dwordx4 v[166:169], v[152:153], off
	s_nop 0
	global_load_dwordx4 v[170:173], v[136:137], off
	v_lshlrev_b32_e32 v136, 7, v158
	v_mov_b32_e32 v137, v0
	v_and_b32_e32 v136, 0x3f780, v136
	v_lshl_add_u64 v[152:153], s[4:5], 0, v[136:137]
	v_lshl_add_u64 v[136:137], s[6:7], 0, v[136:137]
	v_lshl_add_u64 v[136:137], v[136:137], 0, v[130:131]
	v_lshl_add_u64 v[152:153], v[152:153], 0, v[130:131]
	s_waitcnt vmcnt(0)
	v_pk_mul_f32 v[168:169], v[168:169], s[86:87] op_sel_hi:[1,0]
	v_pk_mul_f32 v[172:173], v[172:173], s[86:87] op_sel_hi:[1,0]
	v_pk_mul_f32 v[170:171], v[170:171], s[86:87] op_sel_hi:[1,0]
	v_pk_mul_f32 v[166:167], v[166:167], s[86:87] op_sel_hi:[1,0]
	v_pk_mul_f32 v[176:177], v[28:29], v[172:173]
	v_pk_mul_f32 v[178:179], v[26:27], v[170:171]
	v_pk_mul_f32 v[172:173], v[36:37], v[172:173]
	v_pk_mul_f32 v[170:171], v[34:35], v[170:171]
	v_pk_fma_f32 v[176:177], v[36:37], v[168:169], v[176:177] neg_lo:[0,0,1] neg_hi:[0,0,1]
	v_pk_fma_f32 v[178:179], v[34:35], v[166:167], v[178:179] neg_lo:[0,0,1] neg_hi:[0,0,1]
	v_pk_fma_f32 v[172:173], v[28:29], v[168:169], v[172:173]
	v_pk_fma_f32 v[168:169], v[26:27], v[166:167], v[170:171]
	v_cvt_pk_bf16_f32 v166, v178, v179
	v_cvt_pk_bf16_f32 v167, v176, v177
	v_cvt_pk_bf16_f32 v168, v168, v169
	v_cvt_pk_bf16_f32 v169, v172, v173
	global_store_dwordx4 v[174:175], v[166:169], off offset:256
	global_load_dwordx4 v[170:173], v[136:137], off
	v_mad_i64_i32 v[174:175], s[18:19], v158, s24, v[132:133]
	global_load_dwordx4 v[166:169], v[152:153], off
	v_lshl_add_u64 v[174:175], v[174:175], 0, v[134:135]
	s_waitcnt vmcnt(0)
	v_pk_mul_f32 v[172:173], v[172:173], s[86:87] op_sel_hi:[1,0]
	v_pk_mul_f32 v[170:171], v[170:171], s[86:87] op_sel_hi:[1,0]
	v_pk_mul_f32 v[176:177], v[32:33], v[172:173]
	v_pk_mul_f32 v[168:169], v[168:169], s[86:87] op_sel_hi:[1,0]
	v_pk_mul_f32 v[166:167], v[166:167], s[86:87] op_sel_hi:[1,0]
	v_pk_mul_f32 v[178:179], v[30:31], v[170:171]
	v_pk_mul_f32 v[172:173], v[40:41], v[172:173]
	v_pk_mul_f32 v[170:171], v[38:39], v[170:171]
	v_pk_fma_f32 v[176:177], v[40:41], v[168:169], v[176:177] neg_lo:[0,0,1] neg_hi:[0,0,1]
	v_pk_fma_f32 v[178:179], v[38:39], v[166:167], v[178:179] neg_lo:[0,0,1] neg_hi:[0,0,1]
	v_pk_fma_f32 v[172:173], v[32:33], v[168:169], v[172:173]
	v_pk_fma_f32 v[168:169], v[30:31], v[166:167], v[170:171]
	v_cvt_pk_bf16_f32 v166, v178, v179
	v_cvt_pk_bf16_f32 v167, v176, v177
	v_cvt_pk_bf16_f32 v168, v168, v169
	v_cvt_pk_bf16_f32 v169, v172, v173
	global_store_dwordx4 v[174:175], v[166:169], off
	global_load_dwordx4 v[166:169], v[152:153], off
	s_nop 0
	global_load_dwordx4 v[170:173], v[136:137], off
	v_lshlrev_b32_e32 v136, 7, v157
	v_mov_b32_e32 v137, v0
	v_and_b32_e32 v136, 0x3ff80, v136
	v_lshl_add_u64 v[152:153], s[4:5], 0, v[136:137]
	v_lshl_add_u64 v[176:177], v[152:153], 0, v[130:131]
	v_lshl_add_u64 v[136:137], s[6:7], 0, v[136:137]
	v_lshl_add_u64 v[136:137], v[136:137], 0, v[130:131]
	v_mad_i64_i32 v[130:131], s[18:19], v157, s24, v[132:133]
	s_mov_b64 s[18:19], 0
	s_waitcnt vmcnt(0)
	v_pk_mul_f32 v[152:153], v[168:169], s[86:87] op_sel_hi:[1,0]
	v_pk_mul_f32 v[168:169], v[172:173], s[86:87] op_sel_hi:[1,0]
	v_pk_mul_f32 v[170:171], v[170:171], s[86:87] op_sel_hi:[1,0]
	v_pk_mul_f32 v[166:167], v[166:167], s[86:87] op_sel_hi:[1,0]
	v_pk_mul_f32 v[172:173], v[12:13], v[168:169]
	v_pk_mul_f32 v[178:179], v[10:11], v[170:171]
	v_pk_mul_f32 v[168:169], v[20:21], v[168:169]
	v_pk_mul_f32 v[170:171], v[18:19], v[170:171]
	v_pk_fma_f32 v[172:173], v[20:21], v[152:153], v[172:173] neg_lo:[0,0,1] neg_hi:[0,0,1]
	v_pk_fma_f32 v[178:179], v[18:19], v[166:167], v[178:179] neg_lo:[0,0,1] neg_hi:[0,0,1]
	v_pk_fma_f32 v[152:153], v[12:13], v[152:153], v[168:169]
	v_pk_fma_f32 v[168:169], v[10:11], v[166:167], v[170:171]
	v_cvt_pk_bf16_f32 v166, v178, v179
	v_cvt_pk_bf16_f32 v167, v172, v173
	v_cvt_pk_bf16_f32 v168, v168, v169
	v_cvt_pk_bf16_f32 v169, v152, v153
	global_store_dwordx4 v[174:175], v[166:169], off offset:256
	global_load_dwordx4 v[166:169], v[176:177], off
	v_lshl_add_u64 v[152:153], v[130:131], 0, v[134:135]
	global_load_dwordx4 v[170:173], v[136:137], off
	s_waitcnt vmcnt(0)
	v_pk_mul_f32 v[132:133], v[166:167], s[86:87] op_sel_hi:[1,0]
	v_pk_mul_f32 v[130:131], v[168:169], s[86:87] op_sel_hi:[1,0]
	v_pk_mul_f32 v[134:135], v[172:173], s[86:87] op_sel_hi:[1,0]
	v_pk_mul_f32 v[166:167], v[170:171], s[86:87] op_sel_hi:[1,0]
	v_pk_mul_f32 v[168:169], v[16:17], v[134:135]
	v_pk_mul_f32 v[170:171], v[14:15], v[166:167]
	v_pk_mul_f32 v[134:135], v[24:25], v[134:135]
	v_pk_mul_f32 v[166:167], v[22:23], v[166:167]
	v_pk_fma_f32 v[168:169], v[24:25], v[130:131], v[168:169] neg_lo:[0,0,1] neg_hi:[0,0,1]
	v_pk_fma_f32 v[170:171], v[22:23], v[132:133], v[170:171] neg_lo:[0,0,1] neg_hi:[0,0,1]
	v_pk_fma_f32 v[134:135], v[16:17], v[130:131], v[134:135]
	v_pk_fma_f32 v[132:133], v[14:15], v[132:133], v[166:167]
	v_cvt_pk_bf16_f32 v130, v170, v171
	v_cvt_pk_bf16_f32 v131, v168, v169
	v_cvt_pk_bf16_f32 v132, v132, v133
	v_cvt_pk_bf16_f32 v133, v134, v135
	global_store_dwordx4 v[152:153], v[130:133], off
	global_load_dwordx4 v[130:133], v[176:177], off
	s_nop 0
	global_load_dwordx4 v[134:137], v[136:137], off
	s_waitcnt vmcnt(0)
	v_pk_mul_f32 v[166:167], v[132:133], s[86:87] op_sel_hi:[1,0]
	v_pk_mul_f32 v[168:169], v[130:131], s[86:87] op_sel_hi:[1,0]
	v_pk_mul_f32 v[130:131], v[136:137], s[86:87] op_sel_hi:[1,0]
	v_pk_mul_f32 v[132:133], v[134:135], s[86:87] op_sel_hi:[1,0]
	v_pk_mul_f32 v[134:135], v[4:5], v[130:131]
	v_pk_mul_f32 v[136:137], v[2:3], v[132:133]
	v_pk_mul_f32 v[170:171], v[8:9], v[130:131]
	v_pk_mul_f32 v[172:173], v[6:7], v[132:133]
	v_pk_fma_f32 v[132:133], v[8:9], v[166:167], v[134:135] neg_lo:[0,0,1] neg_hi:[0,0,1]
	v_pk_fma_f32 v[130:131], v[6:7], v[168:169], v[136:137] neg_lo:[0,0,1] neg_hi:[0,0,1]
	v_pk_fma_f32 v[136:137], v[4:5], v[166:167], v[170:171]
	v_pk_fma_f32 v[134:135], v[2:3], v[168:169], v[172:173]

.LBB0_526:
	s_add_u32 s20, s18, 0xfff80080
	s_addc_u32 s21, s19, -1
	s_add_i32 s56, 0, 0x10000
	s_cmp_eq_u32 s55, 28
	s_cselect_b32 s23, s39, s21
	s_cselect_b32 s22, s51, s20
	s_cselect_b32 s21, s31, s54
	s_cselect_b32 s20, s52, s53
	v_lshl_add_u64 v[152:153], s[18:19], 0, v[140:141]
	s_add_i32 m0, s29, 0xc000
	ds_read_b128 v[164:167], v154
	ds_read_b128 v[168:171], v154 offset:1024
	ds_read_b128 v[172:175], v154 offset:2048
	ds_read_b128 v[176:179], v154 offset:3072
	ds_read_b128 v[192:195], v154 offset:4096
	ds_read_b128 v[196:199], v154 offset:5120
	ds_read_b128 v[200:203], v154 offset:6144
	ds_read_b128 v[204:207], v154 offset:7168
	global_load_lds_dwordx4 v[152:153], off
	s_add_i32 m0, s29, 0xe000
	v_lshl_add_u64 v[152:153], s[18:19], 0, v[142:143]
	global_load_lds_dwordx4 v[152:153], off
	s_barrier
	s_waitcnt lgkmcnt(0)
	v_mfma_f32_16x16x32_bf16 v[126:129], v[144:147], v[164:167], v[126:129]
	v_mfma_f32_16x16x32_bf16 v[122:125], v[156:159], v[164:167], v[122:125]
	v_mfma_f32_16x16x32_bf16 v[118:121], v[144:147], v[172:175], v[118:121]
	v_mfma_f32_16x16x32_bf16 v[114:117], v[156:159], v[172:175], v[114:117]
	v_mfma_f32_16x16x32_bf16 v[102:105], v[144:147], v[192:195], v[102:105]
	v_mfma_f32_16x16x32_bf16 v[98:101], v[156:159], v[192:195], v[98:101]
	v_mfma_f32_16x16x32_bf16 v[86:89], v[144:147], v[200:203], v[86:89]
	v_mfma_f32_16x16x32_bf16 v[82:85], v[156:159], v[200:203], v[82:85]
	v_mfma_f32_16x16x32_bf16 v[126:129], v[148:151], v[168:171], v[126:129]
	v_mfma_f32_16x16x32_bf16 v[122:125], v[160:163], v[168:171], v[122:125]
	v_mfma_f32_16x16x32_bf16 v[118:121], v[148:151], v[176:179], v[118:121]
	v_mfma_f32_16x16x32_bf16 v[114:117], v[160:163], v[176:179], v[114:117]
	v_mfma_f32_16x16x32_bf16 v[102:105], v[148:151], v[196:199], v[102:105]
	v_mfma_f32_16x16x32_bf16 v[98:101], v[160:163], v[196:199], v[98:101]
	v_mfma_f32_16x16x32_bf16 v[86:89], v[148:151], v[204:207], v[86:89]
	v_mfma_f32_16x16x32_bf16 v[82:85], v[160:163], v[204:207], v[82:85]
	s_barrier
	s_add_i32 s58, 0, 0x14000
	v_add_u32_e32 v152, s58, v139
	s_add_i32 s56, s56, s28
	ds_read_b128 v[208:211], v152
	ds_read_b128 v[224:227], v152 offset:1024
	ds_read_b128 v[228:231], v152 offset:2048
	ds_read_b128 v[232:235], v152 offset:3072
	v_lshl_add_u64 v[152:153], s[20:21], 0, v[134:135]
	s_mov_b32 m0, s56
	v_lshl_add_u64 v[212:213], s[20:21], 0, v[130:131]
	global_load_lds_dwordx4 v[152:153], off
	s_add_i32 m0, s56, 0x2000
	s_nop 0
	global_load_lds_dwordx4 v[212:213], off
	s_mov_b32 m0, s29
	v_lshl_add_u64 v[236:237], s[22:23], 0, v[136:137]
	s_waitcnt lgkmcnt(0)
	s_barrier
	v_mfma_f32_16x16x32_bf16 v[110:113], v[208:211], v[164:167], v[110:113]
	v_mfma_f32_16x16x32_bf16 v[106:109], v[228:231], v[164:167], v[106:109]
	v_mfma_f32_16x16x32_bf16 v[94:97], v[208:211], v[172:175], v[94:97]
	v_mfma_f32_16x16x32_bf16 v[90:93], v[228:231], v[172:175], v[90:93]
	v_mfma_f32_16x16x32_bf16 v[78:81], v[208:211], v[192:195], v[78:81]
	v_mfma_f32_16x16x32_bf16 v[74:77], v[228:231], v[192:195], v[74:77]
	v_mfma_f32_16x16x32_bf16 v[70:73], v[208:211], v[200:203], v[70:73]
	v_mfma_f32_16x16x32_bf16 v[66:69], v[228:231], v[200:203], v[66:69]
	v_mfma_f32_16x16x32_bf16 v[110:113], v[224:227], v[168:171], v[110:113]
	v_mfma_f32_16x16x32_bf16 v[106:109], v[232:235], v[168:171], v[106:109]
	v_mfma_f32_16x16x32_bf16 v[94:97], v[224:227], v[176:179], v[94:97]
	v_mfma_f32_16x16x32_bf16 v[90:93], v[232:235], v[176:179], v[90:93]
	v_mfma_f32_16x16x32_bf16 v[78:81], v[224:227], v[196:199], v[78:81]
	v_mfma_f32_16x16x32_bf16 v[74:77], v[232:235], v[196:199], v[74:77]
	v_mfma_f32_16x16x32_bf16 v[70:73], v[224:227], v[204:207], v[70:73]
	v_mfma_f32_16x16x32_bf16 v[66:69], v[232:235], v[204:207], v[66:69]
	s_barrier
	ds_read_b128 v[164:167], v154 offset:16384
	ds_read_b128 v[168:171], v154 offset:17408
	ds_read_b128 v[172:175], v154 offset:18432
	ds_read_b128 v[176:179], v154 offset:19456
	ds_read_b128 v[192:195], v154 offset:20480
	ds_read_b128 v[196:199], v154 offset:21504
	ds_read_b128 v[200:203], v154 offset:22528
	ds_read_b128 v[204:207], v154 offset:23552
	global_load_lds_dwordx4 v[236:237], off
	s_mov_b32 m0, s44
	v_lshl_add_u64 v[238:239], s[22:23], 0, v[132:133]
	global_load_lds_dwordx4 v[238:239], off
	s_waitcnt vmcnt(10)
	s_waitcnt lgkmcnt(0)
	s_barrier
	v_mfma_f32_16x16x32_bf16 v[62:65], v[144:147], v[164:167], v[62:65]
	v_mfma_f32_16x16x32_bf16 v[58:61], v[156:159], v[164:167], v[58:61]
	v_mfma_f32_16x16x32_bf16 v[54:57], v[144:147], v[172:175], v[54:57]
	v_mfma_f32_16x16x32_bf16 v[50:53], v[156:159], v[172:175], v[50:53]
	v_mfma_f32_16x16x32_bf16 v[38:41], v[144:147], v[192:195], v[38:41]
	v_mfma_f32_16x16x32_bf16 v[34:37], v[156:159], v[192:195], v[34:37]
	v_mfma_f32_16x16x32_bf16 v[22:25], v[144:147], v[200:203], v[22:25]
	v_mfma_f32_16x16x32_bf16 v[18:21], v[156:159], v[200:203], v[18:21]
	v_mfma_f32_16x16x32_bf16 v[62:65], v[148:151], v[168:171], v[62:65]
	v_mfma_f32_16x16x32_bf16 v[58:61], v[160:163], v[168:171], v[58:61]
	v_mfma_f32_16x16x32_bf16 v[54:57], v[148:151], v[176:179], v[54:57]
	v_mfma_f32_16x16x32_bf16 v[50:53], v[160:163], v[176:179], v[50:53]
	v_mfma_f32_16x16x32_bf16 v[38:41], v[148:151], v[196:199], v[38:41]
	v_mfma_f32_16x16x32_bf16 v[34:37], v[160:163], v[196:199], v[34:37]
	v_mfma_f32_16x16x32_bf16 v[22:25], v[148:151], v[204:207], v[22:25]
	v_mfma_f32_16x16x32_bf16 v[18:21], v[160:163], v[204:207], v[18:21]
	s_barrier
	s_add_u32 s56, s20, 0x80000
	s_addc_u32 s57, s21, 0
	s_add_i32 s58, s58, s28
	s_mov_b32 m0, s58
	v_lshl_add_u64 v[144:145], s[56:57], 0, v[134:135]
	global_load_lds_dwordx4 v[144:145], off
	s_add_i32 m0, s58, 0x2000
	v_lshl_add_u64 v[144:145], s[56:57], 0, v[130:131]
	global_load_lds_dwordx4 v[144:145], off
	v_add_u32_e32 v155, 0x18000, v139
	ds_read_b128 v[144:147], v155
	ds_read_b128 v[148:151], v155 offset:1024
	ds_read_b128 v[156:159], v155 offset:2048
	ds_read_b128 v[160:163], v155 offset:3072
	s_add_i32 s56, 0, 0x18000
	s_waitcnt vmcnt(6)
	s_barrier
	v_mfma_f32_16x16x32_bf16 v[46:49], v[208:211], v[164:167], v[46:49]
	v_mfma_f32_16x16x32_bf16 v[42:45], v[228:231], v[164:167], v[42:45]
	v_mfma_f32_16x16x32_bf16 v[30:33], v[208:211], v[172:175], v[30:33]
	v_mfma_f32_16x16x32_bf16 v[26:29], v[228:231], v[172:175], v[26:29]
	v_mfma_f32_16x16x32_bf16 v[14:17], v[208:211], v[192:195], v[14:17]
	v_mfma_f32_16x16x32_bf16 v[10:13], v[228:231], v[192:195], v[10:13]
	v_mfma_f32_16x16x32_bf16 v[6:9], v[208:211], v[200:203], v[6:9]
	v_mfma_f32_16x16x32_bf16 v[2:5], v[228:231], v[200:203], v[2:5]
	v_mfma_f32_16x16x32_bf16 v[46:49], v[224:227], v[168:171], v[46:49]
	v_mfma_f32_16x16x32_bf16 v[42:45], v[232:235], v[168:171], v[42:45]
	v_mfma_f32_16x16x32_bf16 v[30:33], v[224:227], v[176:179], v[30:33]
	v_mfma_f32_16x16x32_bf16 v[26:29], v[232:235], v[176:179], v[26:29]
	v_mfma_f32_16x16x32_bf16 v[14:17], v[224:227], v[196:199], v[14:17]
	v_mfma_f32_16x16x32_bf16 v[10:13], v[232:235], v[196:199], v[10:13]
	v_mfma_f32_16x16x32_bf16 v[6:9], v[224:227], v[204:207], v[6:9]
	v_mfma_f32_16x16x32_bf16 v[2:5], v[232:235], v[204:207], v[2:5]
	s_barrier
	s_add_u32 s22, s22, 0x80000
	s_addc_u32 s23, s23, 0
	s_mov_b32 m0, s45
	v_lshl_add_u64 v[208:209], s[22:23], 0, v[136:137]
	ds_read_b128 v[164:167], v154 offset:32768
	ds_read_b128 v[168:171], v154 offset:33792
	ds_read_b128 v[172:175], v154 offset:34816
	ds_read_b128 v[176:179], v154 offset:35840
	ds_read_b128 v[192:195], v154 offset:36864
	ds_read_b128 v[196:199], v154 offset:37888
	ds_read_b128 v[200:203], v154 offset:38912
	ds_read_b128 v[204:207], v154 offset:39936
	global_load_lds_dwordx4 v[208:209], off
	s_mov_b32 m0, s46
	v_lshl_add_u64 v[208:209], s[22:23], 0, v[132:133]
	global_load_lds_dwordx4 v[208:209], off
	s_barrier
	s_waitcnt lgkmcnt(0)
	v_mfma_f32_16x16x32_bf16 v[126:129], v[144:147], v[164:167], v[126:129]
	v_mfma_f32_16x16x32_bf16 v[122:125], v[156:159], v[164:167], v[122:125]
	v_mfma_f32_16x16x32_bf16 v[118:121], v[144:147], v[172:175], v[118:121]
	v_mfma_f32_16x16x32_bf16 v[114:117], v[156:159], v[172:175], v[114:117]
	v_mfma_f32_16x16x32_bf16 v[102:105], v[144:147], v[192:195], v[102:105]
	v_mfma_f32_16x16x32_bf16 v[98:101], v[156:159], v[192:195], v[98:101]
	v_mfma_f32_16x16x32_bf16 v[86:89], v[144:147], v[200:203], v[86:89]
	v_mfma_f32_16x16x32_bf16 v[82:85], v[156:159], v[200:203], v[82:85]
	v_mfma_f32_16x16x32_bf16 v[126:129], v[148:151], v[168:171], v[126:129]
	v_mfma_f32_16x16x32_bf16 v[122:125], v[160:163], v[168:171], v[122:125]
	v_mfma_f32_16x16x32_bf16 v[118:121], v[148:151], v[176:179], v[118:121]
	v_mfma_f32_16x16x32_bf16 v[114:117], v[160:163], v[176:179], v[114:117]
	v_mfma_f32_16x16x32_bf16 v[102:105], v[148:151], v[196:199], v[102:105]
	v_mfma_f32_16x16x32_bf16 v[98:101], v[160:163], v[196:199], v[98:101]
	v_mfma_f32_16x16x32_bf16 v[86:89], v[148:151], v[204:207], v[86:89]
	v_mfma_f32_16x16x32_bf16 v[82:85], v[160:163], v[204:207], v[82:85]
	s_barrier
	s_add_i32 s22, 0, 0x1c000
	s_add_i32 s23, s56, s28
	v_add_u32_e32 v155, s22, v139
	v_lshl_add_u64 v[152:153], v[152:153], 0, s[78:79]
	s_mov_b32 m0, s23
	ds_read_b128 v[208:211], v155
	ds_read_b128 v[224:227], v155 offset:1024
	ds_read_b128 v[228:231], v155 offset:2048
	ds_read_b128 v[232:235], v155 offset:3072
	global_load_lds_dwordx4 v[152:153], off
	s_add_i32 m0, s23, 0x2000
	v_lshl_add_u64 v[152:153], v[212:213], 0, s[78:79]
	global_load_lds_dwordx4 v[152:153], off
	s_mov_b32 m0, s47
	v_lshl_add_u64 v[152:153], v[236:237], 0, s[78:79]
	s_waitcnt lgkmcnt(0)
	s_barrier
	v_mfma_f32_16x16x32_bf16 v[110:113], v[208:211], v[164:167], v[110:113]
	v_mfma_f32_16x16x32_bf16 v[106:109], v[228:231], v[164:167], v[106:109]
	v_mfma_f32_16x16x32_bf16 v[94:97], v[208:211], v[172:175], v[94:97]
	v_mfma_f32_16x16x32_bf16 v[90:93], v[228:231], v[172:175], v[90:93]
	v_mfma_f32_16x16x32_bf16 v[78:81], v[208:211], v[192:195], v[78:81]
	v_mfma_f32_16x16x32_bf16 v[74:77], v[228:231], v[192:195], v[74:77]
	v_mfma_f32_16x16x32_bf16 v[70:73], v[208:211], v[200:203], v[70:73]
	v_mfma_f32_16x16x32_bf16 v[66:69], v[228:231], v[200:203], v[66:69]
	v_mfma_f32_16x16x32_bf16 v[110:113], v[224:227], v[168:171], v[110:113]
	v_mfma_f32_16x16x32_bf16 v[106:109], v[232:235], v[168:171], v[106:109]
	v_mfma_f32_16x16x32_bf16 v[94:97], v[224:227], v[176:179], v[94:97]
	v_mfma_f32_16x16x32_bf16 v[90:93], v[232:235], v[176:179], v[90:93]
	v_mfma_f32_16x16x32_bf16 v[78:81], v[224:227], v[196:199], v[78:81]
	v_mfma_f32_16x16x32_bf16 v[74:77], v[232:235], v[196:199], v[74:77]
	v_mfma_f32_16x16x32_bf16 v[70:73], v[224:227], v[204:207], v[70:73]
	v_mfma_f32_16x16x32_bf16 v[66:69], v[232:235], v[204:207], v[66:69]
	s_barrier
	ds_read_b128 v[164:167], v154 offset:49152
	ds_read_b128 v[168:171], v154 offset:50176
	ds_read_b128 v[172:175], v154 offset:51200
	ds_read_b128 v[176:179], v154 offset:52224
	ds_read_b128 v[192:195], v154 offset:53248
	ds_read_b128 v[196:199], v154 offset:54272
	ds_read_b128 v[200:203], v154 offset:55296
	ds_read_b128 v[204:207], v154 offset:56320
	global_load_lds_dwordx4 v[152:153], off
	s_mov_b32 m0, s48
	v_lshl_add_u64 v[152:153], v[238:239], 0, s[78:79]
	global_load_lds_dwordx4 v[152:153], off
	s_waitcnt vmcnt(10)
	s_waitcnt lgkmcnt(0)
	s_barrier
	v_mfma_f32_16x16x32_bf16 v[62:65], v[144:147], v[164:167], v[62:65]
	v_mfma_f32_16x16x32_bf16 v[58:61], v[156:159], v[164:167], v[58:61]
	v_mfma_f32_16x16x32_bf16 v[54:57], v[144:147], v[172:175], v[54:57]
	v_mfma_f32_16x16x32_bf16 v[50:53], v[156:159], v[172:175], v[50:53]
	v_mfma_f32_16x16x32_bf16 v[38:41], v[144:147], v[192:195], v[38:41]
	v_mfma_f32_16x16x32_bf16 v[34:37], v[156:159], v[192:195], v[34:37]
	v_mfma_f32_16x16x32_bf16 v[22:25], v[144:147], v[200:203], v[22:25]
	v_mfma_f32_16x16x32_bf16 v[18:21], v[156:159], v[200:203], v[18:21]
	v_mfma_f32_16x16x32_bf16 v[62:65], v[148:151], v[168:171], v[62:65]
	v_mfma_f32_16x16x32_bf16 v[58:61], v[160:163], v[168:171], v[58:61]
	v_mfma_f32_16x16x32_bf16 v[54:57], v[148:151], v[176:179], v[54:57]
	v_mfma_f32_16x16x32_bf16 v[50:53], v[160:163], v[176:179], v[50:53]
	v_mfma_f32_16x16x32_bf16 v[38:41], v[148:151], v[196:199], v[38:41]
	v_mfma_f32_16x16x32_bf16 v[34:37], v[160:163], v[196:199], v[34:37]
	v_mfma_f32_16x16x32_bf16 v[22:25], v[148:151], v[204:207], v[22:25]
	v_mfma_f32_16x16x32_bf16 v[18:21], v[160:163], v[204:207], v[18:21]
	s_barrier
	s_add_u32 s20, s20, 0x80080
	s_addc_u32 s21, s21, 0
	s_add_i32 s22, s22, s28
	s_mov_b32 m0, s22
	v_lshl_add_u64 v[144:145], s[20:21], 0, v[134:135]
	global_load_lds_dwordx4 v[144:145], off
	s_add_i32 m0, s22, 0x2000
	v_lshl_add_u64 v[144:145], s[20:21], 0, v[130:131]
	global_load_lds_dwordx4 v[144:145], off
	v_add_u32_e32 v152, 0x10000, v139
	ds_read_b128 v[144:147], v152
	ds_read_b128 v[148:151], v152 offset:1024
	ds_read_b128 v[156:159], v152 offset:2048
	ds_read_b128 v[160:163], v152 offset:3072
	s_add_i32 s55, s55, 2
	s_add_u32 s18, s18, 0x100
	s_addc_u32 s19, s19, 0
	s_add_u32 s53, s53, 0x100
	s_addc_u32 s54, s54, 0
	s_cmp_gt_u32 s55, 29
	s_waitcnt vmcnt(6)
	s_barrier
	v_mfma_f32_16x16x32_bf16 v[46:49], v[208:211], v[164:167], v[46:49]
	v_mfma_f32_16x16x32_bf16 v[42:45], v[228:231], v[164:167], v[42:45]
	v_mfma_f32_16x16x32_bf16 v[30:33], v[208:211], v[172:175], v[30:33]
	v_mfma_f32_16x16x32_bf16 v[26:29], v[228:231], v[172:175], v[26:29]
	v_mfma_f32_16x16x32_bf16 v[14:17], v[208:211], v[192:195], v[14:17]
	v_mfma_f32_16x16x32_bf16 v[10:13], v[228:231], v[192:195], v[10:13]
	v_mfma_f32_16x16x32_bf16 v[6:9], v[208:211], v[200:203], v[6:9]
	v_mfma_f32_16x16x32_bf16 v[2:5], v[228:231], v[200:203], v[2:5]
	v_mfma_f32_16x16x32_bf16 v[46:49], v[224:227], v[168:171], v[46:49]
	v_mfma_f32_16x16x32_bf16 v[42:45], v[232:235], v[168:171], v[42:45]
	v_mfma_f32_16x16x32_bf16 v[30:33], v[224:227], v[176:179], v[30:33]
	v_mfma_f32_16x16x32_bf16 v[26:29], v[232:235], v[176:179], v[26:29]
	v_mfma_f32_16x16x32_bf16 v[14:17], v[224:227], v[196:199], v[14:17]
	v_mfma_f32_16x16x32_bf16 v[10:13], v[232:235], v[196:199], v[10:13]
	v_mfma_f32_16x16x32_bf16 v[6:9], v[224:227], v[204:207], v[6:9]
	v_mfma_f32_16x16x32_bf16 v[2:5], v[232:235], v[204:207], v[2:5]
	s_barrier
	s_cbranch_scc0 .LBB0_526
	s_waitcnt lgkmcnt(0)
	v_lshl_add_u32 v152, s36, 8, v1
	v_or_b32_e32 v150, 16, v152
	v_or_b32_e32 v148, 32, v152
	v_or_b32_e32 v146, 48, v152
	s_mov_b64 s[18:19], -1
	s_cmp_lt_i32 s50, 8
	v_ashrrev_i32_e32 v153, 31, v152
	v_lshlrev_b32_e32 v144, 1, v138
	v_ashrrev_i32_e32 v151, 31, v150
	v_ashrrev_i32_e32 v149, 31, v148
	v_ashrrev_i32_e32 v147, 31, v146
	s_cbranch_scc1 .LBB0_529
	s_lshl_b32 s18, s50, 7
	s_add_i32 s36, s18, 0xfffffc00
	v_lshlrev_b64 v[156:157], 12, v[152:153]
	v_lshl_add_u64 v[156:157], s[72:73], 0, v[156:157]
	s_lshl_b64 s[18:19], s[36:37], 1
	v_lshl_add_u64 v[156:157], v[156:157], 0, s[18:19]
	v_mov_b32_e32 v145, v0
	v_lshl_add_u64 v[160:161], v[156:157], 0, v[144:145]
	v_pk_mul_f32 v[158:159], v[128:129], v[112:113]
	v_pk_mul_f32 v[156:157], v[126:127], v[110:111]
	v_pk_mul_f32 v[162:163], v[124:125], v[108:109]
	v_pk_mul_f32 v[164:165], v[122:123], v[106:107]
	v_cvt_pk_bf16_f32 v156, v156, v157
	v_cvt_pk_bf16_f32 v157, v158, v159
	v_cvt_pk_bf16_f32 v158, v164, v165
	v_cvt_pk_bf16_f32 v159, v162, v163
	global_store_dwordx4 v[160:161], v[156:159], off
	v_pk_mul_f32 v[164:165], v[116:117], v[92:93]
	v_pk_mul_f32 v[166:167], v[114:115], v[90:91]
	v_lshlrev_b64 v[156:157], 12, v[150:151]
	v_lshl_add_u64 v[156:157], s[72:73], 0, v[156:157]
	v_lshl_add_u64 v[156:157], v[156:157], 0, s[18:19]
	v_lshl_add_u64 v[162:163], v[156:157], 0, v[144:145]
	v_pk_mul_f32 v[158:159], v[120:121], v[96:97]
	v_pk_mul_f32 v[156:157], v[118:119], v[94:95]
	s_nop 0
	v_cvt_pk_bf16_f32 v156, v156, v157
	v_cvt_pk_bf16_f32 v157, v158, v159
	v_cvt_pk_bf16_f32 v158, v166, v167
	v_cvt_pk_bf16_f32 v159, v164, v165
	global_store_dwordx4 v[162:163], v[156:159], off
	v_pk_mul_f32 v[164:165], v[100:101], v[76:77]
	v_pk_mul_f32 v[166:167], v[98:99], v[74:75]
	v_lshlrev_b64 v[156:157], 12, v[148:149]
	v_lshl_add_u64 v[156:157], s[72:73], 0, v[156:157]
	v_lshl_add_u64 v[156:157], v[156:157], 0, s[18:19]
	v_lshl_add_u64 v[162:163], v[156:157], 0, v[144:145]
	v_pk_mul_f32 v[158:159], v[104:105], v[80:81]
	v_pk_mul_f32 v[156:157], v[102:103], v[78:79]
	s_nop 0
	v_cvt_pk_bf16_f32 v156, v156, v157
	v_cvt_pk_bf16_f32 v157, v158, v159
	v_cvt_pk_bf16_f32 v158, v166, v167
	v_cvt_pk_bf16_f32 v159, v164, v165
	global_store_dwordx4 v[162:163], v[156:159], off
	v_pk_mul_f32 v[164:165], v[84:85], v[68:69]
	v_pk_mul_f32 v[166:167], v[82:83], v[66:67]
	v_lshlrev_b64 v[156:157], 12, v[146:147]
	v_lshl_add_u64 v[156:157], s[72:73], 0, v[156:157]
	v_lshl_add_u64 v[156:157], v[156:157], 0, s[18:19]
	v_lshl_add_u64 v[162:163], v[156:157], 0, v[144:145]
	v_pk_mul_f32 v[158:159], v[88:89], v[72:73]
	v_pk_mul_f32 v[156:157], v[86:87], v[70:71]
	s_mov_b32 s18, 0x80000
	v_cvt_pk_bf16_f32 v156, v156, v157
	v_cvt_pk_bf16_f32 v157, v158, v159
	v_cvt_pk_bf16_f32 v158, v166, v167
	v_cvt_pk_bf16_f32 v159, v164, v165
	global_store_dwordx4 v[162:163], v[156:159], off
	v_pk_mul_f32 v[162:163], v[60:61], v[44:45]
	v_pk_mul_f32 v[164:165], v[58:59], v[42:43]
	v_pk_mul_f32 v[158:159], v[64:65], v[48:49]
	v_pk_mul_f32 v[156:157], v[62:63], v[46:47]
	s_nop 0
	v_cvt_pk_bf16_f32 v156, v156, v157
	v_cvt_pk_bf16_f32 v157, v158, v159
	v_cvt_pk_bf16_f32 v159, v162, v163
	v_add_co_u32_e32 v162, vcc, s18, v160
	v_cvt_pk_bf16_f32 v158, v164, v165
	s_nop 0
	v_addc_co_u32_e32 v163, vcc, 0, v161, vcc
	global_store_dwordx4 v[162:163], v[156:159], off
	v_pk_mul_f32 v[162:163], v[52:53], v[28:29]
	s_mov_b32 s18, 0x90000
	v_pk_mul_f32 v[158:159], v[56:57], v[32:33]
	v_pk_mul_f32 v[156:157], v[54:55], v[30:31]
	v_pk_mul_f32 v[164:165], v[50:51], v[26:27]
	v_cvt_pk_bf16_f32 v156, v156, v157
	v_cvt_pk_bf16_f32 v157, v158, v159
	v_cvt_pk_bf16_f32 v159, v162, v163
	v_add_co_u32_e32 v162, vcc, s18, v160
	v_cvt_pk_bf16_f32 v158, v164, v165
	s_nop 0
	v_addc_co_u32_e32 v163, vcc, 0, v161, vcc
	global_store_dwordx4 v[162:163], v[156:159], off
	v_pk_mul_f32 v[162:163], v[36:37], v[12:13]
	s_mov_b32 s18, 0xa0000
	v_pk_mul_f32 v[158:159], v[40:41], v[16:17]
	v_pk_mul_f32 v[156:157], v[38:39], v[14:15]
	v_pk_mul_f32 v[164:165], v[34:35], v[10:11]
	v_cvt_pk_bf16_f32 v156, v156, v157
	v_cvt_pk_bf16_f32 v157, v158, v159
	v_cvt_pk_bf16_f32 v159, v162, v163
	v_add_co_u32_e32 v162, vcc, s18, v160
	v_cvt_pk_bf16_f32 v158, v164, v165
	s_nop 0
	v_addc_co_u32_e32 v163, vcc, 0, v161, vcc
	global_store_dwordx4 v[162:163], v[156:159], off
	v_pk_mul_f32 v[162:163], v[20:21], v[4:5]
	v_pk_mul_f32 v[164:165], v[18:19], v[2:3]
	v_pk_mul_f32 v[158:159], v[24:25], v[8:9]
	v_pk_mul_f32 v[156:157], v[22:23], v[6:7]
	v_add_co_u32_e32 v160, vcc, 0xb0000, v160
	v_cvt_pk_bf16_f32 v156, v156, v157
	v_cvt_pk_bf16_f32 v157, v158, v159
	v_cvt_pk_bf16_f32 v158, v164, v165
	v_cvt_pk_bf16_f32 v159, v162, v163
	v_addc_co_u32_e32 v161, vcc, 0, v161, vcc
	s_mov_b64 s[18:19], 0
	global_store_dwordx4 v[160:161], v[156:159], off

.LBB0_649:
	s_add_u32 s18, s38, vcc_lo
	s_addc_u32 s19, s39, vcc_hi
	s_add_u32 s18, s18, 0x100
	s_addc_u32 s19, s19, 0
	s_add_u32 s57, s50, vcc_lo
	s_addc_u32 s58, s51, vcc_hi
	s_add_i32 s59, 0, 0x10000
	s_cmpk_eq_i32 vcc_lo, 0xf00
	s_cselect_b32 s23, s52, s19
	s_cselect_b32 s22, s53, s18
	s_cselect_b32 s19, s54, s58
	s_cselect_b32 s18, s55, s57
	v_lshl_add_u64 v[162:163], v[142:143], 0, vcc
	s_add_i32 m0, s28, 0xc000
	ds_read_b128 v[170:173], v148
	ds_read_b128 v[174:177], v148 offset:1024
	ds_read_b128 v[192:195], v148 offset:2048
	ds_read_b128 v[196:199], v148 offset:3072
	ds_read_b128 v[200:203], v148 offset:4096
	ds_read_b128 v[204:207], v148 offset:5120
	ds_read_b128 v[208:211], v148 offset:6144
	ds_read_b128 v[224:227], v148 offset:7168
	global_load_lds_dwordx4 v[162:163], off
	s_add_i32 m0, s28, 0xe000
	v_lshl_add_u64 v[162:163], v[144:145], 0, vcc
	global_load_lds_dwordx4 v[162:163], off
	s_barrier
	s_waitcnt lgkmcnt(0)
	v_mfma_f32_16x16x32_bf16 v[90:93], v[150:153], v[170:173], v[90:93]
	v_mfma_f32_16x16x32_bf16 v[94:97], v[158:161], v[170:173], v[94:97]
	v_mfma_f32_16x16x32_bf16 v[102:105], v[150:153], v[192:195], v[102:105]
	v_mfma_f32_16x16x32_bf16 v[106:109], v[158:161], v[192:195], v[106:109]
	v_mfma_f32_16x16x32_bf16 v[114:117], v[150:153], v[200:203], v[114:117]
	v_mfma_f32_16x16x32_bf16 v[118:121], v[158:161], v[200:203], v[118:121]
	v_mfma_f32_16x16x32_bf16 v[122:125], v[150:153], v[208:211], v[122:125]
	v_mfma_f32_16x16x32_bf16 v[126:129], v[158:161], v[208:211], v[126:129]
	v_mfma_f32_16x16x32_bf16 v[90:93], v[154:157], v[174:177], v[90:93]
	v_mfma_f32_16x16x32_bf16 v[94:97], v[166:169], v[174:177], v[94:97]
	v_mfma_f32_16x16x32_bf16 v[102:105], v[154:157], v[196:199], v[102:105]
	v_mfma_f32_16x16x32_bf16 v[106:109], v[166:169], v[196:199], v[106:109]
	v_mfma_f32_16x16x32_bf16 v[114:117], v[154:157], v[204:207], v[114:117]
	v_mfma_f32_16x16x32_bf16 v[118:121], v[166:169], v[204:207], v[118:121]
	v_mfma_f32_16x16x32_bf16 v[122:125], v[154:157], v[224:227], v[122:125]
	v_mfma_f32_16x16x32_bf16 v[126:129], v[166:169], v[224:227], v[126:129]
	s_barrier
	s_add_i32 s57, 0, 0x14000
	s_add_i32 s58, s59, s85
	v_add_u32_e32 v149, s57, v147
	v_lshl_add_u64 v[162:163], s[18:19], 0, v[134:135]
	s_mov_b32 m0, s58
	ds_read_b128 v[228:231], v149
	ds_read_b128 v[232:235], v149 offset:1024
	ds_read_b128 v[236:239], v149 offset:2048
	ds_read_b128 v[240:243], v149 offset:3072
	global_load_lds_dwordx4 v[162:163], off
	s_add_i32 m0, s58, 0x2000
	v_lshl_add_u64 v[178:179], s[18:19], 0, v[130:131]
	global_load_lds_dwordx4 v[178:179], off
	s_mov_b32 m0, s28
	v_lshl_add_u64 v[212:213], s[22:23], 0, v[136:137]
	s_waitcnt lgkmcnt(0)
	s_barrier
	v_mfma_f32_16x16x32_bf16 v[10:13], v[228:231], v[170:173], v[10:13]
	v_mfma_f32_16x16x32_bf16 v[14:17], v[236:239], v[170:173], v[14:17]
	v_mfma_f32_16x16x32_bf16 v[26:29], v[228:231], v[192:195], v[26:29]
	v_mfma_f32_16x16x32_bf16 v[38:41], v[236:239], v[192:195], v[38:41]
	v_mfma_f32_16x16x32_bf16 v[58:61], v[228:231], v[200:203], v[58:61]
	v_mfma_f32_16x16x32_bf16 v[62:65], v[236:239], v[200:203], v[62:65]
	v_mfma_f32_16x16x32_bf16 v[74:77], v[228:231], v[208:211], v[74:77]
	v_mfma_f32_16x16x32_bf16 v[78:81], v[236:239], v[208:211], v[78:81]
	v_mfma_f32_16x16x32_bf16 v[10:13], v[232:235], v[174:177], v[10:13]
	v_mfma_f32_16x16x32_bf16 v[14:17], v[240:243], v[174:177], v[14:17]
	v_mfma_f32_16x16x32_bf16 v[26:29], v[232:235], v[196:199], v[26:29]
	v_mfma_f32_16x16x32_bf16 v[38:41], v[240:243], v[196:199], v[38:41]
	v_mfma_f32_16x16x32_bf16 v[58:61], v[232:235], v[204:207], v[58:61]
	v_mfma_f32_16x16x32_bf16 v[62:65], v[240:243], v[204:207], v[62:65]
	v_mfma_f32_16x16x32_bf16 v[74:77], v[232:235], v[224:227], v[74:77]
	v_mfma_f32_16x16x32_bf16 v[78:81], v[240:243], v[224:227], v[78:81]
	s_barrier
	ds_read_b128 v[170:173], v148 offset:16384
	ds_read_b128 v[174:177], v148 offset:17408
	ds_read_b128 v[192:195], v148 offset:18432
	ds_read_b128 v[196:199], v148 offset:19456
	ds_read_b128 v[200:203], v148 offset:20480
	ds_read_b128 v[204:207], v148 offset:21504
	ds_read_b128 v[208:211], v148 offset:22528
	ds_read_b128 v[224:227], v148 offset:23552
	global_load_lds_dwordx4 v[212:213], off
	s_mov_b32 m0, s29
	v_lshl_add_u64 v[244:245], s[22:23], 0, v[132:133]
	global_load_lds_dwordx4 v[244:245], off
	s_waitcnt vmcnt(10)
	s_waitcnt lgkmcnt(0)
	s_barrier
	v_mfma_f32_16x16x32_bf16 v[110:113], v[150:153], v[170:173], v[110:113]
	v_mfma_f32_16x16x32_bf16 v[98:101], v[158:161], v[170:173], v[98:101]
	v_mfma_f32_16x16x32_bf16 v[82:85], v[150:153], v[192:195], v[82:85]
	v_mfma_f32_16x16x32_bf16 v[66:69], v[158:161], v[192:195], v[66:69]
	v_mfma_f32_16x16x32_bf16 v[50:53], v[150:153], v[200:203], v[50:53]
	v_mfma_f32_16x16x32_bf16 v[42:45], v[158:161], v[200:203], v[42:45]
	v_mfma_f32_16x16x32_bf16 v[30:33], v[150:153], v[208:211], v[30:33]
	v_mfma_f32_16x16x32_bf16 v[18:21], v[158:161], v[208:211], v[18:21]
	v_mfma_f32_16x16x32_bf16 v[110:113], v[154:157], v[174:177], v[110:113]
	v_mfma_f32_16x16x32_bf16 v[98:101], v[166:169], v[174:177], v[98:101]
	v_mfma_f32_16x16x32_bf16 v[82:85], v[154:157], v[196:199], v[82:85]
	v_mfma_f32_16x16x32_bf16 v[66:69], v[166:169], v[196:199], v[66:69]
	v_mfma_f32_16x16x32_bf16 v[50:53], v[154:157], v[204:207], v[50:53]
	v_mfma_f32_16x16x32_bf16 v[42:45], v[166:169], v[204:207], v[42:45]
	v_mfma_f32_16x16x32_bf16 v[30:33], v[154:157], v[224:227], v[30:33]
	v_mfma_f32_16x16x32_bf16 v[18:21], v[166:169], v[224:227], v[18:21]
	s_barrier
	s_add_u32 s58, s18, 0x80000
	s_addc_u32 s59, s19, 0
	s_add_i32 s57, s57, s85
	s_mov_b32 m0, s57
	v_lshl_add_u64 v[150:151], s[58:59], 0, v[134:135]
	global_load_lds_dwordx4 v[150:151], off
	s_add_i32 m0, s57, 0x2000
	v_lshl_add_u64 v[150:151], s[58:59], 0, v[130:131]
	global_load_lds_dwordx4 v[150:151], off
	v_add_u32_e32 v149, 0x18000, v147
	ds_read_b128 v[150:153], v149
	ds_read_b128 v[154:157], v149 offset:1024
	ds_read_b128 v[158:161], v149 offset:2048
	ds_read_b128 v[166:169], v149 offset:3072
	s_add_i32 s57, 0, 0x18000
	s_waitcnt vmcnt(6)
	s_barrier
	v_mfma_f32_16x16x32_bf16 v[86:89], v[228:231], v[170:173], v[86:89]
	v_mfma_f32_16x16x32_bf16 v[70:73], v[236:239], v[170:173], v[70:73]
	v_mfma_f32_16x16x32_bf16 v[54:57], v[228:231], v[192:195], v[54:57]
	v_mfma_f32_16x16x32_bf16 v[46:49], v[236:239], v[192:195], v[46:49]
	v_mfma_f32_16x16x32_bf16 v[34:37], v[228:231], v[200:203], v[34:37]
	v_mfma_f32_16x16x32_bf16 v[22:25], v[236:239], v[200:203], v[22:25]
	v_mfma_f32_16x16x32_bf16 v[6:9], v[228:231], v[208:211], v[6:9]
	v_mfma_f32_16x16x32_bf16 v[2:5], v[236:239], v[208:211], v[2:5]
	v_mfma_f32_16x16x32_bf16 v[86:89], v[232:235], v[174:177], v[86:89]
	v_mfma_f32_16x16x32_bf16 v[70:73], v[240:243], v[174:177], v[70:73]
	v_mfma_f32_16x16x32_bf16 v[54:57], v[232:235], v[196:199], v[54:57]
	v_mfma_f32_16x16x32_bf16 v[46:49], v[240:243], v[196:199], v[46:49]
	v_mfma_f32_16x16x32_bf16 v[34:37], v[232:235], v[204:207], v[34:37]
	v_mfma_f32_16x16x32_bf16 v[22:25], v[240:243], v[204:207], v[22:25]
	v_mfma_f32_16x16x32_bf16 v[6:9], v[232:235], v[224:227], v[6:9]
	v_mfma_f32_16x16x32_bf16 v[2:5], v[240:243], v[224:227], v[2:5]
	s_barrier
	s_add_u32 s22, s22, 0x80000
	s_addc_u32 s23, s23, 0
	s_mov_b32 m0, s97
	v_lshl_add_u64 v[228:229], s[22:23], 0, v[136:137]
	ds_read_b128 v[170:173], v148 offset:32768
	ds_read_b128 v[174:177], v148 offset:33792
	ds_read_b128 v[192:195], v148 offset:34816
	ds_read_b128 v[196:199], v148 offset:35840
	ds_read_b128 v[200:203], v148 offset:36864
	ds_read_b128 v[204:207], v148 offset:37888
	ds_read_b128 v[208:211], v148 offset:38912
	ds_read_b128 v[224:227], v148 offset:39936
	global_load_lds_dwordx4 v[228:229], off
	s_mov_b32 m0, s44
	v_lshl_add_u64 v[228:229], s[22:23], 0, v[132:133]
	global_load_lds_dwordx4 v[228:229], off
	s_barrier
	s_waitcnt lgkmcnt(0)
	v_mfma_f32_16x16x32_bf16 v[90:93], v[150:153], v[170:173], v[90:93]
	v_mfma_f32_16x16x32_bf16 v[94:97], v[158:161], v[170:173], v[94:97]
	v_mfma_f32_16x16x32_bf16 v[102:105], v[150:153], v[192:195], v[102:105]
	v_mfma_f32_16x16x32_bf16 v[106:109], v[158:161], v[192:195], v[106:109]
	v_mfma_f32_16x16x32_bf16 v[114:117], v[150:153], v[200:203], v[114:117]
	v_mfma_f32_16x16x32_bf16 v[118:121], v[158:161], v[200:203], v[118:121]
	v_mfma_f32_16x16x32_bf16 v[122:125], v[150:153], v[208:211], v[122:125]
	v_mfma_f32_16x16x32_bf16 v[126:129], v[158:161], v[208:211], v[126:129]
	v_mfma_f32_16x16x32_bf16 v[90:93], v[154:157], v[174:177], v[90:93]
	v_mfma_f32_16x16x32_bf16 v[94:97], v[166:169], v[174:177], v[94:97]
	v_mfma_f32_16x16x32_bf16 v[102:105], v[154:157], v[196:199], v[102:105]
	v_mfma_f32_16x16x32_bf16 v[106:109], v[166:169], v[196:199], v[106:109]
	v_mfma_f32_16x16x32_bf16 v[114:117], v[154:157], v[204:207], v[114:117]
	v_mfma_f32_16x16x32_bf16 v[118:121], v[166:169], v[204:207], v[118:121]
	v_mfma_f32_16x16x32_bf16 v[122:125], v[154:157], v[224:227], v[122:125]
	v_mfma_f32_16x16x32_bf16 v[126:129], v[166:169], v[224:227], v[126:129]
	s_barrier
	s_add_i32 s22, 0, 0x1c000
	s_add_i32 s23, s57, s85
	v_add_u32_e32 v149, s22, v147
	v_lshl_add_u64 v[162:163], v[162:163], 0, s[78:79]
	s_mov_b32 m0, s23
	ds_read_b128 v[228:231], v149
	ds_read_b128 v[232:235], v149 offset:1024
	ds_read_b128 v[236:239], v149 offset:2048
	ds_read_b128 v[240:243], v149 offset:3072
	global_load_lds_dwordx4 v[162:163], off
	s_add_i32 m0, s23, 0x2000
	v_lshl_add_u64 v[162:163], v[178:179], 0, s[78:79]
	global_load_lds_dwordx4 v[162:163], off
	s_mov_b32 m0, s46
	v_lshl_add_u64 v[162:163], v[212:213], 0, s[78:79]
	s_waitcnt lgkmcnt(0)
	s_barrier
	v_mfma_f32_16x16x32_bf16 v[10:13], v[228:231], v[170:173], v[10:13]
	v_mfma_f32_16x16x32_bf16 v[14:17], v[236:239], v[170:173], v[14:17]
	v_mfma_f32_16x16x32_bf16 v[26:29], v[228:231], v[192:195], v[26:29]
	v_mfma_f32_16x16x32_bf16 v[38:41], v[236:239], v[192:195], v[38:41]
	v_mfma_f32_16x16x32_bf16 v[58:61], v[228:231], v[200:203], v[58:61]
	v_mfma_f32_16x16x32_bf16 v[62:65], v[236:239], v[200:203], v[62:65]
	v_mfma_f32_16x16x32_bf16 v[74:77], v[228:231], v[208:211], v[74:77]
	v_mfma_f32_16x16x32_bf16 v[78:81], v[236:239], v[208:211], v[78:81]
	v_mfma_f32_16x16x32_bf16 v[10:13], v[232:235], v[174:177], v[10:13]
	v_mfma_f32_16x16x32_bf16 v[14:17], v[240:243], v[174:177], v[14:17]
	v_mfma_f32_16x16x32_bf16 v[26:29], v[232:235], v[196:199], v[26:29]
	v_mfma_f32_16x16x32_bf16 v[38:41], v[240:243], v[196:199], v[38:41]
	v_mfma_f32_16x16x32_bf16 v[58:61], v[232:235], v[204:207], v[58:61]
	v_mfma_f32_16x16x32_bf16 v[62:65], v[240:243], v[204:207], v[62:65]
	v_mfma_f32_16x16x32_bf16 v[74:77], v[232:235], v[224:227], v[74:77]
	v_mfma_f32_16x16x32_bf16 v[78:81], v[240:243], v[224:227], v[78:81]
	s_barrier
	ds_read_b128 v[170:173], v148 offset:49152
	ds_read_b128 v[174:177], v148 offset:50176
	ds_read_b128 v[192:195], v148 offset:51200
	ds_read_b128 v[196:199], v148 offset:52224
	ds_read_b128 v[200:203], v148 offset:53248
	ds_read_b128 v[204:207], v148 offset:54272
	ds_read_b128 v[208:211], v148 offset:55296
	ds_read_b128 v[224:227], v148 offset:56320
	global_load_lds_dwordx4 v[162:163], off
	s_mov_b32 m0, s47
	v_lshl_add_u64 v[162:163], v[244:245], 0, s[78:79]
	global_load_lds_dwordx4 v[162:163], off
	s_waitcnt vmcnt(10)
	s_waitcnt lgkmcnt(0)
	s_barrier
	v_mfma_f32_16x16x32_bf16 v[110:113], v[150:153], v[170:173], v[110:113]
	v_mfma_f32_16x16x32_bf16 v[98:101], v[158:161], v[170:173], v[98:101]
	v_mfma_f32_16x16x32_bf16 v[82:85], v[150:153], v[192:195], v[82:85]
	v_mfma_f32_16x16x32_bf16 v[66:69], v[158:161], v[192:195], v[66:69]
	v_mfma_f32_16x16x32_bf16 v[50:53], v[150:153], v[200:203], v[50:53]
	v_mfma_f32_16x16x32_bf16 v[42:45], v[158:161], v[200:203], v[42:45]
	v_mfma_f32_16x16x32_bf16 v[30:33], v[150:153], v[208:211], v[30:33]
	v_mfma_f32_16x16x32_bf16 v[18:21], v[158:161], v[208:211], v[18:21]
	v_mfma_f32_16x16x32_bf16 v[110:113], v[154:157], v[174:177], v[110:113]
	v_mfma_f32_16x16x32_bf16 v[98:101], v[166:169], v[174:177], v[98:101]
	v_mfma_f32_16x16x32_bf16 v[82:85], v[154:157], v[196:199], v[82:85]
	v_mfma_f32_16x16x32_bf16 v[66:69], v[166:169], v[196:199], v[66:69]
	v_mfma_f32_16x16x32_bf16 v[50:53], v[154:157], v[204:207], v[50:53]
	v_mfma_f32_16x16x32_bf16 v[42:45], v[166:169], v[204:207], v[42:45]
	v_mfma_f32_16x16x32_bf16 v[30:33], v[154:157], v[224:227], v[30:33]
	v_mfma_f32_16x16x32_bf16 v[18:21], v[166:169], v[224:227], v[18:21]
	s_barrier
	s_add_u32 s18, s18, 0x80080
	s_addc_u32 s19, s19, 0
	s_add_i32 s22, s22, s85
	s_mov_b32 m0, s22
	v_lshl_add_u64 v[150:151], s[18:19], 0, v[134:135]
	global_load_lds_dwordx4 v[150:151], off
	s_add_i32 m0, s22, 0x2000
	v_lshl_add_u64 v[150:151], s[18:19], 0, v[130:131]
	global_load_lds_dwordx4 v[150:151], off
	v_add_u32_e32 v149, 0x10000, v147
	ds_read_b128 v[150:153], v149
	ds_read_b128 v[154:157], v149 offset:1024
	ds_read_b128 v[158:161], v149 offset:2048
	ds_read_b128 v[166:169], v149 offset:3072
	s_add_i32 s56, s56, 2
	s_add_u32 vcc_lo, vcc_lo, 0x100
	s_addc_u32 vcc_hi, vcc_hi, 0
	s_cmp_gt_u32 s56, 29
	s_waitcnt vmcnt(6)
	s_barrier
	v_mfma_f32_16x16x32_bf16 v[86:89], v[228:231], v[170:173], v[86:89]
	v_mfma_f32_16x16x32_bf16 v[70:73], v[236:239], v[170:173], v[70:73]
	v_mfma_f32_16x16x32_bf16 v[54:57], v[228:231], v[192:195], v[54:57]
	v_mfma_f32_16x16x32_bf16 v[46:49], v[236:239], v[192:195], v[46:49]
	v_mfma_f32_16x16x32_bf16 v[34:37], v[228:231], v[200:203], v[34:37]
	v_mfma_f32_16x16x32_bf16 v[22:25], v[236:239], v[200:203], v[22:25]
	v_mfma_f32_16x16x32_bf16 v[6:9], v[228:231], v[208:211], v[6:9]
	v_mfma_f32_16x16x32_bf16 v[2:5], v[236:239], v[208:211], v[2:5]
	v_mfma_f32_16x16x32_bf16 v[86:89], v[232:235], v[174:177], v[86:89]
	v_mfma_f32_16x16x32_bf16 v[70:73], v[240:243], v[174:177], v[70:73]
	v_mfma_f32_16x16x32_bf16 v[54:57], v[232:235], v[196:199], v[54:57]
	v_mfma_f32_16x16x32_bf16 v[46:49], v[240:243], v[196:199], v[46:49]
	v_mfma_f32_16x16x32_bf16 v[34:37], v[232:235], v[204:207], v[34:37]
	v_mfma_f32_16x16x32_bf16 v[22:25], v[240:243], v[204:207], v[22:25]
	v_mfma_f32_16x16x32_bf16 v[6:9], v[232:235], v[224:227], v[6:9]
	v_mfma_f32_16x16x32_bf16 v[2:5], v[240:243], v[224:227], v[2:5]
	s_barrier
	s_cbranch_scc0 .LBB0_649
	s_waitcnt lgkmcnt(0)
	s_add_u32 s18, s50, 0xffffff00
	s_addc_u32 s19, s51, -1
	s_andn2_b64 vcc, exec, s[42:43]
	s_cbranch_vccnz .LBB0_652
	v_mov_b32_e32 v2, 0
	s_mov_b32 s84, s80
	s_mov_b32 s25, s82
	s_mov_b64 s[38:39], s[20:21]
	s_mov_b32 s48, s49
	v_mov_b32_e32 v3, v2
	v_mov_b32_e32 v4, v2
	v_mov_b32_e32 v5, v2
	v_mov_b32_e32 v6, v2
	v_mov_b32_e32 v7, v2
	v_mov_b32_e32 v8, v2
	v_mov_b32_e32 v9, v2
	v_mov_b32_e32 v22, v2
	v_mov_b32_e32 v23, v2
	v_mov_b32_e32 v24, v2
	v_mov_b32_e32 v25, v2
	v_mov_b32_e32 v34, v2
	v_mov_b32_e32 v35, v2
	v_mov_b32_e32 v36, v2
	v_mov_b32_e32 v37, v2
	v_mov_b32_e32 v46, v2
	v_mov_b32_e32 v47, v2
	v_mov_b32_e32 v48, v2
	v_mov_b32_e32 v49, v2
	v_mov_b32_e32 v54, v2
	v_mov_b32_e32 v55, v2
	v_mov_b32_e32 v56, v2
	v_mov_b32_e32 v57, v2
	v_mov_b32_e32 v70, v2
	v_mov_b32_e32 v71, v2
	v_mov_b32_e32 v72, v2
	v_mov_b32_e32 v73, v2
	v_mov_b32_e32 v86, v2
	v_mov_b32_e32 v87, v2
	v_mov_b32_e32 v88, v2
	v_mov_b32_e32 v89, v2
	v_mov_b32_e32 v18, v2
	v_mov_b32_e32 v19, v2
	v_mov_b32_e32 v20, v2
	v_mov_b32_e32 v21, v2
	v_mov_b32_e32 v30, v2
	v_mov_b32_e32 v31, v2
	v_mov_b32_e32 v32, v2
	v_mov_b32_e32 v33, v2
	v_mov_b32_e32 v42, v2
	v_mov_b32_e32 v43, v2
	v_mov_b32_e32 v44, v2
	v_mov_b32_e32 v45, v2
	v_mov_b32_e32 v50, v2
	v_mov_b32_e32 v51, v2
	v_mov_b32_e32 v52, v2
	v_mov_b32_e32 v53, v2
	v_mov_b32_e32 v66, v2
	v_mov_b32_e32 v67, v2
	v_mov_b32_e32 v68, v2
	v_mov_b32_e32 v69, v2
	v_mov_b32_e32 v82, v2
	v_mov_b32_e32 v83, v2
	v_mov_b32_e32 v84, v2
	v_mov_b32_e32 v85, v2
	v_mov_b32_e32 v98, v2
	v_mov_b32_e32 v99, v2
	v_mov_b32_e32 v100, v2
	v_mov_b32_e32 v101, v2
	v_mov_b32_e32 v110, v2
	v_mov_b32_e32 v111, v2
	v_mov_b32_e32 v112, v2
	v_mov_b32_e32 v113, v2
	v_mov_b32_e32 v78, v2
	v_mov_b32_e32 v79, v2
	v_mov_b32_e32 v80, v2
	v_mov_b32_e32 v81, v2
	v_mov_b32_e32 v74, v2
	v_mov_b32_e32 v75, v2
	v_mov_b32_e32 v76, v2
	v_mov_b32_e32 v77, v2
	v_mov_b32_e32 v62, v2
	v_mov_b32_e32 v63, v2
	v_mov_b32_e32 v64, v2
	v_mov_b32_e32 v65, v2
	v_mov_b32_e32 v58, v2
	v_mov_b32_e32 v59, v2
	v_mov_b32_e32 v60, v2
	v_mov_b32_e32 v61, v2
	v_mov_b32_e32 v38, v2
	v_mov_b32_e32 v39, v2
	v_mov_b32_e32 v40, v2
	v_mov_b32_e32 v41, v2
	v_mov_b32_e32 v26, v2
	v_mov_b32_e32 v27, v2
	v_mov_b32_e32 v28, v2
	v_mov_b32_e32 v29, v2
	v_mov_b32_e32 v14, v2
	v_mov_b32_e32 v15, v2
	v_mov_b32_e32 v16, v2
	v_mov_b32_e32 v17, v2
	v_mov_b32_e32 v10, v2
	v_mov_b32_e32 v11, v2
	v_mov_b32_e32 v12, v2
	v_mov_b32_e32 v13, v2
	v_mov_b32_e32 v126, v2
	v_mov_b32_e32 v127, v2
	v_mov_b32_e32 v128, v2
	v_mov_b32_e32 v129, v2
	v_mov_b32_e32 v122, v2
	v_mov_b32_e32 v123, v2
	v_mov_b32_e32 v124, v2
	v_mov_b32_e32 v125, v2
	v_mov_b32_e32 v118, v2
	v_mov_b32_e32 v119, v2
	v_mov_b32_e32 v120, v2
	v_mov_b32_e32 v121, v2
	v_mov_b32_e32 v114, v2
	v_mov_b32_e32 v115, v2
	v_mov_b32_e32 v116, v2
	v_mov_b32_e32 v117, v2
	v_mov_b32_e32 v106, v2
	v_mov_b32_e32 v107, v2
	v_mov_b32_e32 v108, v2
	v_mov_b32_e32 v109, v2
	v_mov_b32_e32 v102, v2
	v_mov_b32_e32 v103, v2
	v_mov_b32_e32 v104, v2
	v_mov_b32_e32 v105, v2
	v_mov_b32_e32 v94, v2
	v_mov_b32_e32 v95, v2
	v_mov_b32_e32 v96, v2
	v_mov_b32_e32 v97, v2
	v_mov_b32_e32 v90, v2
	v_mov_b32_e32 v91, v2
	v_mov_b32_e32 v92, v2
	v_mov_b32_e32 v93, v2
	s_andn2_b64 vcc, exec, s[0:1]
	s_cbranch_vccnz .LBB0_653
	s_branch .LBB0_654

.LBB0_749:
	s_add_u32 s20, s18, 0xfff80080
	s_addc_u32 s21, s19, -1
	s_add_i32 s58, 0, 0x10000
	s_cmp_eq_u32 s57, 28
	s_cselect_b32 s23, s39, s21
	s_cselect_b32 s22, s53, s20
	s_cselect_b32 s21, s31, s56
	s_cselect_b32 s20, s54, s55
	v_lshl_add_u64 v[212:213], s[18:19], 0, v[154:155]
	s_add_i32 m0, s44, 0xc000
	ds_read_b128 v[176:179], v158
	ds_read_b128 v[192:195], v158 offset:1024
	ds_read_b128 v[196:199], v158 offset:2048
	ds_read_b128 v[200:203], v158 offset:3072
	ds_read_b128 v[204:207], v158 offset:4096
	ds_read_b128 v[208:211], v158 offset:5120
	ds_read_b128 v[224:227], v158 offset:6144
	ds_read_b128 v[228:231], v158 offset:7168
	global_load_lds_dwordx4 v[212:213], off
	s_add_i32 m0, s44, 0xe000
	v_lshl_add_u64 v[212:213], s[18:19], 0, v[156:157]
	global_load_lds_dwordx4 v[212:213], off
	s_barrier
	s_waitcnt lgkmcnt(0)
	v_mfma_f32_16x16x32_bf16 v[126:129], v[160:163], v[176:179], v[126:129]
	v_mfma_f32_16x16x32_bf16 v[122:125], v[168:171], v[176:179], v[122:125]
	v_mfma_f32_16x16x32_bf16 v[110:113], v[160:163], v[196:199], v[110:113]
	v_mfma_f32_16x16x32_bf16 v[106:109], v[168:171], v[196:199], v[106:109]
	v_mfma_f32_16x16x32_bf16 v[94:97], v[160:163], v[204:207], v[94:97]
	v_mfma_f32_16x16x32_bf16 v[90:93], v[168:171], v[204:207], v[90:93]
	v_mfma_f32_16x16x32_bf16 v[78:81], v[160:163], v[224:227], v[78:81]
	v_mfma_f32_16x16x32_bf16 v[74:77], v[168:171], v[224:227], v[74:77]
	v_mfma_f32_16x16x32_bf16 v[126:129], v[164:167], v[192:195], v[126:129]
	v_mfma_f32_16x16x32_bf16 v[122:125], v[172:175], v[192:195], v[122:125]
	v_mfma_f32_16x16x32_bf16 v[110:113], v[164:167], v[200:203], v[110:113]
	v_mfma_f32_16x16x32_bf16 v[106:109], v[172:175], v[200:203], v[106:109]
	v_mfma_f32_16x16x32_bf16 v[94:97], v[164:167], v[208:211], v[94:97]
	v_mfma_f32_16x16x32_bf16 v[90:93], v[172:175], v[208:211], v[90:93]
	v_mfma_f32_16x16x32_bf16 v[78:81], v[164:167], v[228:231], v[78:81]
	v_mfma_f32_16x16x32_bf16 v[74:77], v[172:175], v[228:231], v[74:77]
	s_barrier
	s_add_i32 s82, 0, 0x14000
	s_add_i32 s58, s58, s29
	v_add_u32_e32 v159, s82, v1
	v_lshl_add_u64 v[212:213], s[20:21], 0, v[134:135]
	s_mov_b32 m0, s58
	ds_read_b128 v[232:235], v159
	ds_read_b128 v[236:239], v159 offset:1024
	ds_read_b128 v[240:243], v159 offset:2048
	ds_read_b128 v[244:247], v159 offset:3072
	global_load_lds_dwordx4 v[212:213], off
	s_add_i32 m0, s58, 0x2000
	v_lshl_add_u64 v[248:249], s[20:21], 0, v[130:131]
	global_load_lds_dwordx4 v[248:249], off
	s_mov_b32 m0, s44
	v_lshl_add_u64 v[250:251], s[22:23], 0, v[136:137]
	s_waitcnt lgkmcnt(0)
	s_barrier
	v_mfma_f32_16x16x32_bf16 v[118:121], v[232:235], v[176:179], v[118:121]
	v_mfma_f32_16x16x32_bf16 v[114:117], v[240:243], v[176:179], v[114:117]
	v_mfma_f32_16x16x32_bf16 v[102:105], v[232:235], v[196:199], v[102:105]
	v_mfma_f32_16x16x32_bf16 v[98:101], v[240:243], v[196:199], v[98:101]
	v_mfma_f32_16x16x32_bf16 v[86:89], v[232:235], v[204:207], v[86:89]
	v_mfma_f32_16x16x32_bf16 v[82:85], v[240:243], v[204:207], v[82:85]
	v_mfma_f32_16x16x32_bf16 v[70:73], v[232:235], v[224:227], v[70:73]
	v_mfma_f32_16x16x32_bf16 v[66:69], v[240:243], v[224:227], v[66:69]
	v_mfma_f32_16x16x32_bf16 v[118:121], v[236:239], v[192:195], v[118:121]
	v_mfma_f32_16x16x32_bf16 v[114:117], v[244:247], v[192:195], v[114:117]
	v_mfma_f32_16x16x32_bf16 v[102:105], v[236:239], v[200:203], v[102:105]
	v_mfma_f32_16x16x32_bf16 v[98:101], v[244:247], v[200:203], v[98:101]
	v_mfma_f32_16x16x32_bf16 v[86:89], v[236:239], v[208:211], v[86:89]
	v_mfma_f32_16x16x32_bf16 v[82:85], v[244:247], v[208:211], v[82:85]
	v_mfma_f32_16x16x32_bf16 v[70:73], v[236:239], v[228:231], v[70:73]
	v_mfma_f32_16x16x32_bf16 v[66:69], v[244:247], v[228:231], v[66:69]
	s_barrier
	ds_read_b128 v[176:179], v158 offset:16384
	ds_read_b128 v[192:195], v158 offset:17408
	ds_read_b128 v[196:199], v158 offset:18432
	ds_read_b128 v[200:203], v158 offset:19456
	ds_read_b128 v[204:207], v158 offset:20480
	ds_read_b128 v[208:211], v158 offset:21504
	ds_read_b128 v[224:227], v158 offset:22528
	ds_read_b128 v[228:231], v158 offset:23552
	global_load_lds_dwordx4 v[250:251], off
	s_mov_b32 m0, s45
	v_lshl_add_u64 v[222:223], s[22:23], 0, v[132:133]
	global_load_lds_dwordx4 v[222:223], off
	s_waitcnt vmcnt(10)
	s_waitcnt lgkmcnt(0)
	s_barrier
	v_mfma_f32_16x16x32_bf16 v[62:65], v[160:163], v[176:179], v[62:65]
	v_mfma_f32_16x16x32_bf16 v[58:61], v[168:171], v[176:179], v[58:61]
	v_mfma_f32_16x16x32_bf16 v[46:49], v[160:163], v[196:199], v[46:49]
	v_mfma_f32_16x16x32_bf16 v[42:45], v[168:171], v[196:199], v[42:45]
	v_mfma_f32_16x16x32_bf16 v[30:33], v[160:163], v[204:207], v[30:33]
	v_mfma_f32_16x16x32_bf16 v[26:29], v[168:171], v[204:207], v[26:29]
	v_mfma_f32_16x16x32_bf16 v[14:17], v[160:163], v[224:227], v[14:17]
	v_mfma_f32_16x16x32_bf16 v[10:13], v[168:171], v[224:227], v[10:13]
	v_mfma_f32_16x16x32_bf16 v[62:65], v[164:167], v[192:195], v[62:65]
	v_mfma_f32_16x16x32_bf16 v[58:61], v[172:175], v[192:195], v[58:61]
	v_mfma_f32_16x16x32_bf16 v[46:49], v[164:167], v[200:203], v[46:49]
	v_mfma_f32_16x16x32_bf16 v[42:45], v[172:175], v[200:203], v[42:45]
	v_mfma_f32_16x16x32_bf16 v[30:33], v[164:167], v[208:211], v[30:33]
	v_mfma_f32_16x16x32_bf16 v[26:29], v[172:175], v[208:211], v[26:29]
	v_mfma_f32_16x16x32_bf16 v[14:17], v[164:167], v[228:231], v[14:17]
	v_mfma_f32_16x16x32_bf16 v[10:13], v[172:175], v[228:231], v[10:13]
	s_barrier
	s_add_u32 s58, s20, 0x80000
	s_addc_u32 s59, s21, 0
	s_add_i32 s82, s82, s29
	s_mov_b32 m0, s82
	v_lshl_add_u64 v[160:161], s[58:59], 0, v[134:135]
	global_load_lds_dwordx4 v[160:161], off
	s_add_i32 m0, s82, 0x2000
	v_lshl_add_u64 v[160:161], s[58:59], 0, v[130:131]
	global_load_lds_dwordx4 v[160:161], off
	v_add_u32_e32 v159, 0x18000, v1
	ds_read_b128 v[160:163], v159
	ds_read_b128 v[164:167], v159 offset:1024
	ds_read_b128 v[168:171], v159 offset:2048
	ds_read_b128 v[172:175], v159 offset:3072
	s_add_i32 s58, 0, 0x18000
	s_waitcnt vmcnt(6)
	s_barrier
	v_mfma_f32_16x16x32_bf16 v[54:57], v[232:235], v[176:179], v[54:57]
	v_mfma_f32_16x16x32_bf16 v[50:53], v[240:243], v[176:179], v[50:53]
	v_mfma_f32_16x16x32_bf16 v[38:41], v[232:235], v[196:199], v[38:41]
	v_mfma_f32_16x16x32_bf16 v[34:37], v[240:243], v[196:199], v[34:37]
	v_mfma_f32_16x16x32_bf16 v[22:25], v[232:235], v[204:207], v[22:25]
	v_mfma_f32_16x16x32_bf16 v[18:21], v[240:243], v[204:207], v[18:21]
	v_mfma_f32_16x16x32_bf16 v[6:9], v[232:235], v[224:227], v[6:9]
	v_mfma_f32_16x16x32_bf16 v[2:5], v[240:243], v[224:227], v[2:5]
	v_mfma_f32_16x16x32_bf16 v[54:57], v[236:239], v[192:195], v[54:57]
	v_mfma_f32_16x16x32_bf16 v[50:53], v[244:247], v[192:195], v[50:53]
	v_mfma_f32_16x16x32_bf16 v[38:41], v[236:239], v[200:203], v[38:41]
	v_mfma_f32_16x16x32_bf16 v[34:37], v[244:247], v[200:203], v[34:37]
	v_mfma_f32_16x16x32_bf16 v[22:25], v[236:239], v[208:211], v[22:25]
	v_mfma_f32_16x16x32_bf16 v[18:21], v[244:247], v[208:211], v[18:21]
	v_mfma_f32_16x16x32_bf16 v[6:9], v[236:239], v[228:231], v[6:9]
	v_mfma_f32_16x16x32_bf16 v[2:5], v[244:247], v[228:231], v[2:5]
	s_barrier
	s_add_u32 s22, s22, 0x80000
	s_addc_u32 s23, s23, 0
	s_mov_b32 m0, s46
	v_lshl_add_u64 v[232:233], s[22:23], 0, v[136:137]
	ds_read_b128 v[176:179], v158 offset:32768
	ds_read_b128 v[192:195], v158 offset:33792
	ds_read_b128 v[196:199], v158 offset:34816
	ds_read_b128 v[200:203], v158 offset:35840
	ds_read_b128 v[204:207], v158 offset:36864
	ds_read_b128 v[208:211], v158 offset:37888
	ds_read_b128 v[224:227], v158 offset:38912
	ds_read_b128 v[228:231], v158 offset:39936
	global_load_lds_dwordx4 v[232:233], off
	s_mov_b32 m0, s47
	v_lshl_add_u64 v[232:233], s[22:23], 0, v[132:133]
	global_load_lds_dwordx4 v[232:233], off
	s_barrier
	s_waitcnt lgkmcnt(0)
	v_mfma_f32_16x16x32_bf16 v[126:129], v[160:163], v[176:179], v[126:129]
	v_mfma_f32_16x16x32_bf16 v[122:125], v[168:171], v[176:179], v[122:125]
	v_mfma_f32_16x16x32_bf16 v[110:113], v[160:163], v[196:199], v[110:113]
	v_mfma_f32_16x16x32_bf16 v[106:109], v[168:171], v[196:199], v[106:109]
	v_mfma_f32_16x16x32_bf16 v[94:97], v[160:163], v[204:207], v[94:97]
	v_mfma_f32_16x16x32_bf16 v[90:93], v[168:171], v[204:207], v[90:93]
	v_mfma_f32_16x16x32_bf16 v[78:81], v[160:163], v[224:227], v[78:81]
	v_mfma_f32_16x16x32_bf16 v[74:77], v[168:171], v[224:227], v[74:77]
	v_mfma_f32_16x16x32_bf16 v[126:129], v[164:167], v[192:195], v[126:129]
	v_mfma_f32_16x16x32_bf16 v[122:125], v[172:175], v[192:195], v[122:125]
	v_mfma_f32_16x16x32_bf16 v[110:113], v[164:167], v[200:203], v[110:113]
	v_mfma_f32_16x16x32_bf16 v[106:109], v[172:175], v[200:203], v[106:109]
	v_mfma_f32_16x16x32_bf16 v[94:97], v[164:167], v[208:211], v[94:97]
	v_mfma_f32_16x16x32_bf16 v[90:93], v[172:175], v[208:211], v[90:93]
	v_mfma_f32_16x16x32_bf16 v[78:81], v[164:167], v[228:231], v[78:81]
	v_mfma_f32_16x16x32_bf16 v[74:77], v[172:175], v[228:231], v[74:77]
	s_barrier
	s_add_i32 s22, 0, 0x1c000
	s_add_i32 s23, s58, s29
	v_add_u32_e32 v159, s22, v1
	v_lshl_add_u64 v[212:213], v[212:213], 0, s[78:79]
	s_mov_b32 m0, s23
	ds_read_b128 v[232:235], v159
	ds_read_b128 v[236:239], v159 offset:1024
	ds_read_b128 v[240:243], v159 offset:2048
	ds_read_b128 v[244:247], v159 offset:3072
	global_load_lds_dwordx4 v[212:213], off
	s_add_i32 m0, s23, 0x2000
	v_lshl_add_u64 v[212:213], v[248:249], 0, s[78:79]
	global_load_lds_dwordx4 v[212:213], off
	s_mov_b32 m0, s48
	v_lshl_add_u64 v[212:213], v[250:251], 0, s[78:79]
	s_waitcnt lgkmcnt(0)
	s_barrier
	v_mfma_f32_16x16x32_bf16 v[118:121], v[232:235], v[176:179], v[118:121]
	v_mfma_f32_16x16x32_bf16 v[114:117], v[240:243], v[176:179], v[114:117]
	v_mfma_f32_16x16x32_bf16 v[102:105], v[232:235], v[196:199], v[102:105]
	v_mfma_f32_16x16x32_bf16 v[98:101], v[240:243], v[196:199], v[98:101]
	v_mfma_f32_16x16x32_bf16 v[86:89], v[232:235], v[204:207], v[86:89]
	v_mfma_f32_16x16x32_bf16 v[82:85], v[240:243], v[204:207], v[82:85]
	v_mfma_f32_16x16x32_bf16 v[70:73], v[232:235], v[224:227], v[70:73]
	v_mfma_f32_16x16x32_bf16 v[66:69], v[240:243], v[224:227], v[66:69]
	v_mfma_f32_16x16x32_bf16 v[118:121], v[236:239], v[192:195], v[118:121]
	v_mfma_f32_16x16x32_bf16 v[114:117], v[244:247], v[192:195], v[114:117]
	v_mfma_f32_16x16x32_bf16 v[102:105], v[236:239], v[200:203], v[102:105]
	v_mfma_f32_16x16x32_bf16 v[98:101], v[244:247], v[200:203], v[98:101]
	v_mfma_f32_16x16x32_bf16 v[86:89], v[236:239], v[208:211], v[86:89]
	v_mfma_f32_16x16x32_bf16 v[82:85], v[244:247], v[208:211], v[82:85]
	v_mfma_f32_16x16x32_bf16 v[70:73], v[236:239], v[228:231], v[70:73]
	v_mfma_f32_16x16x32_bf16 v[66:69], v[244:247], v[228:231], v[66:69]
	s_barrier
	ds_read_b128 v[176:179], v158 offset:49152
	ds_read_b128 v[192:195], v158 offset:50176
	ds_read_b128 v[196:199], v158 offset:51200
	ds_read_b128 v[200:203], v158 offset:52224
	ds_read_b128 v[204:207], v158 offset:53248
	ds_read_b128 v[208:211], v158 offset:54272
	ds_read_b128 v[224:227], v158 offset:55296
	ds_read_b128 v[228:231], v158 offset:56320
	global_load_lds_dwordx4 v[212:213], off
	s_mov_b32 m0, s49
	v_lshl_add_u64 v[212:213], v[222:223], 0, s[78:79]
	global_load_lds_dwordx4 v[212:213], off
	s_waitcnt vmcnt(10)
	s_waitcnt lgkmcnt(0)
	s_barrier
	v_mfma_f32_16x16x32_bf16 v[62:65], v[160:163], v[176:179], v[62:65]
	v_mfma_f32_16x16x32_bf16 v[58:61], v[168:171], v[176:179], v[58:61]
	v_mfma_f32_16x16x32_bf16 v[46:49], v[160:163], v[196:199], v[46:49]
	v_mfma_f32_16x16x32_bf16 v[42:45], v[168:171], v[196:199], v[42:45]
	v_mfma_f32_16x16x32_bf16 v[30:33], v[160:163], v[204:207], v[30:33]
	v_mfma_f32_16x16x32_bf16 v[26:29], v[168:171], v[204:207], v[26:29]
	v_mfma_f32_16x16x32_bf16 v[14:17], v[160:163], v[224:227], v[14:17]
	v_mfma_f32_16x16x32_bf16 v[10:13], v[168:171], v[224:227], v[10:13]
	v_mfma_f32_16x16x32_bf16 v[62:65], v[164:167], v[192:195], v[62:65]
	v_mfma_f32_16x16x32_bf16 v[58:61], v[172:175], v[192:195], v[58:61]
	v_mfma_f32_16x16x32_bf16 v[46:49], v[164:167], v[200:203], v[46:49]
	v_mfma_f32_16x16x32_bf16 v[42:45], v[172:175], v[200:203], v[42:45]
	v_mfma_f32_16x16x32_bf16 v[30:33], v[164:167], v[208:211], v[30:33]
	v_mfma_f32_16x16x32_bf16 v[26:29], v[172:175], v[208:211], v[26:29]
	v_mfma_f32_16x16x32_bf16 v[14:17], v[164:167], v[228:231], v[14:17]
	v_mfma_f32_16x16x32_bf16 v[10:13], v[172:175], v[228:231], v[10:13]
	s_barrier
	s_add_u32 s20, s20, 0x80080
	s_addc_u32 s21, s21, 0
	s_add_i32 s22, s22, s29
	s_mov_b32 m0, s22
	v_lshl_add_u64 v[160:161], s[20:21], 0, v[134:135]
	global_load_lds_dwordx4 v[160:161], off
	s_add_i32 m0, s22, 0x2000
	v_lshl_add_u64 v[160:161], s[20:21], 0, v[130:131]
	global_load_lds_dwordx4 v[160:161], off
	v_add_u32_e32 v159, 0x10000, v1
	ds_read_b128 v[160:163], v159
	ds_read_b128 v[164:167], v159 offset:1024
	ds_read_b128 v[168:171], v159 offset:2048
	ds_read_b128 v[172:175], v159 offset:3072
	s_add_i32 s57, s57, 2
	s_add_u32 s18, s18, 0x100
	s_addc_u32 s19, s19, 0
	s_add_u32 s55, s55, 0x100
	s_addc_u32 s56, s56, 0
	s_cmp_gt_u32 s57, 29
	s_waitcnt vmcnt(6)
	s_barrier
	v_mfma_f32_16x16x32_bf16 v[54:57], v[232:235], v[176:179], v[54:57]
	v_mfma_f32_16x16x32_bf16 v[50:53], v[240:243], v[176:179], v[50:53]
	v_mfma_f32_16x16x32_bf16 v[38:41], v[232:235], v[196:199], v[38:41]
	v_mfma_f32_16x16x32_bf16 v[34:37], v[240:243], v[196:199], v[34:37]
	v_mfma_f32_16x16x32_bf16 v[22:25], v[232:235], v[204:207], v[22:25]
	v_mfma_f32_16x16x32_bf16 v[18:21], v[240:243], v[204:207], v[18:21]
	v_mfma_f32_16x16x32_bf16 v[6:9], v[232:235], v[224:227], v[6:9]
	v_mfma_f32_16x16x32_bf16 v[2:5], v[240:243], v[224:227], v[2:5]
	v_mfma_f32_16x16x32_bf16 v[54:57], v[236:239], v[192:195], v[54:57]
	v_mfma_f32_16x16x32_bf16 v[50:53], v[244:247], v[192:195], v[50:53]
	v_mfma_f32_16x16x32_bf16 v[38:41], v[236:239], v[200:203], v[38:41]
	v_mfma_f32_16x16x32_bf16 v[34:37], v[244:247], v[200:203], v[34:37]
	v_mfma_f32_16x16x32_bf16 v[22:25], v[236:239], v[208:211], v[22:25]
	v_mfma_f32_16x16x32_bf16 v[18:21], v[244:247], v[208:211], v[18:21]
	v_mfma_f32_16x16x32_bf16 v[6:9], v[236:239], v[228:231], v[6:9]
	v_mfma_f32_16x16x32_bf16 v[2:5], v[244:247], v[228:231], v[2:5]
	s_barrier
	s_cbranch_scc0 .LBB0_749
	s_waitcnt lgkmcnt(0)
	s_lshl_b32 s18, s52, 5
	s_add_i32 s18, s18, s51
	v_max_f32_e32 v122, 0, v122
	v_max_f32_e32 v123, 0, v123
	s_ashr_i32 s19, s18, 31
	v_pk_mul_f32 v[162:163], v[122:123], v[122:123]
	v_max_f32_e32 v123, v124, v124
	s_lshl_b64 s[18:19], s[18:19], 17
	v_max_f32_e32 v122, v128, v128
	v_max_f32_e32 v124, 0, v123
	v_max_f32_e32 v123, v129, v129
	s_add_u32 s18, s68, s18
	v_max_f32_e32 v126, 0, v126
	v_max_f32_e32 v127, 0, v127
	v_max_f32_e32 v122, 0, v122
	v_max_f32_e32 v123, 0, v123
	v_max_f32_e32 v125, 0, v125
	s_addc_u32 s19, s69, s19
	v_pk_mul_f32 v[126:127], v[126:127], v[126:127]
	v_pk_mul_f32 v[128:129], v[122:123], v[122:123]
	v_pk_mul_f32 v[164:165], v[124:125], v[124:125]
	v_lshl_add_u64 v[160:161], v[138:139], 1, s[18:19]
	v_cvt_pk_bf16_f32 v122, v126, v127
	v_cvt_pk_bf16_f32 v123, v128, v129
	v_cvt_pk_bf16_f32 v124, v162, v163
	v_cvt_pk_bf16_f32 v125, v164, v165
	v_max_f32_e32 v114, 0, v114
	v_max_f32_e32 v115, 0, v115
	global_store_dwordx4 v[160:161], v[122:125], off
	v_max_f32_e32 v118, v118, v118
	v_max_f32_e32 v119, v119, v119
	v_pk_mul_f32 v[122:123], v[114:115], v[114:115]
	v_max_f32_e32 v115, v116, v116
	v_max_f32_e32 v114, v120, v120
	v_max_f32_e32 v116, 0, v115
	v_max_f32_e32 v115, v121, v121
	v_max_f32_e32 v118, 0, v118
	v_max_f32_e32 v119, 0, v119
	v_max_f32_e32 v114, 0, v114
	v_max_f32_e32 v115, 0, v115
	v_max_f32_e32 v117, 0, v117
	v_pk_mul_f32 v[118:119], v[118:119], v[118:119]
	v_pk_mul_f32 v[120:121], v[114:115], v[114:115]
	v_pk_mul_f32 v[124:125], v[116:117], v[116:117]
	v_cvt_pk_bf16_f32 v114, v118, v119
	v_cvt_pk_bf16_f32 v115, v120, v121
	v_cvt_pk_bf16_f32 v116, v122, v123
	v_cvt_pk_bf16_f32 v117, v124, v125
	v_max_f32_e32 v106, 0, v106
	v_max_f32_e32 v107, 0, v107
	global_store_dwordx4 v[160:161], v[114:117], off offset:256
	v_max_f32_e32 v110, v110, v110
	v_max_f32_e32 v111, v111, v111
	v_pk_mul_f32 v[116:117], v[106:107], v[106:107]
	v_max_f32_e32 v107, v108, v108
	v_max_f32_e32 v106, v112, v112
	v_max_f32_e32 v108, 0, v107
	v_max_f32_e32 v107, v113, v113
	v_max_f32_e32 v110, 0, v110
	v_max_f32_e32 v111, 0, v111
	v_max_f32_e32 v106, 0, v106
	v_max_f32_e32 v107, 0, v107
	v_max_f32_e32 v109, 0, v109
	v_pk_mul_f32 v[110:111], v[110:111], v[110:111]
	v_pk_mul_f32 v[112:113], v[106:107], v[106:107]
	v_pk_mul_f32 v[118:119], v[108:109], v[108:109]
	v_lshl_add_u64 v[114:115], v[140:141], 1, s[18:19]
	v_cvt_pk_bf16_f32 v106, v110, v111
	v_cvt_pk_bf16_f32 v107, v112, v113
	v_cvt_pk_bf16_f32 v108, v116, v117
	v_cvt_pk_bf16_f32 v109, v118, v119
	v_max_f32_e32 v98, 0, v98
	v_max_f32_e32 v99, 0, v99
	global_store_dwordx4 v[114:115], v[106:109], off
	v_max_f32_e32 v102, v102, v102
	v_max_f32_e32 v103, v103, v103
	v_pk_mul_f32 v[106:107], v[98:99], v[98:99]
	v_max_f32_e32 v99, v100, v100
	v_max_f32_e32 v98, v104, v104
	v_max_f32_e32 v100, 0, v99
	v_max_f32_e32 v99, v105, v105
	v_max_f32_e32 v102, 0, v102
	v_max_f32_e32 v103, 0, v103
	v_max_f32_e32 v98, 0, v98
	v_max_f32_e32 v99, 0, v99
	v_max_f32_e32 v101, 0, v101
	v_pk_mul_f32 v[102:103], v[102:103], v[102:103]
	v_pk_mul_f32 v[104:105], v[98:99], v[98:99]
	v_pk_mul_f32 v[108:109], v[100:101], v[100:101]
	v_cvt_pk_bf16_f32 v98, v102, v103
	v_cvt_pk_bf16_f32 v99, v104, v105
	v_cvt_pk_bf16_f32 v100, v106, v107
	v_cvt_pk_bf16_f32 v101, v108, v109
	v_max_f32_e32 v90, 0, v90
	v_max_f32_e32 v91, 0, v91
	global_store_dwordx4 v[114:115], v[98:101], off offset:256
	v_max_f32_e32 v94, v94, v94
	v_max_f32_e32 v95, v95, v95
	v_pk_mul_f32 v[100:101], v[90:91], v[90:91]
	v_max_f32_e32 v91, v92, v92
	v_max_f32_e32 v90, v96, v96
	v_max_f32_e32 v92, 0, v91
	v_max_f32_e32 v91, v97, v97
	v_max_f32_e32 v94, 0, v94
	v_max_f32_e32 v95, 0, v95
	v_max_f32_e32 v90, 0, v90
	v_max_f32_e32 v91, 0, v91
	v_max_f32_e32 v93, 0, v93
	v_pk_mul_f32 v[94:95], v[94:95], v[94:95]
	v_pk_mul_f32 v[96:97], v[90:91], v[90:91]
	v_pk_mul_f32 v[102:103], v[92:93], v[92:93]
	v_lshl_add_u64 v[98:99], v[142:143], 1, s[18:19]
	v_cvt_pk_bf16_f32 v90, v94, v95
	v_cvt_pk_bf16_f32 v91, v96, v97
	v_cvt_pk_bf16_f32 v92, v100, v101
	v_cvt_pk_bf16_f32 v93, v102, v103
	v_max_f32_e32 v82, 0, v82
	v_max_f32_e32 v83, 0, v83
	global_store_dwordx4 v[98:99], v[90:93], off
	v_max_f32_e32 v86, v86, v86
	v_max_f32_e32 v87, v87, v87
	v_pk_mul_f32 v[90:91], v[82:83], v[82:83]
	v_max_f32_e32 v83, v84, v84
	v_max_f32_e32 v82, v88, v88
	v_max_f32_e32 v84, 0, v83
	v_max_f32_e32 v83, v89, v89
	v_max_f32_e32 v86, 0, v86
	v_max_f32_e32 v87, 0, v87
	v_max_f32_e32 v82, 0, v82
	v_max_f32_e32 v83, 0, v83
	v_max_f32_e32 v85, 0, v85
	v_pk_mul_f32 v[86:87], v[86:87], v[86:87]
	v_pk_mul_f32 v[88:89], v[82:83], v[82:83]
	v_pk_mul_f32 v[92:93], v[84:85], v[84:85]
	v_cvt_pk_bf16_f32 v82, v86, v87
	v_cvt_pk_bf16_f32 v83, v88, v89
	v_cvt_pk_bf16_f32 v84, v90, v91
	v_cvt_pk_bf16_f32 v85, v92, v93
	v_max_f32_e32 v74, 0, v74
	v_max_f32_e32 v75, 0, v75
	global_store_dwordx4 v[98:99], v[82:85], off offset:256
	v_max_f32_e32 v78, v78, v78
	v_max_f32_e32 v79, v79, v79
	v_pk_mul_f32 v[84:85], v[74:75], v[74:75]
	v_max_f32_e32 v75, v76, v76
	v_max_f32_e32 v74, v80, v80
	v_max_f32_e32 v76, 0, v75
	v_max_f32_e32 v75, v81, v81
	v_max_f32_e32 v78, 0, v78
	v_max_f32_e32 v79, 0, v79
	v_max_f32_e32 v74, 0, v74
	v_max_f32_e32 v75, 0, v75
	v_max_f32_e32 v77, 0, v77
	v_pk_mul_f32 v[78:79], v[78:79], v[78:79]
	v_pk_mul_f32 v[80:81], v[74:75], v[74:75]
	v_pk_mul_f32 v[86:87], v[76:77], v[76:77]
	v_lshl_add_u64 v[82:83], v[144:145], 1, s[18:19]
	v_cvt_pk_bf16_f32 v74, v78, v79
	v_cvt_pk_bf16_f32 v75, v80, v81
	v_cvt_pk_bf16_f32 v76, v84, v85
	v_cvt_pk_bf16_f32 v77, v86, v87
	v_max_f32_e32 v66, 0, v66
	v_max_f32_e32 v67, 0, v67
	global_store_dwordx4 v[82:83], v[74:77], off
	v_max_f32_e32 v70, v70, v70
	v_max_f32_e32 v71, v71, v71
	v_pk_mul_f32 v[74:75], v[66:67], v[66:67]
	v_max_f32_e32 v67, v68, v68
	v_max_f32_e32 v66, v72, v72
	v_max_f32_e32 v68, 0, v67
	v_max_f32_e32 v67, v73, v73
	v_max_f32_e32 v70, 0, v70
	v_max_f32_e32 v71, 0, v71
	v_max_f32_e32 v66, 0, v66
	v_max_f32_e32 v67, 0, v67
	v_max_f32_e32 v69, 0, v69
	v_pk_mul_f32 v[70:71], v[70:71], v[70:71]
	v_pk_mul_f32 v[72:73], v[66:67], v[66:67]
	v_pk_mul_f32 v[76:77], v[68:69], v[68:69]
	v_cvt_pk_bf16_f32 v66, v70, v71
	v_cvt_pk_bf16_f32 v67, v72, v73
	v_cvt_pk_bf16_f32 v68, v74, v75
	v_cvt_pk_bf16_f32 v69, v76, v77
	v_max_f32_e32 v58, 0, v58
	v_max_f32_e32 v59, 0, v59
	global_store_dwordx4 v[82:83], v[66:69], off offset:256
	v_max_f32_e32 v62, v62, v62
	v_max_f32_e32 v63, v63, v63
	v_pk_mul_f32 v[68:69], v[58:59], v[58:59]
	v_max_f32_e32 v59, v60, v60
	v_max_f32_e32 v58, v64, v64
	v_max_f32_e32 v60, 0, v59
	v_max_f32_e32 v59, v65, v65
	v_max_f32_e32 v62, 0, v62
	v_max_f32_e32 v63, 0, v63
	v_max_f32_e32 v58, 0, v58
	v_max_f32_e32 v59, 0, v59
	v_max_f32_e32 v61, 0, v61
	v_pk_mul_f32 v[62:63], v[62:63], v[62:63]
	v_pk_mul_f32 v[64:65], v[58:59], v[58:59]
	v_pk_mul_f32 v[70:71], v[60:61], v[60:61]
	v_lshl_add_u64 v[66:67], v[146:147], 1, s[18:19]
	v_cvt_pk_bf16_f32 v58, v62, v63
	v_cvt_pk_bf16_f32 v59, v64, v65
	v_cvt_pk_bf16_f32 v60, v68, v69
	v_cvt_pk_bf16_f32 v61, v70, v71
	v_max_f32_e32 v50, 0, v50
	v_max_f32_e32 v51, 0, v51
	global_store_dwordx4 v[66:67], v[58:61], off
	v_max_f32_e32 v54, v54, v54
	v_max_f32_e32 v55, v55, v55
	v_pk_mul_f32 v[58:59], v[50:51], v[50:51]
	v_max_f32_e32 v51, v52, v52
	v_max_f32_e32 v50, v56, v56
	v_max_f32_e32 v52, 0, v51
	v_max_f32_e32 v51, v57, v57
	v_max_f32_e32 v54, 0, v54
	v_max_f32_e32 v55, 0, v55
	v_max_f32_e32 v50, 0, v50
	v_max_f32_e32 v51, 0, v51
	v_max_f32_e32 v53, 0, v53
	v_pk_mul_f32 v[54:55], v[54:55], v[54:55]
	v_pk_mul_f32 v[56:57], v[50:51], v[50:51]
	v_pk_mul_f32 v[60:61], v[52:53], v[52:53]
	v_cvt_pk_bf16_f32 v50, v54, v55
	v_cvt_pk_bf16_f32 v51, v56, v57
	v_cvt_pk_bf16_f32 v52, v58, v59
	v_cvt_pk_bf16_f32 v53, v60, v61
	v_max_f32_e32 v42, 0, v42
	v_max_f32_e32 v43, 0, v43
	global_store_dwordx4 v[66:67], v[50:53], off offset:256
	v_max_f32_e32 v46, v46, v46
	v_max_f32_e32 v47, v47, v47
	v_pk_mul_f32 v[52:53], v[42:43], v[42:43]
	v_max_f32_e32 v43, v44, v44
	v_max_f32_e32 v42, v48, v48
	v_max_f32_e32 v44, 0, v43
	v_max_f32_e32 v43, v49, v49
	v_max_f32_e32 v46, 0, v46
	v_max_f32_e32 v47, 0, v47
	v_max_f32_e32 v42, 0, v42
	v_max_f32_e32 v43, 0, v43
	v_max_f32_e32 v45, 0, v45
	v_pk_mul_f32 v[46:47], v[46:47], v[46:47]
	v_pk_mul_f32 v[48:49], v[42:43], v[42:43]
	v_pk_mul_f32 v[54:55], v[44:45], v[44:45]
	v_lshl_add_u64 v[50:51], v[148:149], 1, s[18:19]
	v_cvt_pk_bf16_f32 v42, v46, v47
	v_cvt_pk_bf16_f32 v43, v48, v49
	v_cvt_pk_bf16_f32 v44, v52, v53
	v_cvt_pk_bf16_f32 v45, v54, v55
	v_max_f32_e32 v34, 0, v34
	v_max_f32_e32 v35, 0, v35
	global_store_dwordx4 v[50:51], v[42:45], off
	v_max_f32_e32 v38, v38, v38
	v_max_f32_e32 v39, v39, v39
	v_pk_mul_f32 v[42:43], v[34:35], v[34:35]
	v_max_f32_e32 v35, v36, v36
	v_max_f32_e32 v34, v40, v40
	v_max_f32_e32 v36, 0, v35
	v_max_f32_e32 v35, v41, v41
	v_max_f32_e32 v38, 0, v38
	v_max_f32_e32 v39, 0, v39
	v_max_f32_e32 v34, 0, v34
	v_max_f32_e32 v35, 0, v35
	v_max_f32_e32 v37, 0, v37
	v_pk_mul_f32 v[38:39], v[38:39], v[38:39]
	v_pk_mul_f32 v[40:41], v[34:35], v[34:35]
	v_pk_mul_f32 v[44:45], v[36:37], v[36:37]
	v_cvt_pk_bf16_f32 v34, v38, v39
	v_cvt_pk_bf16_f32 v35, v40, v41
	v_cvt_pk_bf16_f32 v36, v42, v43
	v_cvt_pk_bf16_f32 v37, v44, v45
	v_max_f32_e32 v26, 0, v26
	v_max_f32_e32 v27, 0, v27
	global_store_dwordx4 v[50:51], v[34:37], off offset:256
	v_max_f32_e32 v30, v30, v30
	v_max_f32_e32 v31, v31, v31
	v_pk_mul_f32 v[36:37], v[26:27], v[26:27]
	v_max_f32_e32 v27, v28, v28
	v_max_f32_e32 v26, v32, v32
	v_max_f32_e32 v28, 0, v27
	v_max_f32_e32 v27, v33, v33
	v_max_f32_e32 v30, 0, v30
	v_max_f32_e32 v31, 0, v31
	v_max_f32_e32 v26, 0, v26
	v_max_f32_e32 v27, 0, v27
	v_max_f32_e32 v29, 0, v29
	v_pk_mul_f32 v[30:31], v[30:31], v[30:31]
	v_pk_mul_f32 v[32:33], v[26:27], v[26:27]
	v_pk_mul_f32 v[38:39], v[28:29], v[28:29]
	v_lshl_add_u64 v[34:35], v[150:151], 1, s[18:19]
	v_cvt_pk_bf16_f32 v26, v30, v31
	v_cvt_pk_bf16_f32 v27, v32, v33
	v_cvt_pk_bf16_f32 v28, v36, v37
	v_cvt_pk_bf16_f32 v29, v38, v39
	v_max_f32_e32 v18, 0, v18
	v_max_f32_e32 v19, 0, v19
	global_store_dwordx4 v[34:35], v[26:29], off
	v_max_f32_e32 v22, v22, v22
	v_max_f32_e32 v23, v23, v23
	v_pk_mul_f32 v[26:27], v[18:19], v[18:19]
	v_max_f32_e32 v19, v20, v20
	v_max_f32_e32 v18, v24, v24
	v_max_f32_e32 v20, 0, v19
	v_max_f32_e32 v19, v25, v25
	v_max_f32_e32 v22, 0, v22
	v_max_f32_e32 v23, 0, v23
	v_max_f32_e32 v18, 0, v18
	v_max_f32_e32 v19, 0, v19
	v_max_f32_e32 v21, 0, v21
	v_pk_mul_f32 v[22:23], v[22:23], v[22:23]
	v_pk_mul_f32 v[24:25], v[18:19], v[18:19]
	v_pk_mul_f32 v[28:29], v[20:21], v[20:21]
	v_cvt_pk_bf16_f32 v18, v22, v23
	v_cvt_pk_bf16_f32 v19, v24, v25
	v_cvt_pk_bf16_f32 v20, v26, v27
	v_cvt_pk_bf16_f32 v21, v28, v29
	v_max_f32_e32 v10, 0, v10
	v_max_f32_e32 v11, 0, v11
	global_store_dwordx4 v[34:35], v[18:21], off offset:256
	v_max_f32_e32 v14, v14, v14
	v_max_f32_e32 v15, v15, v15
	v_pk_mul_f32 v[20:21], v[10:11], v[10:11]
	v_max_f32_e32 v11, v12, v12
	v_max_f32_e32 v10, v16, v16
	v_max_f32_e32 v12, 0, v11
	v_max_f32_e32 v11, v17, v17
	v_max_f32_e32 v14, 0, v14
	v_max_f32_e32 v15, 0, v15
	v_max_f32_e32 v10, 0, v10
	v_max_f32_e32 v11, 0, v11
	v_max_f32_e32 v13, 0, v13
	v_pk_mul_f32 v[14:15], v[14:15], v[14:15]
	v_pk_mul_f32 v[16:17], v[10:11], v[10:11]
	v_pk_mul_f32 v[22:23], v[12:13], v[12:13]
	v_lshl_add_u64 v[18:19], v[152:153], 1, s[18:19]
	v_cvt_pk_bf16_f32 v10, v14, v15
	v_cvt_pk_bf16_f32 v11, v16, v17
	v_cvt_pk_bf16_f32 v12, v20, v21
	v_cvt_pk_bf16_f32 v13, v22, v23
	v_max_f32_e32 v2, 0, v2
	v_max_f32_e32 v3, 0, v3
	global_store_dwordx4 v[18:19], v[10:13], off
	v_max_f32_e32 v6, v6, v6
	v_max_f32_e32 v7, v7, v7
	v_pk_mul_f32 v[10:11], v[2:3], v[2:3]
	v_max_f32_e32 v3, v4, v4
	v_max_f32_e32 v2, v8, v8
	v_max_f32_e32 v4, 0, v3
	v_max_f32_e32 v3, v9, v9
	v_max_f32_e32 v6, 0, v6
	v_max_f32_e32 v7, 0, v7
	v_max_f32_e32 v2, 0, v2
	v_max_f32_e32 v3, 0, v3
	v_max_f32_e32 v5, 0, v5
	v_pk_mul_f32 v[6:7], v[6:7], v[6:7]
	v_pk_mul_f32 v[8:9], v[2:3], v[2:3]
	v_pk_mul_f32 v[12:13], v[4:5], v[4:5]
	v_cvt_pk_bf16_f32 v2, v6, v7
	v_cvt_pk_bf16_f32 v3, v8, v9
	v_cvt_pk_bf16_f32 v4, v10, v11
	v_cvt_pk_bf16_f32 v5, v12, v13
	s_and_b64 vcc, exec, s[0:1]
	s_mov_b32 s51, s30
	s_mov_b32 s52, s38
	s_mov_b64 s[20:21], s[80:81]
	s_mov_b64 s[18:19], s[42:43]
	global_store_dwordx4 v[18:19], v[2:5], off offset:256
	s_cbranch_vccz .LBB0_742
	s_waitcnt vmcnt(0)
	v_readlane_b32 s38, v255, 28
	s_cmpk_gt_u32 s26, 0xff
	v_readlane_b32 s39, v255, 29
	v_readlane_b32 s42, v255, 32
	s_cbranch_scc1 .LBB0_753
	s_barrier

.LBB0_814:
	s_add_i32 s22, s55, 0xffff0000
	s_and_b32 s22, s22, 0x3e0000
	s_and_b32 s23, s90, 0x100
	s_or_b32 s56, s23, s22
	s_and_b32 s22, s55, 0x7e0000
	s_add_u32 vcc_lo, s90, 0x100
	s_addc_u32 vcc_hi, s91, 0
	s_and_b32 s23, vcc_lo, 0x100
	s_or_b32 s22, s22, s23
	s_add_u32 s22, s84, s22
	s_addc_u32 s23, s85, 0
	s_add_u32 s57, s30, s90
	s_addc_u32 s58, s31, s91
	s_add_u32 s57, s57, 0x100
	s_addc_u32 s58, s58, 0
	s_add_i32 s59, 0, 0x10000
	s_cmpk_eq_i32 s54, 0x7c
	s_cselect_b32 s91, s43, s58
	s_cselect_b32 s90, s53, s57
	s_cselect_b32 s23, s51, s23
	s_cselect_b32 s22, s52, s22
	s_add_u32 s56, s84, s56
	s_addc_u32 s57, s85, 0
	s_add_u32 s56, s56, 0x10080
	s_addc_u32 s57, s57, 0
	v_lshl_add_u64 v[204:205], s[56:57], 0, v[136:137]
	s_add_i32 m0, s28, 0xc000
	ds_read_b128 v[158:161], v140
	ds_read_b128 v[162:165], v140 offset:1024
	ds_read_b128 v[168:171], v140 offset:2048
	ds_read_b128 v[172:175], v140 offset:3072
	ds_read_b128 v[176:179], v140 offset:4096
	ds_read_b128 v[192:195], v140 offset:5120
	ds_read_b128 v[196:199], v140 offset:6144
	ds_read_b128 v[200:203], v140 offset:7168
	global_load_lds_dwordx4 v[204:205], off
	s_add_i32 m0, s28, 0xe000
	v_lshl_add_u64 v[204:205], s[56:57], 0, v[132:133]
	global_load_lds_dwordx4 v[204:205], off
	s_barrier
	s_waitcnt lgkmcnt(0)
	v_mfma_f32_16x16x32_bf16 v[86:89], v[142:145], v[158:161], v[86:89]
	v_mfma_f32_16x16x32_bf16 v[94:97], v[150:153], v[158:161], v[94:97]
	v_mfma_f32_16x16x32_bf16 v[98:101], v[142:145], v[168:171], v[98:101]
	v_mfma_f32_16x16x32_bf16 v[102:105], v[150:153], v[168:171], v[102:105]
	v_mfma_f32_16x16x32_bf16 v[114:117], v[142:145], v[176:179], v[114:117]
	v_mfma_f32_16x16x32_bf16 v[122:125], v[150:153], v[176:179], v[122:125]
	v_mfma_f32_16x16x32_bf16 v[126:129], v[142:145], v[196:199], v[126:129]
	v_mfma_f32_16x16x32_bf16 v[118:121], v[150:153], v[196:199], v[118:121]
	v_mfma_f32_16x16x32_bf16 v[86:89], v[146:149], v[162:165], v[86:89]
	v_mfma_f32_16x16x32_bf16 v[94:97], v[154:157], v[162:165], v[94:97]
	v_mfma_f32_16x16x32_bf16 v[98:101], v[146:149], v[172:175], v[98:101]
	v_mfma_f32_16x16x32_bf16 v[102:105], v[154:157], v[172:175], v[102:105]
	v_mfma_f32_16x16x32_bf16 v[114:117], v[146:149], v[192:195], v[114:117]
	v_mfma_f32_16x16x32_bf16 v[122:125], v[154:157], v[192:195], v[122:125]
	v_mfma_f32_16x16x32_bf16 v[126:129], v[146:149], v[200:203], v[126:129]
	v_mfma_f32_16x16x32_bf16 v[118:121], v[154:157], v[200:203], v[118:121]
	s_barrier
	s_add_i32 s58, 0, 0x14000
	s_add_i32 s56, s59, s81
	v_add_u32_e32 v141, s58, v139
	v_lshl_add_u64 v[212:213], s[90:91], 0, v[134:135]
	s_mov_b32 m0, s56
	ds_read_b128 v[204:207], v141
	ds_read_b128 v[208:211], v141 offset:1024
	ds_read_b128 v[224:227], v141 offset:2048
	ds_read_b128 v[228:231], v141 offset:3072
	global_load_lds_dwordx4 v[212:213], off
	s_add_i32 m0, s56, 0x2000
	v_lshl_add_u64 v[222:223], s[90:91], 0, v[130:131]
	global_load_lds_dwordx4 v[222:223], off
	s_mov_b32 m0, s28
	v_lshl_add_u64 v[232:233], s[22:23], 0, v[136:137]
	s_waitcnt lgkmcnt(0)
	s_barrier
	v_mfma_f32_16x16x32_bf16 v[2:5], v[204:207], v[158:161], v[2:5]
	v_mfma_f32_16x16x32_bf16 v[6:9], v[224:227], v[158:161], v[6:9]
	v_mfma_f32_16x16x32_bf16 v[10:13], v[204:207], v[168:171], v[10:13]
	v_mfma_f32_16x16x32_bf16 v[14:17], v[224:227], v[168:171], v[14:17]
	v_mfma_f32_16x16x32_bf16 v[22:25], v[204:207], v[176:179], v[22:25]
	v_mfma_f32_16x16x32_bf16 v[18:21], v[224:227], v[176:179], v[18:21]
	v_mfma_f32_16x16x32_bf16 v[30:33], v[204:207], v[196:199], v[30:33]
	v_mfma_f32_16x16x32_bf16 v[26:29], v[224:227], v[196:199], v[26:29]
	v_mfma_f32_16x16x32_bf16 v[2:5], v[208:211], v[162:165], v[2:5]
	v_mfma_f32_16x16x32_bf16 v[6:9], v[228:231], v[162:165], v[6:9]
	v_mfma_f32_16x16x32_bf16 v[10:13], v[208:211], v[172:175], v[10:13]
	v_mfma_f32_16x16x32_bf16 v[14:17], v[228:231], v[172:175], v[14:17]
	v_mfma_f32_16x16x32_bf16 v[22:25], v[208:211], v[192:195], v[22:25]
	v_mfma_f32_16x16x32_bf16 v[18:21], v[228:231], v[192:195], v[18:21]
	v_mfma_f32_16x16x32_bf16 v[30:33], v[208:211], v[200:203], v[30:33]
	v_mfma_f32_16x16x32_bf16 v[26:29], v[228:231], v[200:203], v[26:29]
	s_barrier
	ds_read_b128 v[158:161], v140 offset:16384
	ds_read_b128 v[162:165], v140 offset:17408
	ds_read_b128 v[168:171], v140 offset:18432
	ds_read_b128 v[172:175], v140 offset:19456
	ds_read_b128 v[176:179], v140 offset:20480
	ds_read_b128 v[192:195], v140 offset:21504
	ds_read_b128 v[196:199], v140 offset:22528
	ds_read_b128 v[200:203], v140 offset:23552
	global_load_lds_dwordx4 v[232:233], off
	s_mov_b32 m0, s29
	v_lshl_add_u64 v[234:235], s[22:23], 0, v[132:133]
	global_load_lds_dwordx4 v[234:235], off
	s_waitcnt vmcnt(10)
	s_waitcnt lgkmcnt(0)
	s_barrier
	v_mfma_f32_16x16x32_bf16 v[110:113], v[142:145], v[158:161], v[110:113]
	v_mfma_f32_16x16x32_bf16 v[106:109], v[150:153], v[158:161], v[106:109]
	v_mfma_f32_16x16x32_bf16 v[90:93], v[142:145], v[168:171], v[90:93]
	v_mfma_f32_16x16x32_bf16 v[82:85], v[150:153], v[168:171], v[82:85]
	v_mfma_f32_16x16x32_bf16 v[78:81], v[142:145], v[176:179], v[78:81]
	v_mfma_f32_16x16x32_bf16 v[74:77], v[150:153], v[176:179], v[74:77]
	v_mfma_f32_16x16x32_bf16 v[70:73], v[142:145], v[196:199], v[70:73]
	v_mfma_f32_16x16x32_bf16 v[66:69], v[150:153], v[196:199], v[66:69]
	v_mfma_f32_16x16x32_bf16 v[110:113], v[146:149], v[162:165], v[110:113]
	v_mfma_f32_16x16x32_bf16 v[106:109], v[154:157], v[162:165], v[106:109]
	v_mfma_f32_16x16x32_bf16 v[90:93], v[146:149], v[172:175], v[90:93]
	v_mfma_f32_16x16x32_bf16 v[82:85], v[154:157], v[172:175], v[82:85]
	v_mfma_f32_16x16x32_bf16 v[78:81], v[146:149], v[192:195], v[78:81]
	v_mfma_f32_16x16x32_bf16 v[74:77], v[154:157], v[192:195], v[74:77]
	v_mfma_f32_16x16x32_bf16 v[70:73], v[146:149], v[200:203], v[70:73]
	v_mfma_f32_16x16x32_bf16 v[66:69], v[154:157], v[200:203], v[66:69]
	s_barrier
	s_add_u32 s56, s90, 0x200000
	s_addc_u32 s57, s91, 0
	s_add_i32 s58, s58, s81
	s_mov_b32 m0, s58
	v_lshl_add_u64 v[142:143], s[56:57], 0, v[134:135]
	global_load_lds_dwordx4 v[142:143], off
	s_add_i32 m0, s58, 0x2000
	v_lshl_add_u64 v[142:143], s[56:57], 0, v[130:131]
	global_load_lds_dwordx4 v[142:143], off
	v_add_u32_e32 v141, 0x18000, v139
	ds_read_b128 v[142:145], v141
	ds_read_b128 v[146:149], v141 offset:1024
	ds_read_b128 v[150:153], v141 offset:2048
	ds_read_b128 v[154:157], v141 offset:3072
	s_add_i32 s56, 0, 0x18000
	s_waitcnt vmcnt(6)
	s_barrier
	v_mfma_f32_16x16x32_bf16 v[38:41], v[204:207], v[158:161], v[38:41]
	v_mfma_f32_16x16x32_bf16 v[34:37], v[224:227], v[158:161], v[34:37]
	v_mfma_f32_16x16x32_bf16 v[46:49], v[204:207], v[168:171], v[46:49]
	v_mfma_f32_16x16x32_bf16 v[42:45], v[224:227], v[168:171], v[42:45]
	v_mfma_f32_16x16x32_bf16 v[54:57], v[204:207], v[176:179], v[54:57]
	v_mfma_f32_16x16x32_bf16 v[50:53], v[224:227], v[176:179], v[50:53]
	v_mfma_f32_16x16x32_bf16 v[62:65], v[204:207], v[196:199], v[62:65]
	v_mfma_f32_16x16x32_bf16 v[58:61], v[224:227], v[196:199], v[58:61]
	v_mfma_f32_16x16x32_bf16 v[38:41], v[208:211], v[162:165], v[38:41]
	v_mfma_f32_16x16x32_bf16 v[34:37], v[228:231], v[162:165], v[34:37]
	v_mfma_f32_16x16x32_bf16 v[46:49], v[208:211], v[172:175], v[46:49]
	v_mfma_f32_16x16x32_bf16 v[42:45], v[228:231], v[172:175], v[42:45]
	v_mfma_f32_16x16x32_bf16 v[54:57], v[208:211], v[192:195], v[54:57]
	v_mfma_f32_16x16x32_bf16 v[50:53], v[228:231], v[192:195], v[50:53]
	v_mfma_f32_16x16x32_bf16 v[62:65], v[208:211], v[200:203], v[62:65]
	v_mfma_f32_16x16x32_bf16 v[58:61], v[228:231], v[200:203], v[58:61]
	s_barrier
	s_add_u32 s22, s22, 0x10000
	s_addc_u32 s23, s23, 0
	s_mov_b32 m0, s44
	v_lshl_add_u64 v[204:205], s[22:23], 0, v[136:137]
	ds_read_b128 v[158:161], v140 offset:32768
	ds_read_b128 v[162:165], v140 offset:33792
	ds_read_b128 v[168:171], v140 offset:34816
	ds_read_b128 v[172:175], v140 offset:35840
	ds_read_b128 v[176:179], v140 offset:36864
	ds_read_b128 v[192:195], v140 offset:37888
	ds_read_b128 v[196:199], v140 offset:38912
	ds_read_b128 v[200:203], v140 offset:39936
	global_load_lds_dwordx4 v[204:205], off
	s_mov_b32 m0, s45
	v_lshl_add_u64 v[204:205], s[22:23], 0, v[132:133]
	global_load_lds_dwordx4 v[204:205], off
	s_barrier
	s_waitcnt lgkmcnt(0)
	v_mfma_f32_16x16x32_bf16 v[86:89], v[142:145], v[158:161], v[86:89]
	v_mfma_f32_16x16x32_bf16 v[94:97], v[150:153], v[158:161], v[94:97]
	v_mfma_f32_16x16x32_bf16 v[98:101], v[142:145], v[168:171], v[98:101]
	v_mfma_f32_16x16x32_bf16 v[102:105], v[150:153], v[168:171], v[102:105]
	v_mfma_f32_16x16x32_bf16 v[114:117], v[142:145], v[176:179], v[114:117]
	v_mfma_f32_16x16x32_bf16 v[122:125], v[150:153], v[176:179], v[122:125]
	v_mfma_f32_16x16x32_bf16 v[126:129], v[142:145], v[196:199], v[126:129]
	v_mfma_f32_16x16x32_bf16 v[118:121], v[150:153], v[196:199], v[118:121]
	v_mfma_f32_16x16x32_bf16 v[86:89], v[146:149], v[162:165], v[86:89]
	v_mfma_f32_16x16x32_bf16 v[94:97], v[154:157], v[162:165], v[94:97]
	v_mfma_f32_16x16x32_bf16 v[98:101], v[146:149], v[172:175], v[98:101]
	v_mfma_f32_16x16x32_bf16 v[102:105], v[154:157], v[172:175], v[102:105]
	v_mfma_f32_16x16x32_bf16 v[114:117], v[146:149], v[192:195], v[114:117]
	v_mfma_f32_16x16x32_bf16 v[122:125], v[154:157], v[192:195], v[122:125]
	v_mfma_f32_16x16x32_bf16 v[126:129], v[146:149], v[200:203], v[126:129]
	v_mfma_f32_16x16x32_bf16 v[118:121], v[154:157], v[200:203], v[118:121]
	s_barrier
	s_add_i32 s57, 0, 0x1c000
	s_add_i32 s22, s56, s81
	v_add_u32_e32 v141, s57, v139
	v_lshl_add_u64 v[212:213], v[212:213], 0, s[78:79]
	s_mov_b32 m0, s22
	ds_read_b128 v[204:207], v141
	ds_read_b128 v[208:211], v141 offset:1024
	ds_read_b128 v[224:227], v141 offset:2048
	ds_read_b128 v[228:231], v141 offset:3072
	global_load_lds_dwordx4 v[212:213], off
	s_add_i32 m0, s22, 0x2000
	v_lshl_add_u64 v[212:213], v[222:223], 0, s[78:79]
	global_load_lds_dwordx4 v[212:213], off
	s_mov_b32 m0, s47
	v_lshl_add_u64 v[212:213], v[232:233], 0, s[78:79]
	s_waitcnt lgkmcnt(0)
	s_barrier
	v_mfma_f32_16x16x32_bf16 v[2:5], v[204:207], v[158:161], v[2:5]
	v_mfma_f32_16x16x32_bf16 v[6:9], v[224:227], v[158:161], v[6:9]
	v_mfma_f32_16x16x32_bf16 v[10:13], v[204:207], v[168:171], v[10:13]
	v_mfma_f32_16x16x32_bf16 v[14:17], v[224:227], v[168:171], v[14:17]
	v_mfma_f32_16x16x32_bf16 v[22:25], v[204:207], v[176:179], v[22:25]
	v_mfma_f32_16x16x32_bf16 v[18:21], v[224:227], v[176:179], v[18:21]
	v_mfma_f32_16x16x32_bf16 v[30:33], v[204:207], v[196:199], v[30:33]
	v_mfma_f32_16x16x32_bf16 v[26:29], v[224:227], v[196:199], v[26:29]
	v_mfma_f32_16x16x32_bf16 v[2:5], v[208:211], v[162:165], v[2:5]
	v_mfma_f32_16x16x32_bf16 v[6:9], v[228:231], v[162:165], v[6:9]
	v_mfma_f32_16x16x32_bf16 v[10:13], v[208:211], v[172:175], v[10:13]
	v_mfma_f32_16x16x32_bf16 v[14:17], v[228:231], v[172:175], v[14:17]
	v_mfma_f32_16x16x32_bf16 v[22:25], v[208:211], v[192:195], v[22:25]
	v_mfma_f32_16x16x32_bf16 v[18:21], v[228:231], v[192:195], v[18:21]
	v_mfma_f32_16x16x32_bf16 v[30:33], v[208:211], v[200:203], v[30:33]
	v_mfma_f32_16x16x32_bf16 v[26:29], v[228:231], v[200:203], v[26:29]
	s_barrier
	ds_read_b128 v[158:161], v140 offset:49152
	ds_read_b128 v[162:165], v140 offset:50176
	ds_read_b128 v[168:171], v140 offset:51200
	ds_read_b128 v[172:175], v140 offset:52224
	ds_read_b128 v[176:179], v140 offset:53248
	ds_read_b128 v[192:195], v140 offset:54272
	ds_read_b128 v[196:199], v140 offset:55296
	ds_read_b128 v[200:203], v140 offset:56320
	global_load_lds_dwordx4 v[212:213], off
	s_mov_b32 m0, s48
	v_lshl_add_u64 v[212:213], v[234:235], 0, s[78:79]
	global_load_lds_dwordx4 v[212:213], off
	s_waitcnt vmcnt(10)
	s_waitcnt lgkmcnt(0)
	s_barrier
	v_mfma_f32_16x16x32_bf16 v[110:113], v[142:145], v[158:161], v[110:113]
	v_mfma_f32_16x16x32_bf16 v[106:109], v[150:153], v[158:161], v[106:109]
	v_mfma_f32_16x16x32_bf16 v[90:93], v[142:145], v[168:171], v[90:93]
	v_mfma_f32_16x16x32_bf16 v[82:85], v[150:153], v[168:171], v[82:85]
	v_mfma_f32_16x16x32_bf16 v[78:81], v[142:145], v[176:179], v[78:81]
	v_mfma_f32_16x16x32_bf16 v[74:77], v[150:153], v[176:179], v[74:77]
	v_mfma_f32_16x16x32_bf16 v[70:73], v[142:145], v[196:199], v[70:73]
	v_mfma_f32_16x16x32_bf16 v[66:69], v[150:153], v[196:199], v[66:69]
	v_mfma_f32_16x16x32_bf16 v[110:113], v[146:149], v[162:165], v[110:113]
	v_mfma_f32_16x16x32_bf16 v[106:109], v[154:157], v[162:165], v[106:109]
	v_mfma_f32_16x16x32_bf16 v[90:93], v[146:149], v[172:175], v[90:93]
	v_mfma_f32_16x16x32_bf16 v[82:85], v[154:157], v[172:175], v[82:85]
	v_mfma_f32_16x16x32_bf16 v[78:81], v[146:149], v[192:195], v[78:81]
	v_mfma_f32_16x16x32_bf16 v[74:77], v[154:157], v[192:195], v[74:77]
	v_mfma_f32_16x16x32_bf16 v[70:73], v[146:149], v[200:203], v[70:73]
	v_mfma_f32_16x16x32_bf16 v[66:69], v[154:157], v[200:203], v[66:69]
	s_barrier
	s_add_u32 s22, s90, 0x200080
	s_addc_u32 s23, s91, 0
	s_add_i32 s56, s57, s81
	s_mov_b32 m0, s56
	v_lshl_add_u64 v[142:143], s[22:23], 0, v[134:135]
	global_load_lds_dwordx4 v[142:143], off
	s_add_i32 m0, s56, 0x2000
	v_lshl_add_u64 v[142:143], s[22:23], 0, v[130:131]
	global_load_lds_dwordx4 v[142:143], off
	v_add_u32_e32 v141, 0x10000, v139
	ds_read_b128 v[142:145], v141
	ds_read_b128 v[146:149], v141 offset:1024
	ds_read_b128 v[150:153], v141 offset:2048
	ds_read_b128 v[154:157], v141 offset:3072
	s_add_i32 s54, s54, 2
	s_add_i32 s55, s55, 0x10000
	s_cmpk_gt_u32 s54, 0x7d
	s_mov_b64 s[90:91], vcc
	s_waitcnt vmcnt(6)
	s_barrier
	v_mfma_f32_16x16x32_bf16 v[38:41], v[204:207], v[158:161], v[38:41]
	v_mfma_f32_16x16x32_bf16 v[34:37], v[224:227], v[158:161], v[34:37]
	v_mfma_f32_16x16x32_bf16 v[46:49], v[204:207], v[168:171], v[46:49]
	v_mfma_f32_16x16x32_bf16 v[42:45], v[224:227], v[168:171], v[42:45]
	v_mfma_f32_16x16x32_bf16 v[54:57], v[204:207], v[176:179], v[54:57]
	v_mfma_f32_16x16x32_bf16 v[50:53], v[224:227], v[176:179], v[50:53]
	v_mfma_f32_16x16x32_bf16 v[62:65], v[204:207], v[196:199], v[62:65]
	v_mfma_f32_16x16x32_bf16 v[58:61], v[224:227], v[196:199], v[58:61]
	v_mfma_f32_16x16x32_bf16 v[38:41], v[208:211], v[162:165], v[38:41]
	v_mfma_f32_16x16x32_bf16 v[34:37], v[228:231], v[162:165], v[34:37]
	v_mfma_f32_16x16x32_bf16 v[46:49], v[208:211], v[172:175], v[46:49]
	v_mfma_f32_16x16x32_bf16 v[42:45], v[228:231], v[172:175], v[42:45]
	v_mfma_f32_16x16x32_bf16 v[54:57], v[208:211], v[192:195], v[54:57]
	v_mfma_f32_16x16x32_bf16 v[50:53], v[228:231], v[192:195], v[50:53]
	v_mfma_f32_16x16x32_bf16 v[62:65], v[208:211], v[200:203], v[62:65]
	v_mfma_f32_16x16x32_bf16 v[58:61], v[228:231], v[200:203], v[58:61]
	s_barrier
	s_cbranch_scc0 .LBB0_814
	s_waitcnt lgkmcnt(0)
	s_andn2_b64 vcc, exec, s[38:39]
	s_cbranch_vccnz .LBB0_806
	v_mov_b32_e32 v58, 0
	s_mov_b32 s80, s42
	s_mov_b32 s25, s82
	s_mov_b64 s[30:31], s[20:21]
	s_mov_b64 s[84:85], s[18:19]
	s_mov_b32 s49, s50
	v_mov_b32_e32 v59, v58
	v_mov_b32_e32 v60, v58
	v_mov_b32_e32 v61, v58
	v_mov_b32_e32 v62, v58
	v_mov_b32_e32 v63, v58
	v_mov_b32_e32 v64, v58
	v_mov_b32_e32 v65, v58
	v_mov_b32_e32 v50, v58
	v_mov_b32_e32 v51, v58
	v_mov_b32_e32 v52, v58
	v_mov_b32_e32 v53, v58
	v_mov_b32_e32 v54, v58
	v_mov_b32_e32 v55, v58
	v_mov_b32_e32 v56, v58
	v_mov_b32_e32 v57, v58
	v_mov_b32_e32 v42, v58
	v_mov_b32_e32 v43, v58
	v_mov_b32_e32 v44, v58
	v_mov_b32_e32 v45, v58
	v_mov_b32_e32 v46, v58
	v_mov_b32_e32 v47, v58
	v_mov_b32_e32 v48, v58
	v_mov_b32_e32 v49, v58
	v_mov_b32_e32 v34, v58
	v_mov_b32_e32 v35, v58
	v_mov_b32_e32 v36, v58
	v_mov_b32_e32 v37, v58
	v_mov_b32_e32 v38, v58
	v_mov_b32_e32 v39, v58
	v_mov_b32_e32 v40, v58
	v_mov_b32_e32 v41, v58
	v_mov_b32_e32 v66, v58
	v_mov_b32_e32 v67, v58
	v_mov_b32_e32 v68, v58
	v_mov_b32_e32 v69, v58
	v_mov_b32_e32 v70, v58
	v_mov_b32_e32 v71, v58
	v_mov_b32_e32 v72, v58
	v_mov_b32_e32 v73, v58
	v_mov_b32_e32 v74, v58
	v_mov_b32_e32 v75, v58
	v_mov_b32_e32 v76, v58
	v_mov_b32_e32 v77, v58
	v_mov_b32_e32 v78, v58
	v_mov_b32_e32 v79, v58
	v_mov_b32_e32 v80, v58
	v_mov_b32_e32 v81, v58
	v_mov_b32_e32 v82, v58
	v_mov_b32_e32 v83, v58
	v_mov_b32_e32 v84, v58
	v_mov_b32_e32 v85, v58
	v_mov_b32_e32 v90, v58
	v_mov_b32_e32 v91, v58
	v_mov_b32_e32 v92, v58
	v_mov_b32_e32 v93, v58
	v_mov_b32_e32 v106, v58
	v_mov_b32_e32 v107, v58
	v_mov_b32_e32 v108, v58
	v_mov_b32_e32 v109, v58
	v_mov_b32_e32 v110, v58
	v_mov_b32_e32 v111, v58
	v_mov_b32_e32 v112, v58
	v_mov_b32_e32 v113, v58
	v_mov_b32_e32 v26, v58
	v_mov_b32_e32 v27, v58
	v_mov_b32_e32 v28, v58
	v_mov_b32_e32 v29, v58
	v_mov_b32_e32 v30, v58
	v_mov_b32_e32 v31, v58
	v_mov_b32_e32 v32, v58
	v_mov_b32_e32 v33, v58
	v_mov_b32_e32 v18, v58
	v_mov_b32_e32 v19, v58
	v_mov_b32_e32 v20, v58
	v_mov_b32_e32 v21, v58
	v_mov_b32_e32 v22, v58
	v_mov_b32_e32 v23, v58
	v_mov_b32_e32 v24, v58
	v_mov_b32_e32 v25, v58
	v_mov_b32_e32 v14, v58
	v_mov_b32_e32 v15, v58
	v_mov_b32_e32 v16, v58
	v_mov_b32_e32 v17, v58
	v_mov_b32_e32 v10, v58
	v_mov_b32_e32 v11, v58
	v_mov_b32_e32 v12, v58
	v_mov_b32_e32 v13, v58
	v_mov_b32_e32 v6, v58
	v_mov_b32_e32 v7, v58
	v_mov_b32_e32 v8, v58
	v_mov_b32_e32 v9, v58
	v_mov_b32_e32 v2, v58
	v_mov_b32_e32 v3, v58
	v_mov_b32_e32 v4, v58
	v_mov_b32_e32 v5, v58
	v_mov_b32_e32 v118, v58
	v_mov_b32_e32 v119, v58
	v_mov_b32_e32 v120, v58
	v_mov_b32_e32 v121, v58
	v_mov_b32_e32 v126, v58
	v_mov_b32_e32 v127, v58
	v_mov_b32_e32 v128, v58
	v_mov_b32_e32 v129, v58
	v_mov_b32_e32 v122, v58
	v_mov_b32_e32 v123, v58
	v_mov_b32_e32 v124, v58
	v_mov_b32_e32 v125, v58
	v_mov_b32_e32 v114, v58
	v_mov_b32_e32 v115, v58
	v_mov_b32_e32 v116, v58
	v_mov_b32_e32 v117, v58
	v_mov_b32_e32 v102, v58
	v_mov_b32_e32 v103, v58
	v_mov_b32_e32 v104, v58
	v_mov_b32_e32 v105, v58
	v_mov_b32_e32 v98, v58
	v_mov_b32_e32 v99, v58
	v_mov_b32_e32 v100, v58
	v_mov_b32_e32 v101, v58
	v_mov_b32_e32 v94, v58
	v_mov_b32_e32 v95, v58
	v_mov_b32_e32 v96, v58
	v_mov_b32_e32 v97, v58
	v_mov_b32_e32 v86, v58
	v_mov_b32_e32 v87, v58
	v_mov_b32_e32 v88, v58
	v_mov_b32_e32 v89, v58
	s_branch .LBB0_806
